# attention: O accumulators kept in place + thresholded lazy softmax rescale with max-subtraction folded into QK MFMA C operand (f32, exact reformulation)
# speedup vs baseline: 1.0289x; 1.0163x over previous
; #define LAS __attribute__((address_space(3)))
; __device__ __forceinline__ void attn_unit(LAS unsigned char* lds, const bf16_t* Qrow0, int nqw, int limbase, bool prompt, size_t kv0, int NT, int h,
;                                           const bf16_t* KN, const bf16_t* KR, const bf16_t* VVt, bf16_t* Yrow0, unsigned* tkctr, int& tick) {
;     ...
;     float mrow = -1e30f, lsum = 0.f; f32x16 o0 = {}, o1 = {}, s0 = {}, s1 = {};
;     if (wid >= 4) __builtin_amdgcn_s_setprio(1);
;     const LAS unsigned char* kbase = lds + r32 * KPITCH + hi * 16;
;     const LAS unsigned char* vbase = lds + ATT_V0 + r32 * VPITCH + hi * 8;
;     if (lim > 0) attn_step<true, false>(kbase, vbase, qr, s0, s1, o0, o1, mrow, lsum);
.LBB0_938:
	s_or_b64 exec, exec, s[10:11]
	s_cmp_lt_i32 s73, 0
	v_lshlrev_b32_e32 v204, 3, v34
	s_cbranch_scc1 .LBB0_959
	v_mov_b32_e32 v14, v1
	v_mov_b32_e32 v15, v1
	v_mad_i32_i24 v214, v33, s26, v35
	v_mov_b32_e32 v0, v1
	v_mov_b32_e32 v2, v1
	v_mov_b32_e32 v3, v1
	v_mov_b32_e32 v4, v1
	v_mov_b32_e32 v5, v1
	v_mov_b32_e32 v6, v1
	v_mov_b32_e32 v7, v1
	v_mov_b32_e32 v8, v1
	v_mov_b32_e32 v9, v1
	v_mov_b32_e32 v10, v1
	v_mov_b32_e32 v11, v1
	v_mov_b32_e32 v12, v1
	v_mov_b32_e32 v13, v1
	v_mov_b64_e32 v[46:47], v[14:15]
	v_mov_b64_e32 v[78:79], v[14:15]
	s_mov_b32 s73, 4
	s_add_i32 s74, s74, 4
	v_mov_b32_e32 v206, 0xf149f2ca
	v_mov_b32_e32 v215, 0
	v_mov_b64_e32 v[44:45], v[12:13]
	v_mov_b64_e32 v[42:43], v[10:11]
	v_mov_b64_e32 v[40:41], v[8:9]
	v_mov_b64_e32 v[38:39], v[6:7]
	v_mov_b64_e32 v[36:37], v[4:5]
	v_mov_b64_e32 v[34:35], v[2:3]
	v_mov_b64_e32 v[32:33], v[0:1]
	v_mov_b64_e32 v[76:77], v[12:13]
	v_mov_b64_e32 v[74:75], v[10:11]
	v_mov_b64_e32 v[72:73], v[8:9]
	v_mov_b64_e32 v[70:71], v[6:7]
	v_mov_b64_e32 v[68:69], v[4:5]
	v_mov_b64_e32 v[66:67], v[2:3]
	v_mov_b64_e32 v[64:65], v[0:1]
	v_mov_b32_e32 v218, 0
	v_mov_b32_e32 v219, 0
	v_mov_b32_e32 v220, 0
	v_mov_b32_e32 v221, 0
	v_mov_b32_e32 v222, 0
	v_mov_b32_e32 v223, 0
	v_mov_b32_e32 v224, 0
	v_mov_b32_e32 v225, 0
	v_mov_b32_e32 v226, 0
	v_mov_b32_e32 v227, 0
	v_mov_b32_e32 v228, 0
	v_mov_b32_e32 v229, 0
	v_mov_b32_e32 v230, 0
	v_mov_b32_e32 v231, 0
	v_mov_b32_e32 v232, 0
	v_mov_b32_e32 v233, 0
	s_mov_b32 s99, 0
	s_branch .LBB0_941

; #define LAS __attribute__((address_space(3)))
; template <bool QK, bool SM>
; __device__ __forceinline__ void attn_step(const LAS unsigned char* kb, const LAS unsigned char* vbp, const bf16x8 (&qr)[6],
;                                           f32x16& s0, f32x16& s1, f32x16& o0, f32x16& o1, float& mrow, float& lsum) {
;     ...
;         float mx = max3f(s0[0], s1[0], s0[1]); mx = max3f(mx, s1[1], s0[2]); float my = max3f(s1[2], s0[3], s1[3]);
; #pragma unroll
;         for (int r = 4; r < 16; r += 4) { mx = max3f(mx, s0[r], s1[r]); my = max3f(my, s0[r + 1], s1[r + 1]); mx = max3f(mx, s0[r + 2], s1[r + 2]); my = max3f(my, s0[r + 3], s1[r + 3]); }
;         mx = fmaxf(mx, my);
;         { const auto rr = __builtin_amdgcn_permlane32_swap(__float_as_uint(mx), __float_as_uint(mx), false, false); mx = fmaxf(__uint_as_float(rr[0]), __uint_as_float(rr[1])); }
;         const float mnew = fmaxf(mrow, mx), alpha = __builtin_amdgcn_exp2f(mrow - mnew); mrow = mnew;
;         const f32x2 m2 = (f32x2){mnew, mnew}; f32x2 ps2 = (f32x2){0.f, 0.f};
; #pragma unroll
;         for (int r = 0; r < 16; r += 2) { f32x2 a = (f32x2){s0[r], s0[r + 1]} - m2, b = (f32x2){s1[r], s1[r + 1]} - m2;
;             a.x = __builtin_amdgcn_exp2f(a.x); a.y = __builtin_amdgcn_exp2f(a.y); b.x = __builtin_amdgcn_exp2f(b.x); b.y = __builtin_amdgcn_exp2f(b.y);
;             s0[r] = a.x; s0[r + 1] = a.y; s1[r] = b.x; s1[r + 1] = b.y; ps2 += a + b; }
;         const float ps = ps2.x + ps2.y;
;         lsum = lsum * alpha + ps;
; #pragma unroll
;         for (int r = 0; r < 16; ++r) { o0[r] *= alpha; o1[r] *= alpha; }
;         bf16x8 pb[4];
; #pragma unroll
;         for (int S = 0; S < 4; ++S) { u32x4 w;
;             if (S < 2) { w.x = cvt_pk_bf16(s0[8 * S + 0], s0[8 * S + 1]); w.y = cvt_pk_bf16(s0[8 * S + 2], s0[8 * S + 3]); w.z = cvt_pk_bf16(s0[8 * S + 4], s0[8 * S + 5]); w.w = cvt_pk_bf16(s0[8 * S + 6], s0[8 * S + 7]); }
;             else { w.x = cvt_pk_bf16(s1[8 * S - 16], s1[8 * S - 15]); w.y = cvt_pk_bf16(s1[8 * S - 14], s1[8 * S - 13]); w.z = cvt_pk_bf16(s1[8 * S - 12], s1[8 * S - 11]); w.w = cvt_pk_bf16(s1[8 * S - 10], s1[8 * S - 9]); }
;             pb[S] = __builtin_bit_cast(bf16x8, w); }
; #pragma unroll
;         for (int S = 0; S < 4; ++S) {
;             const u32x2 a0 = *(const LAS u32x2*)(vbp + S * 32), a1 = *(const LAS u32x2*)(vbp + S * 32 + 16);
.LBB0_949:
	s_add_i32 s10, s73, -4
	v_mov_b64_e32 v[94:95], v[30:31]
	v_mov_b64_e32 v[126:127], v[62:63]
	s_cmp_ge_i32 s10, s72
	v_mov_b64_e32 v[92:93], v[28:29]
	v_mov_b64_e32 v[90:91], v[26:27]
	v_mov_b64_e32 v[88:89], v[24:25]
	v_mov_b64_e32 v[86:87], v[22:23]
	v_mov_b64_e32 v[84:85], v[20:21]
	v_mov_b64_e32 v[82:83], v[18:19]
	v_mov_b64_e32 v[80:81], v[16:17]
	v_mov_b64_e32 v[124:125], v[60:61]
	v_mov_b64_e32 v[122:123], v[58:59]
	v_mov_b64_e32 v[120:121], v[56:57]
	v_mov_b64_e32 v[118:119], v[54:55]
	v_mov_b64_e32 v[116:117], v[52:53]
	v_mov_b64_e32 v[114:115], v[50:51]
	v_mov_b64_e32 v[112:113], v[48:49]
	v_mov_b32_e32 v216, v215
	v_mov_b32_e32 v208, v206
	s_cbranch_scc1 .LBB0_951
	v_max3_f32 v0, v48, v16, v49
	v_max3_f32 v2, v18, v51, v19
	s_nop 0
	v_max3_f32 v0, v0, v17, v50
	v_max3_f32 v2, v2, v53, v21
	s_nop 0
	v_max3_f32 v0, v0, v52, v20
	v_max3_f32 v2, v2, v55, v23
	s_nop 0
	v_max3_f32 v0, v0, v54, v22
	v_max3_f32 v2, v2, v57, v25
	s_nop 0
	v_max3_f32 v0, v0, v56, v24
	v_max3_f32 v2, v2, v59, v27
	s_nop 0
	v_max3_f32 v0, v0, v58, v26
	v_max3_f32 v2, v2, v61, v29
	s_nop 0
	v_max3_f32 v0, v0, v60, v28
	v_max3_f32 v2, v2, v63, v31
	s_nop 0
	v_max3_f32 v0, v0, v62, v30
	v_max_f32_e32 v2, v2, v2
	v_max_f32_e32 v0, v0, v0
	v_max_f32_e32 v0, v0, v2
	v_mov_b32_e32 v2, v0
	s_nop 1
	v_permlane32_swap_b32_e32 v0, v2
	v_max3_f32 v208, v206, v0, v2
	v_sub_f32_e32 v2, v48, v208
	v_sub_f32_e32 v3, v49, v208
	v_sub_f32_e32 v4, v16, v208
	v_sub_f32_e32 v5, v17, v208
	v_exp_f32_e32 v14, v2
	v_exp_f32_e32 v15, v3
	v_exp_f32_e32 v2, v4
	v_exp_f32_e32 v3, v5
	v_sub_f32_e32 v4, v50, v208
	v_sub_f32_e32 v5, v51, v208
	v_sub_f32_e32 v6, v18, v208
	v_sub_f32_e32 v7, v19, v208
	v_exp_f32_e32 v82, v4
	v_exp_f32_e32 v83, v5
	v_exp_f32_e32 v4, v6
	v_exp_f32_e32 v5, v7
	v_add_f32_e32 v8, v14, v2
	v_add_f32_e32 v9, v15, v3
	v_sub_f32_e32 v6, v52, v208
	v_sub_f32_e32 v7, v53, v208
	v_sub_f32_e32 v10, v20, v208
	v_sub_f32_e32 v11, v21, v208
	v_exp_f32_e32 v84, v6
	v_exp_f32_e32 v85, v7
	v_exp_f32_e32 v6, v10
	v_exp_f32_e32 v7, v11
	v_add_f32_e32 v8, 0, v8
	v_add_f32_e32 v9, 0, v9
	v_add_f32_e32 v10, v82, v4
	v_add_f32_e32 v11, v83, v5
	v_sub_f32_e32 v112, v24, v208
	v_sub_f32_e32 v113, v25, v208
	v_add_f32_e32 v88, v10, v8
	v_add_f32_e32 v89, v11, v9
	v_sub_f32_e32 v8, v54, v208
	v_sub_f32_e32 v9, v55, v208
	v_sub_f32_e32 v10, v22, v208
	v_sub_f32_e32 v11, v23, v208
	v_exp_f32_e32 v92, v8
	v_exp_f32_e32 v93, v9
	v_sub_f32_e32 v8, v56, v208
	v_sub_f32_e32 v9, v57, v208
	v_exp_f32_e32 v94, v10
	v_exp_f32_e32 v95, v11
	v_exp_f32_e32 v115, v9
	v_sub_f32_e32 v10, v58, v208
	v_sub_f32_e32 v11, v59, v208
	v_add_u32_e32 v9, v214, v204
	v_exp_f32_e32 v114, v8
	v_exp_f32_e32 v8, v112
	v_exp_f32_e32 v116, v10
	v_exp_f32_e32 v117, v11
	v_sub_f32_e32 v10, v60, v208
	v_sub_f32_e32 v11, v61, v208
	v_add_u32_e32 v112, 0x6800, v9
	v_exp_f32_e32 v118, v10
	v_exp_f32_e32 v119, v11
	ds_read2_b64 v[10:13], v112 offset1:2
	v_add_u32_e32 v122, 0x7800, v9
	v_add_f32_e32 v90, v84, v6
	v_add_f32_e32 v91, v85, v7
	v_cvt_pk_bf16_f32 v81, v82, v83
	v_cvt_pk_bf16_f32 v82, v84, v85
	ds_read2_b64 v[84:87], v122 offset0:32 offset1:34
	v_sub_f32_e32 v0, v206, v208
	v_exp_f32_e32 v0, v0
	v_cvt_pk_bf16_f32 v80, v14, v15
	v_cvt_pk_bf16_f32 v83, v92, v93
	v_sub_f32_e32 v120, v62, v208
	v_sub_f32_e32 v121, v63, v208
	v_mul_f32_e32 v46, v46, v0
	v_mul_f32_e32 v47, v47, v0
	v_mul_f32_e32 v44, v44, v0
	v_mul_f32_e32 v45, v45, v0
	v_mul_f32_e32 v42, v42, v0
	v_mul_f32_e32 v43, v43, v0
	v_mul_f32_e32 v40, v40, v0
	v_mul_f32_e32 v41, v41, v0
	v_mul_f32_e32 v38, v38, v0
	v_mul_f32_e32 v39, v39, v0
	v_mul_f32_e32 v36, v36, v0
	v_mul_f32_e32 v37, v37, v0
	v_mul_f32_e32 v34, v34, v0
	v_mul_f32_e32 v35, v35, v0
	v_mul_f32_e32 v32, v32, v0
	v_mul_f32_e32 v33, v33, v0
	v_mul_f32_e32 v78, v78, v0
	v_mul_f32_e32 v79, v79, v0
	v_mul_f32_e32 v76, v76, v0
	v_mul_f32_e32 v77, v77, v0
	s_waitcnt lgkmcnt(1)
	v_mfma_f32_32x32x16_bf16 v[32:47], v[10:13], v[80:83], v[32:47]
	v_mul_f32_e32 v74, v74, v0
	v_mul_f32_e32 v75, v75, v0
	v_mul_f32_e32 v72, v72, v0
	v_mul_f32_e32 v73, v73, v0
	v_mul_f32_e32 v70, v70, v0
	v_mul_f32_e32 v71, v71, v0
	v_mul_f32_e32 v68, v68, v0
	v_mul_f32_e32 v69, v69, v0
	v_mul_f32_e32 v66, v66, v0
	v_mul_f32_e32 v67, v67, v0
	v_mul_f32_e32 v64, v64, v0
	v_mul_f32_e32 v65, v65, v0
	ds_read2_b64 v[10:13], v112 offset0:4 offset1:6
	v_exp_f32_e32 v14, v120
	s_waitcnt lgkmcnt(1)
	v_mfma_f32_32x32x16_bf16 v[64:79], v[84:87], v[80:83], v[64:79]
	ds_read2_b64 v[84:87], v122 offset0:36 offset1:38
	v_exp_f32_e32 v15, v121

; __device__ __forceinline__ unsigned cvt_pk_bf16(float lo, float hi) { unsigned r; asm("v_cvt_pk_bf16_f32 %0, %1, %2" : "=v"(r) : "v"(lo), "v"(hi)); return r; }
; template <bool QK, bool SM>
; __device__ __forceinline__ void attn_step(const LAS unsigned char* kb, const LAS unsigned char* vbp, const bf16x8 (&qr)[6],
;                                           f32x16& s0, f32x16& s1, f32x16& o0, f32x16& o1, float& mrow, float& lsum) {
;     ...
;         for (int S = 0; S < 4; ++S) { u32x4 w;
;             if (S < 2) { w.x = cvt_pk_bf16(s0[8 * S + 0], s0[8 * S + 1]); w.y = cvt_pk_bf16(s0[8 * S + 2], s0[8 * S + 3]); w.z = cvt_pk_bf16(s0[8 * S + 4], s0[8 * S + 5]); w.w = cvt_pk_bf16(s0[8 * S + 6], s0[8 * S + 7]); }
;             else { w.x = cvt_pk_bf16(s1[8 * S - 16], s1[8 * S - 15]); w.y = cvt_pk_bf16(s1[8 * S - 14], s1[8 * S - 13]); w.z = cvt_pk_bf16(s1[8 * S - 12], s1[8 * S - 11]); w.w = cvt_pk_bf16(s1[8 * S - 10], s1[8 * S - 9]); }
;             pb[S] = __builtin_bit_cast(bf16x8, w); }
	v_cvt_pk_bf16_f32 v80, v114, v115


; __device__ __forceinline__ unsigned cvt_pk_bf16(float lo, float hi) { unsigned r; asm("v_cvt_pk_bf16_f32 %0, %1, %2" : "=v"(r) : "v"(lo), "v"(hi)); return r; }
; template <bool QK, bool SM>
; __device__ __forceinline__ void attn_step(const LAS unsigned char* kb, const LAS unsigned char* vbp, const bf16x8 (&qr)[6],
;                                           f32x16& s0, f32x16& s1, f32x16& o0, f32x16& o1, float& mrow, float& lsum) {
;     ...
;         for (int S = 0; S < 4; ++S) { u32x4 w;
;             if (S < 2) { w.x = cvt_pk_bf16(s0[8 * S + 0], s0[8 * S + 1]); w.y = cvt_pk_bf16(s0[8 * S + 2], s0[8 * S + 3]); w.z = cvt_pk_bf16(s0[8 * S + 4], s0[8 * S + 5]); w.w = cvt_pk_bf16(s0[8 * S + 6], s0[8 * S + 7]); }
;             else { w.x = cvt_pk_bf16(s1[8 * S - 16], s1[8 * S - 15]); w.y = cvt_pk_bf16(s1[8 * S - 14], s1[8 * S - 13]); w.z = cvt_pk_bf16(s1[8 * S - 12], s1[8 * S - 11]); w.w = cvt_pk_bf16(s1[8 * S - 10], s1[8 * S - 9]); }
;             pb[S] = __builtin_bit_cast(bf16x8, w); }
	v_cvt_pk_bf16_f32 v81, v116, v117


; __device__ __forceinline__ unsigned cvt_pk_bf16(float lo, float hi) { unsigned r; asm("v_cvt_pk_bf16_f32 %0, %1, %2" : "=v"(r) : "v"(lo), "v"(hi)); return r; }
; template <bool QK, bool SM>
; __device__ __forceinline__ void attn_step(const LAS unsigned char* kb, const LAS unsigned char* vbp, const bf16x8 (&qr)[6],
;                                           f32x16& s0, f32x16& s1, f32x16& o0, f32x16& o1, float& mrow, float& lsum) {
;     ...
;         for (int S = 0; S < 4; ++S) { u32x4 w;
;             if (S < 2) { w.x = cvt_pk_bf16(s0[8 * S + 0], s0[8 * S + 1]); w.y = cvt_pk_bf16(s0[8 * S + 2], s0[8 * S + 3]); w.z = cvt_pk_bf16(s0[8 * S + 4], s0[8 * S + 5]); w.w = cvt_pk_bf16(s0[8 * S + 6], s0[8 * S + 7]); }
;             else { w.x = cvt_pk_bf16(s1[8 * S - 16], s1[8 * S - 15]); w.y = cvt_pk_bf16(s1[8 * S - 14], s1[8 * S - 13]); w.z = cvt_pk_bf16(s1[8 * S - 12], s1[8 * S - 11]); w.w = cvt_pk_bf16(s1[8 * S - 10], s1[8 * S - 9]); }
;             pb[S] = __builtin_bit_cast(bf16x8, w); }
	v_cvt_pk_bf16_f32 v82, v118, v119


; __device__ __forceinline__ unsigned cvt_pk_bf16(float lo, float hi) { unsigned r; asm("v_cvt_pk_bf16_f32 %0, %1, %2" : "=v"(r) : "v"(lo), "v"(hi)); return r; }
; template <bool QK, bool SM>
; __device__ __forceinline__ void attn_step(const LAS unsigned char* kb, const LAS unsigned char* vbp, const bf16x8 (&qr)[6],
;                                           f32x16& s0, f32x16& s1, f32x16& o0, f32x16& o1, float& mrow, float& lsum) {
;     ...
;         for (int S = 0; S < 4; ++S) { u32x4 w;
;             if (S < 2) { w.x = cvt_pk_bf16(s0[8 * S + 0], s0[8 * S + 1]); w.y = cvt_pk_bf16(s0[8 * S + 2], s0[8 * S + 3]); w.z = cvt_pk_bf16(s0[8 * S + 4], s0[8 * S + 5]); w.w = cvt_pk_bf16(s0[8 * S + 6], s0[8 * S + 7]); }
;             else { w.x = cvt_pk_bf16(s1[8 * S - 16], s1[8 * S - 15]); w.y = cvt_pk_bf16(s1[8 * S - 14], s1[8 * S - 13]); w.z = cvt_pk_bf16(s1[8 * S - 12], s1[8 * S - 11]); w.w = cvt_pk_bf16(s1[8 * S - 10], s1[8 * S - 9]); }
;             pb[S] = __builtin_bit_cast(bf16x8, w); }
	v_cvt_pk_bf16_f32 v83, v14, v15

; #define LAS __attribute__((address_space(3)))
; template <bool QK, bool SM>
; __device__ __forceinline__ void attn_step(const LAS unsigned char* kb, const LAS unsigned char* vbp, const bf16x8 (&qr)[6],
;                                           f32x16& s0, f32x16& s1, f32x16& o0, f32x16& o1, float& mrow, float& lsum) {
;     ...
;             s0[r] = a.x; s0[r + 1] = a.y; s1[r] = b.x; s1[r + 1] = b.y; ps2 += a + b; }
;         const float ps = ps2.x + ps2.y;
;     ...
;         for (int S = 0; S < 4; ++S) {
;             const u32x2 a0 = *(const LAS u32x2*)(vbp + S * 32), a1 = *(const LAS u32x2*)(vbp + S * 32 + 16);
;             const u32x2 c0 = *(const LAS u32x2*)(vbp + 32 * VPITCH + S * 32), c1 = *(const LAS u32x2*)(vbp + 32 * VPITCH + S * 32 + 16);
;             const bf16x8 va = __builtin_bit_cast(bf16x8, (u32x4){a0.x, a0.y, a1.x, a1.y}), vc = __builtin_bit_cast(bf16x8, (u32x4){c0.x, c0.y, c1.x, c1.y});
;             o0 = __builtin_amdgcn_mfma_f32_32x32x16_bf16(va, pb[S], o0, 0, 0, 0); o1 = __builtin_amdgcn_mfma_f32_32x32x16_bf16(vc, pb[S], o1, 0, 0, 0); }
	v_exp_f32_e32 v9, v113
	s_waitcnt lgkmcnt(1)
	v_mfma_f32_32x32x16_bf16 v[32:47], v[10:13], v[80:83], v[32:47]
	v_add_f32_e32 v10, v90, v88
	v_add_f32_e32 v11, v91, v89
	v_add_f32_e32 v12, v92, v94
	v_add_f32_e32 v13, v93, v95
	v_add_f32_e32 v90, v114, v8
	v_add_f32_e32 v91, v115, v9
	v_add_f32_e32 v88, v12, v10
	v_add_f32_e32 v89, v13, v11
	ds_read2_b64 v[10:13], v112 offset0:8 offset1:10

; __device__ __forceinline__ unsigned cvt_pk_bf16(float lo, float hi) { unsigned r; asm("v_cvt_pk_bf16_f32 %0, %1, %2" : "=v"(r) : "v"(lo), "v"(hi)); return r; }
; template <bool QK, bool SM>
; __device__ __forceinline__ void attn_step(const LAS unsigned char* kb, const LAS unsigned char* vbp, const bf16x8 (&qr)[6],
;                                           f32x16& s0, f32x16& s1, f32x16& o0, f32x16& o1, float& mrow, float& lsum) {
;     ...
;         for (int S = 0; S < 4; ++S) { u32x4 w;
;             if (S < 2) { w.x = cvt_pk_bf16(s0[8 * S + 0], s0[8 * S + 1]); w.y = cvt_pk_bf16(s0[8 * S + 2], s0[8 * S + 3]); w.z = cvt_pk_bf16(s0[8 * S + 4], s0[8 * S + 5]); w.w = cvt_pk_bf16(s0[8 * S + 6], s0[8 * S + 7]); }
;             else { w.x = cvt_pk_bf16(s1[8 * S - 16], s1[8 * S - 15]); w.y = cvt_pk_bf16(s1[8 * S - 14], s1[8 * S - 13]); w.z = cvt_pk_bf16(s1[8 * S - 12], s1[8 * S - 11]); w.w = cvt_pk_bf16(s1[8 * S - 10], s1[8 * S - 9]); }
;             pb[S] = __builtin_bit_cast(bf16x8, w); }
	v_cvt_pk_bf16_f32 v2, v2, v3


; __device__ __forceinline__ unsigned cvt_pk_bf16(float lo, float hi) { unsigned r; asm("v_cvt_pk_bf16_f32 %0, %1, %2" : "=v"(r) : "v"(lo), "v"(hi)); return r; }
; template <bool QK, bool SM>
; __device__ __forceinline__ void attn_step(const LAS unsigned char* kb, const LAS unsigned char* vbp, const bf16x8 (&qr)[6],
;                                           f32x16& s0, f32x16& s1, f32x16& o0, f32x16& o1, float& mrow, float& lsum) {
;     ...
;         for (int S = 0; S < 4; ++S) { u32x4 w;
;             if (S < 2) { w.x = cvt_pk_bf16(s0[8 * S + 0], s0[8 * S + 1]); w.y = cvt_pk_bf16(s0[8 * S + 2], s0[8 * S + 3]); w.z = cvt_pk_bf16(s0[8 * S + 4], s0[8 * S + 5]); w.w = cvt_pk_bf16(s0[8 * S + 6], s0[8 * S + 7]); }
;             else { w.x = cvt_pk_bf16(s1[8 * S - 16], s1[8 * S - 15]); w.y = cvt_pk_bf16(s1[8 * S - 14], s1[8 * S - 13]); w.z = cvt_pk_bf16(s1[8 * S - 12], s1[8 * S - 11]); w.w = cvt_pk_bf16(s1[8 * S - 10], s1[8 * S - 9]); }
;             pb[S] = __builtin_bit_cast(bf16x8, w); }
	v_cvt_pk_bf16_f32 v3, v4, v5

; #define LAS __attribute__((address_space(3)))
; template <bool QK, bool SM>
; __device__ __forceinline__ void attn_step(const LAS unsigned char* kb, const LAS unsigned char* vbp, const bf16x8 (&qr)[6],
;                                           f32x16& s0, f32x16& s1, f32x16& o0, f32x16& o1, float& mrow, float& lsum) {
;     ...
;         for (int S = 0; S < 4; ++S) {
;             const u32x2 a0 = *(const LAS u32x2*)(vbp + S * 32), a1 = *(const LAS u32x2*)(vbp + S * 32 + 16);
;             const u32x2 c0 = *(const LAS u32x2*)(vbp + 32 * VPITCH + S * 32), c1 = *(const LAS u32x2*)(vbp + 32 * VPITCH + S * 32 + 16);
;             const bf16x8 va = __builtin_bit_cast(bf16x8, (u32x4){a0.x, a0.y, a1.x, a1.y}), vc = __builtin_bit_cast(bf16x8, (u32x4){c0.x, c0.y, c1.x, c1.y});
;             o0 = __builtin_amdgcn_mfma_f32_32x32x16_bf16(va, pb[S], o0, 0, 0, 0); o1 = __builtin_amdgcn_mfma_f32_32x32x16_bf16(vc, pb[S], o1, 0, 0, 0); }
	s_waitcnt lgkmcnt(1)
	v_mfma_f32_32x32x16_bf16 v[64:79], v[84:87], v[80:83], v[64:79]
	ds_read2_b64 v[80:83], v122 offset0:40 offset1:42

; __device__ __forceinline__ unsigned cvt_pk_bf16(float lo, float hi) { unsigned r; asm("v_cvt_pk_bf16_f32 %0, %1, %2" : "=v"(r) : "v"(lo), "v"(hi)); return r; }
; template <bool QK, bool SM>
; __device__ __forceinline__ void attn_step(const LAS unsigned char* kb, const LAS unsigned char* vbp, const bf16x8 (&qr)[6],
;                                           f32x16& s0, f32x16& s1, f32x16& o0, f32x16& o1, float& mrow, float& lsum) {
;     ...
;         for (int S = 0; S < 4; ++S) { u32x4 w;
;             if (S < 2) { w.x = cvt_pk_bf16(s0[8 * S + 0], s0[8 * S + 1]); w.y = cvt_pk_bf16(s0[8 * S + 2], s0[8 * S + 3]); w.z = cvt_pk_bf16(s0[8 * S + 4], s0[8 * S + 5]); w.w = cvt_pk_bf16(s0[8 * S + 6], s0[8 * S + 7]); }
;             else { w.x = cvt_pk_bf16(s1[8 * S - 16], s1[8 * S - 15]); w.y = cvt_pk_bf16(s1[8 * S - 14], s1[8 * S - 13]); w.z = cvt_pk_bf16(s1[8 * S - 12], s1[8 * S - 11]); w.w = cvt_pk_bf16(s1[8 * S - 10], s1[8 * S - 9]); }
;             pb[S] = __builtin_bit_cast(bf16x8, w); }
	v_cvt_pk_bf16_f32 v4, v6, v7

; template <bool QK, bool SM>
; __device__ __forceinline__ void attn_step(const LAS unsigned char* kb, const LAS unsigned char* vbp, const bf16x8 (&qr)[6],
;                                           f32x16& s0, f32x16& s1, f32x16& o0, f32x16& o1, float& mrow, float& lsum) {
;     ...
;         for (int r = 0; r < 16; r += 2) { f32x2 a = (f32x2){s0[r], s0[r + 1]} - m2, b = (f32x2){s1[r], s1[r + 1]} - m2;
;             a.x = __builtin_amdgcn_exp2f(a.x); a.y = __builtin_amdgcn_exp2f(a.y); b.x = __builtin_amdgcn_exp2f(b.x); b.y = __builtin_amdgcn_exp2f(b.y);
;             s0[r] = a.x; s0[r + 1] = a.y; s1[r] = b.x; s1[r + 1] = b.y; ps2 += a + b; }
;         const float ps = ps2.x + ps2.y;
	v_sub_f32_e32 v6, v28, v208
	v_sub_f32_e32 v7, v29, v208
	v_add_f32_e32 v86, v90, v88
	v_add_f32_e32 v87, v91, v89
	v_exp_f32_e32 v90, v6
	v_exp_f32_e32 v91, v7
	v_sub_f32_e32 v6, v30, v208
	v_sub_f32_e32 v7, v31, v208

; __device__ __forceinline__ unsigned cvt_pk_bf16(float lo, float hi) { unsigned r; asm("v_cvt_pk_bf16_f32 %0, %1, %2" : "=v"(r) : "v"(lo), "v"(hi)); return r; }
; template <bool QK, bool SM>
; __device__ __forceinline__ void attn_step(const LAS unsigned char* kb, const LAS unsigned char* vbp, const bf16x8 (&qr)[6],
;                                           f32x16& s0, f32x16& s1, f32x16& o0, f32x16& o1, float& mrow, float& lsum) {
;     ...
;         for (int S = 0; S < 4; ++S) { u32x4 w;
;             if (S < 2) { w.x = cvt_pk_bf16(s0[8 * S + 0], s0[8 * S + 1]); w.y = cvt_pk_bf16(s0[8 * S + 2], s0[8 * S + 3]); w.z = cvt_pk_bf16(s0[8 * S + 4], s0[8 * S + 5]); w.w = cvt_pk_bf16(s0[8 * S + 6], s0[8 * S + 7]); }
;             else { w.x = cvt_pk_bf16(s1[8 * S - 16], s1[8 * S - 15]); w.y = cvt_pk_bf16(s1[8 * S - 14], s1[8 * S - 13]); w.z = cvt_pk_bf16(s1[8 * S - 12], s1[8 * S - 11]); w.w = cvt_pk_bf16(s1[8 * S - 10], s1[8 * S - 9]); }
;             pb[S] = __builtin_bit_cast(bf16x8, w); }
	v_cvt_pk_bf16_f32 v5, v94, v95

; #define LAS __attribute__((address_space(3)))
; __device__ __forceinline__ unsigned cvt_pk_bf16(float lo, float hi) { unsigned r; asm("v_cvt_pk_bf16_f32 %0, %1, %2" : "=v"(r) : "v"(lo), "v"(hi)); return r; }
; template <bool QK, bool SM>
; __device__ __forceinline__ void attn_step(const LAS unsigned char* kb, const LAS unsigned char* vbp, const bf16x8 (&qr)[6],
;                                           f32x16& s0, f32x16& s1, f32x16& o0, f32x16& o1, float& mrow, float& lsum) {
;     ...
;         for (int r = 0; r < 16; r += 2) { f32x2 a = (f32x2){s0[r], s0[r + 1]} - m2, b = (f32x2){s1[r], s1[r + 1]} - m2;
;             a.x = __builtin_amdgcn_exp2f(a.x); a.y = __builtin_amdgcn_exp2f(a.y); b.x = __builtin_amdgcn_exp2f(b.x); b.y = __builtin_amdgcn_exp2f(b.y);
;             s0[r] = a.x; s0[r + 1] = a.y; s1[r] = b.x; s1[r + 1] = b.y; ps2 += a + b; }
;         const float ps = ps2.x + ps2.y;
;         lsum = lsum * alpha + ps;
; #pragma unroll
;         for (int r = 0; r < 16; ++r) { o0[r] *= alpha; o1[r] *= alpha; }
;         bf16x8 pb[4];
; #pragma unroll
;         for (int S = 0; S < 4; ++S) { u32x4 w;
;             if (S < 2) { w.x = cvt_pk_bf16(s0[8 * S + 0], s0[8 * S + 1]); w.y = cvt_pk_bf16(s0[8 * S + 2], s0[8 * S + 3]); w.z = cvt_pk_bf16(s0[8 * S + 4], s0[8 * S + 5]); w.w = cvt_pk_bf16(s0[8 * S + 6], s0[8 * S + 7]); }
;             else { w.x = cvt_pk_bf16(s1[8 * S - 16], s1[8 * S - 15]); w.y = cvt_pk_bf16(s1[8 * S - 14], s1[8 * S - 13]); w.z = cvt_pk_bf16(s1[8 * S - 12], s1[8 * S - 11]); w.w = cvt_pk_bf16(s1[8 * S - 10], s1[8 * S - 9]); }
;             pb[S] = __builtin_bit_cast(bf16x8, w); }
; #pragma unroll
;         for (int S = 0; S < 4; ++S) {
;             const u32x2 a0 = *(const LAS u32x2*)(vbp + S * 32), a1 = *(const LAS u32x2*)(vbp + S * 32 + 16);
;             const u32x2 c0 = *(const LAS u32x2*)(vbp + 32 * VPITCH + S * 32), c1 = *(const LAS u32x2*)(vbp + 32 * VPITCH + S * 32 + 16);
;             const bf16x8 va = __builtin_bit_cast(bf16x8, (u32x4){a0.x, a0.y, a1.x, a1.y}), vc = __builtin_bit_cast(bf16x8, (u32x4){c0.x, c0.y, c1.x, c1.y});
;             o0 = __builtin_amdgcn_mfma_f32_32x32x16_bf16(va, pb[S], o0, 0, 0, 0); o1 = __builtin_amdgcn_mfma_f32_32x32x16_bf16(vc, pb[S], o1, 0, 0, 0); }
	v_sub_f32_e32 v92, v26, v208
	v_sub_f32_e32 v93, v27, v208
	s_waitcnt lgkmcnt(1)
	v_mfma_f32_32x32x16_bf16 v[32:47], v[10:13], v[2:5], v[32:47]
	ds_read2_b64 v[10:13], v112 offset0:12 offset1:14
	v_exp_f32_e32 v84, v92
	v_exp_f32_e32 v85, v93
	s_nop 0
	v_add_f32_e32 v88, v116, v84
	v_add_f32_e32 v89, v117, v85
	s_waitcnt lgkmcnt(1)
	v_mfma_f32_32x32x16_bf16 v[64:79], v[80:83], v[2:5], v[64:79]
	v_exp_f32_e32 v80, v6
	v_exp_f32_e32 v81, v7

; __device__ __forceinline__ unsigned cvt_pk_bf16(float lo, float hi) { unsigned r; asm("v_cvt_pk_bf16_f32 %0, %1, %2" : "=v"(r) : "v"(lo), "v"(hi)); return r; }
; template <bool QK, bool SM>
; __device__ __forceinline__ void attn_step(const LAS unsigned char* kb, const LAS unsigned char* vbp, const bf16x8 (&qr)[6],
;                                           f32x16& s0, f32x16& s1, f32x16& o0, f32x16& o1, float& mrow, float& lsum) {
;     ...
;         for (int S = 0; S < 4; ++S) { u32x4 w;
;             if (S < 2) { w.x = cvt_pk_bf16(s0[8 * S + 0], s0[8 * S + 1]); w.y = cvt_pk_bf16(s0[8 * S + 2], s0[8 * S + 3]); w.z = cvt_pk_bf16(s0[8 * S + 4], s0[8 * S + 5]); w.w = cvt_pk_bf16(s0[8 * S + 6], s0[8 * S + 7]); }
;             else { w.x = cvt_pk_bf16(s1[8 * S - 16], s1[8 * S - 15]); w.y = cvt_pk_bf16(s1[8 * S - 14], s1[8 * S - 13]); w.z = cvt_pk_bf16(s1[8 * S - 12], s1[8 * S - 11]); w.w = cvt_pk_bf16(s1[8 * S - 10], s1[8 * S - 9]); }
;             pb[S] = __builtin_bit_cast(bf16x8, w); }
	v_cvt_pk_bf16_f32 v2, v8, v9

; #define LAS __attribute__((address_space(3)))
; template <bool QK, bool SM>
; __device__ __forceinline__ void attn_step(const LAS unsigned char* kb, const LAS unsigned char* vbp, const bf16x8 (&qr)[6],
;                                           f32x16& s0, f32x16& s1, f32x16& o0, f32x16& o1, float& mrow, float& lsum) {
;     ...
;             const u32x2 a0 = *(const LAS u32x2*)(vbp + S * 32), a1 = *(const LAS u32x2*)(vbp + S * 32 + 16);
;             const u32x2 c0 = *(const LAS u32x2*)(vbp + 32 * VPITCH + S * 32), c1 = *(const LAS u32x2*)(vbp + 32 * VPITCH + S * 32 + 16);
	ds_read2_b64 v[6:9], v122 offset0:44 offset1:46

; __device__ __forceinline__ unsigned cvt_pk_bf16(float lo, float hi) { unsigned r; asm("v_cvt_pk_bf16_f32 %0, %1, %2" : "=v"(r) : "v"(lo), "v"(hi)); return r; }
; template <bool QK, bool SM>
; __device__ __forceinline__ void attn_step(const LAS unsigned char* kb, const LAS unsigned char* vbp, const bf16x8 (&qr)[6],
;                                           f32x16& s0, f32x16& s1, f32x16& o0, f32x16& o1, float& mrow, float& lsum) {
;     ...
;         for (int S = 0; S < 4; ++S) { u32x4 w;
;             if (S < 2) { w.x = cvt_pk_bf16(s0[8 * S + 0], s0[8 * S + 1]); w.y = cvt_pk_bf16(s0[8 * S + 2], s0[8 * S + 3]); w.z = cvt_pk_bf16(s0[8 * S + 4], s0[8 * S + 5]); w.w = cvt_pk_bf16(s0[8 * S + 6], s0[8 * S + 7]); }
;             else { w.x = cvt_pk_bf16(s1[8 * S - 16], s1[8 * S - 15]); w.y = cvt_pk_bf16(s1[8 * S - 14], s1[8 * S - 13]); w.z = cvt_pk_bf16(s1[8 * S - 12], s1[8 * S - 11]); w.w = cvt_pk_bf16(s1[8 * S - 10], s1[8 * S - 9]); }
;             pb[S] = __builtin_bit_cast(bf16x8, w); }
	v_cvt_pk_bf16_f32 v3, v84, v85


; __device__ __forceinline__ unsigned cvt_pk_bf16(float lo, float hi) { unsigned r; asm("v_cvt_pk_bf16_f32 %0, %1, %2" : "=v"(r) : "v"(lo), "v"(hi)); return r; }
; template <bool QK, bool SM>
; __device__ __forceinline__ void attn_step(const LAS unsigned char* kb, const LAS unsigned char* vbp, const bf16x8 (&qr)[6],
;                                           f32x16& s0, f32x16& s1, f32x16& o0, f32x16& o1, float& mrow, float& lsum) {
;     ...
;         for (int S = 0; S < 4; ++S) { u32x4 w;
;             if (S < 2) { w.x = cvt_pk_bf16(s0[8 * S + 0], s0[8 * S + 1]); w.y = cvt_pk_bf16(s0[8 * S + 2], s0[8 * S + 3]); w.z = cvt_pk_bf16(s0[8 * S + 4], s0[8 * S + 5]); w.w = cvt_pk_bf16(s0[8 * S + 6], s0[8 * S + 7]); }
;             else { w.x = cvt_pk_bf16(s1[8 * S - 16], s1[8 * S - 15]); w.y = cvt_pk_bf16(s1[8 * S - 14], s1[8 * S - 13]); w.z = cvt_pk_bf16(s1[8 * S - 12], s1[8 * S - 11]); w.w = cvt_pk_bf16(s1[8 * S - 10], s1[8 * S - 9]); }
;             pb[S] = __builtin_bit_cast(bf16x8, w); }
	v_cvt_pk_bf16_f32 v4, v90, v91


; __device__ __forceinline__ unsigned cvt_pk_bf16(float lo, float hi) { unsigned r; asm("v_cvt_pk_bf16_f32 %0, %1, %2" : "=v"(r) : "v"(lo), "v"(hi)); return r; }
; template <bool QK, bool SM>
; __device__ __forceinline__ void attn_step(const LAS unsigned char* kb, const LAS unsigned char* vbp, const bf16x8 (&qr)[6],
;                                           f32x16& s0, f32x16& s1, f32x16& o0, f32x16& o1, float& mrow, float& lsum) {
;     ...
;         for (int S = 0; S < 4; ++S) { u32x4 w;
;             if (S < 2) { w.x = cvt_pk_bf16(s0[8 * S + 0], s0[8 * S + 1]); w.y = cvt_pk_bf16(s0[8 * S + 2], s0[8 * S + 3]); w.z = cvt_pk_bf16(s0[8 * S + 4], s0[8 * S + 5]); w.w = cvt_pk_bf16(s0[8 * S + 6], s0[8 * S + 7]); }
;             else { w.x = cvt_pk_bf16(s1[8 * S - 16], s1[8 * S - 15]); w.y = cvt_pk_bf16(s1[8 * S - 14], s1[8 * S - 13]); w.z = cvt_pk_bf16(s1[8 * S - 12], s1[8 * S - 11]); w.w = cvt_pk_bf16(s1[8 * S - 10], s1[8 * S - 9]); }
;             pb[S] = __builtin_bit_cast(bf16x8, w); }
	v_cvt_pk_bf16_f32 v5, v80, v81

; #define LAS __attribute__((address_space(3)))
; __device__ __forceinline__ unsigned cvt_pk_bf16(float lo, float hi) { unsigned r; asm("v_cvt_pk_bf16_f32 %0, %1, %2" : "=v"(r) : "v"(lo), "v"(hi)); return r; }
; template <bool QK, bool SM>
; __device__ __forceinline__ void attn_step(const LAS unsigned char* kb, const LAS unsigned char* vbp, const bf16x8 (&qr)[6],
;                                           f32x16& s0, f32x16& s1, f32x16& o0, f32x16& o1, float& mrow, float& lsum) {
;     ...
;             s0[r] = a.x; s0[r + 1] = a.y; s1[r] = b.x; s1[r + 1] = b.y; ps2 += a + b; }
;         const float ps = ps2.x + ps2.y;
;         lsum = lsum * alpha + ps;
; #pragma unroll
;         for (int r = 0; r < 16; ++r) { o0[r] *= alpha; o1[r] *= alpha; }
;         bf16x8 pb[4];
; #pragma unroll
;         for (int S = 0; S < 4; ++S) { u32x4 w;
;             if (S < 2) { w.x = cvt_pk_bf16(s0[8 * S + 0], s0[8 * S + 1]); w.y = cvt_pk_bf16(s0[8 * S + 2], s0[8 * S + 3]); w.z = cvt_pk_bf16(s0[8 * S + 4], s0[8 * S + 5]); w.w = cvt_pk_bf16(s0[8 * S + 6], s0[8 * S + 7]); }
;             else { w.x = cvt_pk_bf16(s1[8 * S - 16], s1[8 * S - 15]); w.y = cvt_pk_bf16(s1[8 * S - 14], s1[8 * S - 13]); w.z = cvt_pk_bf16(s1[8 * S - 12], s1[8 * S - 11]); w.w = cvt_pk_bf16(s1[8 * S - 10], s1[8 * S - 9]); }
;             pb[S] = __builtin_bit_cast(bf16x8, w); }
; #pragma unroll
;         for (int S = 0; S < 4; ++S) {
;             const u32x2 a0 = *(const LAS u32x2*)(vbp + S * 32), a1 = *(const LAS u32x2*)(vbp + S * 32 + 16);
;             const u32x2 c0 = *(const LAS u32x2*)(vbp + 32 * VPITCH + S * 32), c1 = *(const LAS u32x2*)(vbp + 32 * VPITCH + S * 32 + 16);
;             const bf16x8 va = __builtin_bit_cast(bf16x8, (u32x4){a0.x, a0.y, a1.x, a1.y}), vc = __builtin_bit_cast(bf16x8, (u32x4){c0.x, c0.y, c1.x, c1.y});
;             o0 = __builtin_amdgcn_mfma_f32_32x32x16_bf16(va, pb[S], o0, 0, 0, 0); o1 = __builtin_amdgcn_mfma_f32_32x32x16_bf16(vc, pb[S], o1, 0, 0, 0); }
;     }
;     s0 = n0; s1 = n1;
	s_waitcnt lgkmcnt(1)
	v_mfma_f32_32x32x16_bf16 v[32:47], v[10:13], v[2:5], v[32:47]
	v_add_f32_e32 v10, v88, v86
	v_add_f32_e32 v11, v89, v87
	v_add_f32_e32 v12, v118, v90
	v_add_f32_e32 v13, v119, v91
	v_add_f32_e32 v10, v12, v10
	v_add_f32_e32 v11, v13, v11
	v_add_f32_e32 v12, v14, v80
	v_add_f32_e32 v13, v15, v81
	v_mov_b32_e32 v14, v1
	v_add_f32_e32 v10, v12, v10
	v_add_f32_e32 v11, v13, v11
	s_waitcnt lgkmcnt(0)
	v_mfma_f32_32x32x16_bf16 v[64:79], v[6:9], v[2:5], v[64:79]
	v_add_f32_e32 v216, v10, v11
	v_mov_b32_e32 v15, v1
	v_fmac_f32_e32 v216, v215, v0
	v_mov_b32_e32 v0, v1
	v_mov_b32_e32 v2, v1
	v_mov_b32_e32 v3, v1
	v_mov_b32_e32 v4, v1
	v_mov_b32_e32 v5, v1
	v_mov_b32_e32 v6, v1
	v_mov_b32_e32 v7, v1
	v_mov_b32_e32 v8, v1
	v_mov_b32_e32 v9, v1
	v_mov_b32_e32 v10, v1
	v_mov_b32_e32 v11, v1
	v_mov_b32_e32 v12, v1
	v_mov_b32_e32 v13, v1
	v_mov_b64_e32 v[94:95], v[14:15]
	v_mov_b64_e32 v[126:127], v[14:15]
	v_mov_b64_e32 v[92:93], v[12:13]
	v_mov_b64_e32 v[90:91], v[10:11]
	v_mov_b64_e32 v[88:89], v[8:9]
	v_mov_b64_e32 v[86:87], v[6:7]
	v_mov_b64_e32 v[84:85], v[4:5]
	v_mov_b64_e32 v[82:83], v[2:3]
	v_mov_b64_e32 v[80:81], v[0:1]
	v_mov_b64_e32 v[124:125], v[12:13]
	v_mov_b64_e32 v[122:123], v[10:11]
	v_mov_b64_e32 v[120:121], v[8:9]
	v_mov_b64_e32 v[118:119], v[6:7]
	v_mov_b64_e32 v[116:117], v[4:5]
	v_mov_b64_e32 v[114:115], v[2:3]
	v_mov_b64_e32 v[112:113], v[0:1]

; #define LAS __attribute__((address_space(3)))
; __device__ __forceinline__ float max3f(float a, float b, float c) { float r; asm("v_max3_f32 %0, %1, %2, %3" : "=v"(r) : "v"(a), "v"(b), "v"(c)); return r; }
; template <bool QK, bool SM>
; __device__ __forceinline__ void attn_step(const LAS unsigned char* kb, const LAS unsigned char* vbp, const bf16x8 (&qr)[6],
;                                           f32x16& s0, f32x16& s1, f32x16& o0, f32x16& o1, float& mrow, float& lsum) {
;     ...
;         for (int s = 0; s < 6; ++s) { const bf16x8 ka = *(const LAS bf16x8*)(kb + s * 32), kc = *(const LAS bf16x8*)(kb + 32 * KPITCH + s * 32);
;             n0 = __builtin_amdgcn_mfma_f32_32x32x16_bf16(ka, qr[s], n0, 0, 0, 0); n1 = __builtin_amdgcn_mfma_f32_32x32x16_bf16(kc, qr[s], n1, 0, 0, 0); }
;     }
;     if constexpr (SM) {
;         float mx = max3f(s0[0], s1[0], s0[1]); mx = max3f(mx, s1[1], s0[2]); float my = max3f(s1[2], s0[3], s1[3]);
; #pragma unroll
;         for (int r = 4; r < 16; r += 4) { mx = max3f(mx, s0[r], s1[r]); my = max3f(my, s0[r + 1], s1[r + 1]); mx = max3f(mx, s0[r + 2], s1[r + 2]); my = max3f(my, s0[r + 3], s1[r + 3]); }
;         mx = fmaxf(mx, my);
;         { const auto rr = __builtin_amdgcn_permlane32_swap(__float_as_uint(mx), __float_as_uint(mx), false, false); mx = fmaxf(__uint_as_float(rr[0]), __uint_as_float(rr[1])); }
;         const float mnew = fmaxf(mrow, mx), alpha = __builtin_amdgcn_exp2f(mrow - mnew); mrow = mnew;
;         const f32x2 m2 = (f32x2){mnew, mnew}; f32x2 ps2 = (f32x2){0.f, 0.f};
; #pragma unroll
;         for (int r = 0; r < 16; r += 2) { f32x2 a = (f32x2){s0[r], s0[r + 1]} - m2, b = (f32x2){s1[r], s1[r + 1]} - m2;
;             a.x = __builtin_amdgcn_exp2f(a.x); a.y = __builtin_amdgcn_exp2f(a.y); b.x = __builtin_amdgcn_exp2f(b.x); b.y = __builtin_amdgcn_exp2f(b.y);
;             s0[r] = a.x; s0[r + 1] = a.y; s1[r] = b.x; s1[r + 1] = b.y; ps2 += a + b; }
;         const float ps = ps2.x + ps2.y;
;         lsum = lsum * alpha + ps;
; #pragma unroll
;         for (int r = 0; r < 16; ++r) { o0[r] *= alpha; o1[r] *= alpha; }
.LBB0_952:
	ds_read_b128 v[2:5], v213 offset:13312
	ds_read_b128 v[10:13], v213 offset:13344
	ds_read_b128 v[80:83], v213 offset:19968
	ds_read_b128 v[96:99], v213 offset:20000
	ds_read_b128 v[84:87], v213 offset:13376
	ds_read_b128 v[88:91], v213 offset:13408
	s_waitcnt lgkmcnt(5)
	v_mfma_f32_32x32x16_bf16 v[112:127], v[2:5], v[164:167], v[218:233]
	ds_read_b128 v[100:103], v213 offset:20032
	ds_read_b128 v[104:107], v213 offset:20064
	ds_read_b128 v[92:95], v213 offset:13440
	ds_read_b128 v[108:111], v213 offset:13472
	ds_read_b128 v[6:9], v213 offset:20096
	ds_read_b128 v[2:5], v213 offset:20128
	v_max3_f32 v0, v48, v16, v49
	s_nop 0
	v_max3_f32 v0, v0, v17, v50
	s_nop 0
	v_max3_f32 v0, v0, v52, v20
	s_waitcnt lgkmcnt(10)
	v_mfma_f32_32x32x16_bf16 v[112:127], v[10:13], v[160:163], v[112:127]
	v_max3_f32 v10, v18, v51, v19
	v_max3_f32 v0, v0, v54, v22
	s_nop 0
	v_max3_f32 v10, v10, v53, v21
	v_max3_f32 v0, v0, v56, v24
	s_nop 0
	v_max3_f32 v10, v10, v55, v23
	s_waitcnt lgkmcnt(7)
	v_mfma_f32_32x32x16_bf16 v[112:127], v[84:87], v[156:159], v[112:127]
	v_max3_f32 v10, v10, v57, v25
	v_max3_f32 v0, v0, v58, v26
	s_nop 0
	v_max3_f32 v10, v10, v59, v27
	v_max3_f32 v0, v0, v60, v28
	s_nop 0
	v_max3_f32 v10, v10, v61, v29
	s_waitcnt lgkmcnt(6)
	v_mfma_f32_32x32x16_bf16 v[112:127], v[88:91], v[152:155], v[112:127]
	v_max3_f32 v10, v10, v63, v31
	v_max3_f32 v0, v0, v62, v30
	s_nop 0
	v_max_f32_e32 v10, v10, v10
	v_max_f32_e32 v0, v0, v0
	v_max_f32_e32 v0, v0, v10
	v_mov_b32_e32 v10, v0
	s_waitcnt lgkmcnt(3)
	v_mfma_f32_32x32x16_bf16 v[112:127], v[92:95], v[148:151], v[112:127]
	v_permlane32_swap_b32_e32 v0, v10
	v_max_f32_e32 v0, v0, v10
	v_sub_f32_e32 v10, v0, v206
	v_cmp_lt_f32_e32 vcc, 0x41000000, v10
	v_mov_b32_e32 v208, v206
	s_nop 0
	s_cbranch_vccnz .Latt_slowA
.Latt_contA:
	v_mfma_f32_32x32x16_bf16 v[80:95], v[80:83], v[164:167], v[218:233]
	v_exp_f32_e32 v128, v48
	v_exp_f32_e32 v129, v49
	v_exp_f32_e32 v48, v16
	v_exp_f32_e32 v49, v17
	v_exp_f32_e32 v130, v50
	v_mfma_f32_32x32x16_bf16 v[80:95], v[96:99], v[160:163], v[80:95]
	v_exp_f32_e32 v131, v51
	v_exp_f32_e32 v50, v18
	v_exp_f32_e32 v51, v19
	v_add_f32_e32 v10, v128, v48
	v_add_f32_e32 v11, v129, v49
	v_add_f32_e32 v10, 0, v10
	v_add_f32_e32 v11, 0, v11
	v_add_f32_e32 v12, v130, v50
	v_add_f32_e32 v13, v131, v51
	v_mfma_f32_32x32x16_bf16 v[80:95], v[100:103], v[156:159], v[80:95]
	v_add_u32_e32 v100, v214, v204
	v_add_f32_e32 v10, v12, v10
	v_add_f32_e32 v11, v13, v11
	v_mfma_f32_32x32x16_bf16 v[80:95], v[104:107], v[152:155], v[80:95]
	v_exp_f32_e32 v12, v52
	v_exp_f32_e32 v13, v53
	v_exp_f32_e32 v16, v54
	v_exp_f32_e32 v17, v55

; __device__ __forceinline__ unsigned cvt_pk_bf16(float lo, float hi) { unsigned r; asm("v_cvt_pk_bf16_f32 %0, %1, %2" : "=v"(r) : "v"(lo), "v"(hi)); return r; }
; template <bool QK, bool SM>
; __device__ __forceinline__ void attn_step(const LAS unsigned char* kb, const LAS unsigned char* vbp, const bf16x8 (&qr)[6],
;                                           f32x16& s0, f32x16& s1, f32x16& o0, f32x16& o1, float& mrow, float& lsum) {
;     ...
;         for (int S = 0; S < 4; ++S) { u32x4 w;
;             if (S < 2) { w.x = cvt_pk_bf16(s0[8 * S + 0], s0[8 * S + 1]); w.y = cvt_pk_bf16(s0[8 * S + 2], s0[8 * S + 3]); w.z = cvt_pk_bf16(s0[8 * S + 4], s0[8 * S + 5]); w.w = cvt_pk_bf16(s0[8 * S + 6], s0[8 * S + 7]); }
;             else { w.x = cvt_pk_bf16(s1[8 * S - 16], s1[8 * S - 15]); w.y = cvt_pk_bf16(s1[8 * S - 14], s1[8 * S - 13]); w.z = cvt_pk_bf16(s1[8 * S - 12], s1[8 * S - 11]); w.w = cvt_pk_bf16(s1[8 * S - 10], s1[8 * S - 9]); }
;             pb[S] = __builtin_bit_cast(bf16x8, w); }
	v_cvt_pk_bf16_f32 v96, v128, v129

; #define LAS __attribute__((address_space(3)))
; template <bool QK, bool SM>
; __device__ __forceinline__ void attn_step(const LAS unsigned char* kb, const LAS unsigned char* vbp, const bf16x8 (&qr)[6],
;                                           f32x16& s0, f32x16& s1, f32x16& o0, f32x16& o1, float& mrow, float& lsum) {
;     ...
;         for (int s = 0; s < 6; ++s) { const bf16x8 ka = *(const LAS bf16x8*)(kb + s * 32), kc = *(const LAS bf16x8*)(kb + 32 * KPITCH + s * 32);
;             n0 = __builtin_amdgcn_mfma_f32_32x32x16_bf16(ka, qr[s], n0, 0, 0, 0); n1 = __builtin_amdgcn_mfma_f32_32x32x16_bf16(kc, qr[s], n1, 0, 0, 0); }
;     ...
;             const u32x2 a0 = *(const LAS u32x2*)(vbp + S * 32), a1 = *(const LAS u32x2*)(vbp + S * 32 + 16);
;             const u32x2 c0 = *(const LAS u32x2*)(vbp + 32 * VPITCH + S * 32), c1 = *(const LAS u32x2*)(vbp + 32 * VPITCH + S * 32 + 16);
	s_waitcnt lgkmcnt(2)
	v_mfma_f32_32x32x16_bf16 v[112:127], v[108:111], v[144:147], v[112:127]
	v_add_u32_e32 v110, 0x6800, v100
	v_add_u32_e32 v111, 0x7800, v100
	ds_read2_b64 v[100:103], v111 offset0:32 offset1:34

; __device__ __forceinline__ unsigned cvt_pk_bf16(float lo, float hi) { unsigned r; asm("v_cvt_pk_bf16_f32 %0, %1, %2" : "=v"(r) : "v"(lo), "v"(hi)); return r; }
; template <bool QK, bool SM>
; __device__ __forceinline__ void attn_step(const LAS unsigned char* kb, const LAS unsigned char* vbp, const bf16x8 (&qr)[6],
;                                           f32x16& s0, f32x16& s1, f32x16& o0, f32x16& o1, float& mrow, float& lsum) {
;     ...
;         for (int S = 0; S < 4; ++S) { u32x4 w;
;             if (S < 2) { w.x = cvt_pk_bf16(s0[8 * S + 0], s0[8 * S + 1]); w.y = cvt_pk_bf16(s0[8 * S + 2], s0[8 * S + 3]); w.z = cvt_pk_bf16(s0[8 * S + 4], s0[8 * S + 5]); w.w = cvt_pk_bf16(s0[8 * S + 6], s0[8 * S + 7]); }
;             else { w.x = cvt_pk_bf16(s1[8 * S - 16], s1[8 * S - 15]); w.y = cvt_pk_bf16(s1[8 * S - 14], s1[8 * S - 13]); w.z = cvt_pk_bf16(s1[8 * S - 12], s1[8 * S - 11]); w.w = cvt_pk_bf16(s1[8 * S - 10], s1[8 * S - 9]); }
;             pb[S] = __builtin_bit_cast(bf16x8, w); }
	v_cvt_pk_bf16_f32 v97, v130, v131


; __device__ __forceinline__ unsigned cvt_pk_bf16(float lo, float hi) { unsigned r; asm("v_cvt_pk_bf16_f32 %0, %1, %2" : "=v"(r) : "v"(lo), "v"(hi)); return r; }
; template <bool QK, bool SM>
; __device__ __forceinline__ void attn_step(const LAS unsigned char* kb, const LAS unsigned char* vbp, const bf16x8 (&qr)[6],
;                                           f32x16& s0, f32x16& s1, f32x16& o0, f32x16& o1, float& mrow, float& lsum) {
;     ...
;         for (int S = 0; S < 4; ++S) { u32x4 w;
;             if (S < 2) { w.x = cvt_pk_bf16(s0[8 * S + 0], s0[8 * S + 1]); w.y = cvt_pk_bf16(s0[8 * S + 2], s0[8 * S + 3]); w.z = cvt_pk_bf16(s0[8 * S + 4], s0[8 * S + 5]); w.w = cvt_pk_bf16(s0[8 * S + 6], s0[8 * S + 7]); }
;             else { w.x = cvt_pk_bf16(s1[8 * S - 16], s1[8 * S - 15]); w.y = cvt_pk_bf16(s1[8 * S - 14], s1[8 * S - 13]); w.z = cvt_pk_bf16(s1[8 * S - 12], s1[8 * S - 11]); w.w = cvt_pk_bf16(s1[8 * S - 10], s1[8 * S - 9]); }
;             pb[S] = __builtin_bit_cast(bf16x8, w); }
	v_cvt_pk_bf16_f32 v98, v12, v13

; #define LAS __attribute__((address_space(3)))
; template <bool QK, bool SM>
; __device__ __forceinline__ void attn_step(const LAS unsigned char* kb, const LAS unsigned char* vbp, const bf16x8 (&qr)[6],
;                                           f32x16& s0, f32x16& s1, f32x16& o0, f32x16& o1, float& mrow, float& lsum) {
;     ...
;         for (int s = 0; s < 6; ++s) { const bf16x8 ka = *(const LAS bf16x8*)(kb + s * 32), kc = *(const LAS bf16x8*)(kb + 32 * KPITCH + s * 32);
;             n0 = __builtin_amdgcn_mfma_f32_32x32x16_bf16(ka, qr[s], n0, 0, 0, 0); n1 = __builtin_amdgcn_mfma_f32_32x32x16_bf16(kc, qr[s], n1, 0, 0, 0); }
;     ...
;             const u32x2 a0 = *(const LAS u32x2*)(vbp + S * 32), a1 = *(const LAS u32x2*)(vbp + S * 32 + 16);
;             const u32x2 c0 = *(const LAS u32x2*)(vbp + 32 * VPITCH + S * 32), c1 = *(const LAS u32x2*)(vbp + 32 * VPITCH + S * 32 + 16);
	s_waitcnt lgkmcnt(2)
	v_mfma_f32_32x32x16_bf16 v[80:95], v[6:9], v[148:151], v[80:95]
	ds_read2_b64 v[6:9], v110 offset1:2

; __device__ __forceinline__ unsigned cvt_pk_bf16(float lo, float hi) { unsigned r; asm("v_cvt_pk_bf16_f32 %0, %1, %2" : "=v"(r) : "v"(lo), "v"(hi)); return r; }
; template <bool QK, bool SM>
; __device__ __forceinline__ void attn_step(const LAS unsigned char* kb, const LAS unsigned char* vbp, const bf16x8 (&qr)[6],
;                                           f32x16& s0, f32x16& s1, f32x16& o0, f32x16& o1, float& mrow, float& lsum) {
;     ...
;         for (int S = 0; S < 4; ++S) { u32x4 w;
;             if (S < 2) { w.x = cvt_pk_bf16(s0[8 * S + 0], s0[8 * S + 1]); w.y = cvt_pk_bf16(s0[8 * S + 2], s0[8 * S + 3]); w.z = cvt_pk_bf16(s0[8 * S + 4], s0[8 * S + 5]); w.w = cvt_pk_bf16(s0[8 * S + 6], s0[8 * S + 7]); }
;             else { w.x = cvt_pk_bf16(s1[8 * S - 16], s1[8 * S - 15]); w.y = cvt_pk_bf16(s1[8 * S - 14], s1[8 * S - 13]); w.z = cvt_pk_bf16(s1[8 * S - 12], s1[8 * S - 11]); w.w = cvt_pk_bf16(s1[8 * S - 10], s1[8 * S - 9]); }
;             pb[S] = __builtin_bit_cast(bf16x8, w); }
	v_cvt_pk_bf16_f32 v99, v16, v17

; #define LAS __attribute__((address_space(3)))
; template <bool QK, bool SM>
; __device__ __forceinline__ void attn_step(const LAS unsigned char* kb, const LAS unsigned char* vbp, const bf16x8 (&qr)[6],
;                                           f32x16& s0, f32x16& s1, f32x16& o0, f32x16& o1, float& mrow, float& lsum) {
;     ...
;         for (int r = 0; r < 16; r += 2) { f32x2 a = (f32x2){s0[r], s0[r + 1]} - m2, b = (f32x2){s1[r], s1[r + 1]} - m2;
;             a.x = __builtin_amdgcn_exp2f(a.x); a.y = __builtin_amdgcn_exp2f(a.y); b.x = __builtin_amdgcn_exp2f(b.x); b.y = __builtin_amdgcn_exp2f(b.y);
;             s0[r] = a.x; s0[r + 1] = a.y; s1[r] = b.x; s1[r + 1] = b.y; ps2 += a + b; }
;     ...
;         for (int S = 0; S < 4; ++S) {
;             const u32x2 a0 = *(const LAS u32x2*)(vbp + S * 32), a1 = *(const LAS u32x2*)(vbp + S * 32 + 16);
;             const u32x2 c0 = *(const LAS u32x2*)(vbp + 32 * VPITCH + S * 32), c1 = *(const LAS u32x2*)(vbp + 32 * VPITCH + S * 32 + 16);
;             const bf16x8 va = __builtin_bit_cast(bf16x8, (u32x4){a0.x, a0.y, a1.x, a1.y}), vc = __builtin_bit_cast(bf16x8, (u32x4){c0.x, c0.y, c1.x, c1.y});
;             o0 = __builtin_amdgcn_mfma_f32_32x32x16_bf16(va, pb[S], o0, 0, 0, 0); o1 = __builtin_amdgcn_mfma_f32_32x32x16_bf16(vc, pb[S], o1, 0, 0, 0); }
	s_waitcnt lgkmcnt(0)
	s_nop 0
	v_mfma_f32_32x32x16_bf16 v[32:47], v[6:9], v[96:99], v[32:47]
	ds_read2_b64 v[6:9], v110 offset0:4 offset1:6
	v_mov_b32_e32 v14, v20
	v_mov_b32_e32 v15, v21
	v_mfma_f32_32x32x16_bf16 v[64:79], v[100:103], v[96:99], v[64:79]
	ds_read2_b64 v[100:103], v111 offset0:36 offset1:38
	v_exp_f32_e32 v18, v56
	v_exp_f32_e32 v19, v57
	v_exp_f32_e32 v20, v58
	v_exp_f32_e32 v21, v59
	v_exp_f32_e32 v52, v60
	v_exp_f32_e32 v53, v61
	v_exp_f32_e32 v104, v62
	v_exp_f32_e32 v105, v63

; __device__ __forceinline__ unsigned cvt_pk_bf16(float lo, float hi) { unsigned r; asm("v_cvt_pk_bf16_f32 %0, %1, %2" : "=v"(r) : "v"(lo), "v"(hi)); return r; }
; template <bool QK, bool SM>
; __device__ __forceinline__ void attn_step(const LAS unsigned char* kb, const LAS unsigned char* vbp, const bf16x8 (&qr)[6],
;                                           f32x16& s0, f32x16& s1, f32x16& o0, f32x16& o1, float& mrow, float& lsum) {
;     ...
;         for (int S = 0; S < 4; ++S) { u32x4 w;
;             if (S < 2) { w.x = cvt_pk_bf16(s0[8 * S + 0], s0[8 * S + 1]); w.y = cvt_pk_bf16(s0[8 * S + 2], s0[8 * S + 3]); w.z = cvt_pk_bf16(s0[8 * S + 4], s0[8 * S + 5]); w.w = cvt_pk_bf16(s0[8 * S + 6], s0[8 * S + 7]); }
;             else { w.x = cvt_pk_bf16(s1[8 * S - 16], s1[8 * S - 15]); w.y = cvt_pk_bf16(s1[8 * S - 14], s1[8 * S - 13]); w.z = cvt_pk_bf16(s1[8 * S - 12], s1[8 * S - 11]); w.w = cvt_pk_bf16(s1[8 * S - 10], s1[8 * S - 9]); }
;             pb[S] = __builtin_bit_cast(bf16x8, w); }
	v_cvt_pk_bf16_f32 v96, v18, v19


; __device__ __forceinline__ unsigned cvt_pk_bf16(float lo, float hi) { unsigned r; asm("v_cvt_pk_bf16_f32 %0, %1, %2" : "=v"(r) : "v"(lo), "v"(hi)); return r; }
; template <bool QK, bool SM>
; __device__ __forceinline__ void attn_step(const LAS unsigned char* kb, const LAS unsigned char* vbp, const bf16x8 (&qr)[6],
;                                           f32x16& s0, f32x16& s1, f32x16& o0, f32x16& o1, float& mrow, float& lsum) {
;     ...
;         for (int S = 0; S < 4; ++S) { u32x4 w;
;             if (S < 2) { w.x = cvt_pk_bf16(s0[8 * S + 0], s0[8 * S + 1]); w.y = cvt_pk_bf16(s0[8 * S + 2], s0[8 * S + 3]); w.z = cvt_pk_bf16(s0[8 * S + 4], s0[8 * S + 5]); w.w = cvt_pk_bf16(s0[8 * S + 6], s0[8 * S + 7]); }
;             else { w.x = cvt_pk_bf16(s1[8 * S - 16], s1[8 * S - 15]); w.y = cvt_pk_bf16(s1[8 * S - 14], s1[8 * S - 13]); w.z = cvt_pk_bf16(s1[8 * S - 12], s1[8 * S - 11]); w.w = cvt_pk_bf16(s1[8 * S - 10], s1[8 * S - 9]); }
;             pb[S] = __builtin_bit_cast(bf16x8, w); }
	v_cvt_pk_bf16_f32 v97, v20, v21


; __device__ __forceinline__ unsigned cvt_pk_bf16(float lo, float hi) { unsigned r; asm("v_cvt_pk_bf16_f32 %0, %1, %2" : "=v"(r) : "v"(lo), "v"(hi)); return r; }
; template <bool QK, bool SM>
; __device__ __forceinline__ void attn_step(const LAS unsigned char* kb, const LAS unsigned char* vbp, const bf16x8 (&qr)[6],
;                                           f32x16& s0, f32x16& s1, f32x16& o0, f32x16& o1, float& mrow, float& lsum) {
;     ...
;         for (int S = 0; S < 4; ++S) { u32x4 w;
;             if (S < 2) { w.x = cvt_pk_bf16(s0[8 * S + 0], s0[8 * S + 1]); w.y = cvt_pk_bf16(s0[8 * S + 2], s0[8 * S + 3]); w.z = cvt_pk_bf16(s0[8 * S + 4], s0[8 * S + 5]); w.w = cvt_pk_bf16(s0[8 * S + 6], s0[8 * S + 7]); }
;             else { w.x = cvt_pk_bf16(s1[8 * S - 16], s1[8 * S - 15]); w.y = cvt_pk_bf16(s1[8 * S - 14], s1[8 * S - 13]); w.z = cvt_pk_bf16(s1[8 * S - 12], s1[8 * S - 11]); w.w = cvt_pk_bf16(s1[8 * S - 10], s1[8 * S - 9]); }
;             pb[S] = __builtin_bit_cast(bf16x8, w); }
	v_cvt_pk_bf16_f32 v98, v52, v53


; __device__ __forceinline__ unsigned cvt_pk_bf16(float lo, float hi) { unsigned r; asm("v_cvt_pk_bf16_f32 %0, %1, %2" : "=v"(r) : "v"(lo), "v"(hi)); return r; }
; template <bool QK, bool SM>
; __device__ __forceinline__ void attn_step(const LAS unsigned char* kb, const LAS unsigned char* vbp, const bf16x8 (&qr)[6],
;                                           f32x16& s0, f32x16& s1, f32x16& o0, f32x16& o1, float& mrow, float& lsum) {
;     ...
;         for (int S = 0; S < 4; ++S) { u32x4 w;
;             if (S < 2) { w.x = cvt_pk_bf16(s0[8 * S + 0], s0[8 * S + 1]); w.y = cvt_pk_bf16(s0[8 * S + 2], s0[8 * S + 3]); w.z = cvt_pk_bf16(s0[8 * S + 4], s0[8 * S + 5]); w.w = cvt_pk_bf16(s0[8 * S + 6], s0[8 * S + 7]); }
;             else { w.x = cvt_pk_bf16(s1[8 * S - 16], s1[8 * S - 15]); w.y = cvt_pk_bf16(s1[8 * S - 14], s1[8 * S - 13]); w.z = cvt_pk_bf16(s1[8 * S - 12], s1[8 * S - 11]); w.w = cvt_pk_bf16(s1[8 * S - 10], s1[8 * S - 9]); }
;             pb[S] = __builtin_bit_cast(bf16x8, w); }
	v_cvt_pk_bf16_f32 v99, v104, v105

; #define LAS __attribute__((address_space(3)))
; __device__ __forceinline__ unsigned cvt_pk_bf16(float lo, float hi) { unsigned r; asm("v_cvt_pk_bf16_f32 %0, %1, %2" : "=v"(r) : "v"(lo), "v"(hi)); return r; }
; template <bool QK, bool SM>
; __device__ __forceinline__ void attn_step(const LAS unsigned char* kb, const LAS unsigned char* vbp, const bf16x8 (&qr)[6],
;                                           f32x16& s0, f32x16& s1, f32x16& o0, f32x16& o1, float& mrow, float& lsum) {
;     ...
;         for (int r = 0; r < 16; r += 2) { f32x2 a = (f32x2){s0[r], s0[r + 1]} - m2, b = (f32x2){s1[r], s1[r + 1]} - m2;
;             a.x = __builtin_amdgcn_exp2f(a.x); a.y = __builtin_amdgcn_exp2f(a.y); b.x = __builtin_amdgcn_exp2f(b.x); b.y = __builtin_amdgcn_exp2f(b.y);
;             s0[r] = a.x; s0[r + 1] = a.y; s1[r] = b.x; s1[r + 1] = b.y; ps2 += a + b; }
;         const float ps = ps2.x + ps2.y;
;         lsum = lsum * alpha + ps;
; #pragma unroll
;         for (int r = 0; r < 16; ++r) { o0[r] *= alpha; o1[r] *= alpha; }
;         bf16x8 pb[4];
; #pragma unroll
;         for (int S = 0; S < 4; ++S) { u32x4 w;
;             if (S < 2) { w.x = cvt_pk_bf16(s0[8 * S + 0], s0[8 * S + 1]); w.y = cvt_pk_bf16(s0[8 * S + 2], s0[8 * S + 3]); w.z = cvt_pk_bf16(s0[8 * S + 4], s0[8 * S + 5]); w.w = cvt_pk_bf16(s0[8 * S + 6], s0[8 * S + 7]); }
;             else { w.x = cvt_pk_bf16(s1[8 * S - 16], s1[8 * S - 15]); w.y = cvt_pk_bf16(s1[8 * S - 14], s1[8 * S - 13]); w.z = cvt_pk_bf16(s1[8 * S - 12], s1[8 * S - 11]); w.w = cvt_pk_bf16(s1[8 * S - 10], s1[8 * S - 9]); }
;             pb[S] = __builtin_bit_cast(bf16x8, w); }
; #pragma unroll
;         for (int S = 0; S < 4; ++S) {
;             const u32x2 a0 = *(const LAS u32x2*)(vbp + S * 32), a1 = *(const LAS u32x2*)(vbp + S * 32 + 16);
;             const u32x2 c0 = *(const LAS u32x2*)(vbp + 32 * VPITCH + S * 32), c1 = *(const LAS u32x2*)(vbp + 32 * VPITCH + S * 32 + 16);
;             const bf16x8 va = __builtin_bit_cast(bf16x8, (u32x4){a0.x, a0.y, a1.x, a1.y}), vc = __builtin_bit_cast(bf16x8, (u32x4){c0.x, c0.y, c1.x, c1.y});
;             o0 = __builtin_amdgcn_mfma_f32_32x32x16_bf16(va, pb[S], o0, 0, 0, 0); o1 = __builtin_amdgcn_mfma_f32_32x32x16_bf16(vc, pb[S], o1, 0, 0, 0); }
	v_exp_f32_e32 v14, v14
	s_waitcnt lgkmcnt(1)
	v_mfma_f32_32x32x16_bf16 v[32:47], v[6:9], v[96:99], v[32:47]
	v_exp_f32_e32 v106, v22
	v_exp_f32_e32 v107, v23
	ds_read2_b64 v[6:9], v110 offset0:8 offset1:10
	v_exp_f32_e32 v15, v15
	v_exp_f32_e32 v108, v24
	s_waitcnt lgkmcnt(1)
	v_mfma_f32_32x32x16_bf16 v[64:79], v[100:103], v[96:99], v[64:79]
	ds_read2_b64 v[96:99], v111 offset0:40 offset1:42
	v_exp_f32_e32 v109, v25

; __device__ __forceinline__ unsigned cvt_pk_bf16(float lo, float hi) { unsigned r; asm("v_cvt_pk_bf16_f32 %0, %1, %2" : "=v"(r) : "v"(lo), "v"(hi)); return r; }
; template <bool QK, bool SM>
; __device__ __forceinline__ void attn_step(const LAS unsigned char* kb, const LAS unsigned char* vbp, const bf16x8 (&qr)[6],
;                                           f32x16& s0, f32x16& s1, f32x16& o0, f32x16& o1, float& mrow, float& lsum) {
;     ...
;         for (int S = 0; S < 4; ++S) { u32x4 w;
;             if (S < 2) { w.x = cvt_pk_bf16(s0[8 * S + 0], s0[8 * S + 1]); w.y = cvt_pk_bf16(s0[8 * S + 2], s0[8 * S + 3]); w.z = cvt_pk_bf16(s0[8 * S + 4], s0[8 * S + 5]); w.w = cvt_pk_bf16(s0[8 * S + 6], s0[8 * S + 7]); }
;             else { w.x = cvt_pk_bf16(s1[8 * S - 16], s1[8 * S - 15]); w.y = cvt_pk_bf16(s1[8 * S - 14], s1[8 * S - 13]); w.z = cvt_pk_bf16(s1[8 * S - 12], s1[8 * S - 11]); w.w = cvt_pk_bf16(s1[8 * S - 10], s1[8 * S - 9]); }
;             pb[S] = __builtin_bit_cast(bf16x8, w); }
	v_cvt_pk_bf16_f32 v22, v48, v49


; __device__ __forceinline__ unsigned cvt_pk_bf16(float lo, float hi) { unsigned r; asm("v_cvt_pk_bf16_f32 %0, %1, %2" : "=v"(r) : "v"(lo), "v"(hi)); return r; }
; template <bool QK, bool SM>
; __device__ __forceinline__ void attn_step(const LAS unsigned char* kb, const LAS unsigned char* vbp, const bf16x8 (&qr)[6],
;                                           f32x16& s0, f32x16& s1, f32x16& o0, f32x16& o1, float& mrow, float& lsum) {
;     ...
;         for (int S = 0; S < 4; ++S) { u32x4 w;
;             if (S < 2) { w.x = cvt_pk_bf16(s0[8 * S + 0], s0[8 * S + 1]); w.y = cvt_pk_bf16(s0[8 * S + 2], s0[8 * S + 3]); w.z = cvt_pk_bf16(s0[8 * S + 4], s0[8 * S + 5]); w.w = cvt_pk_bf16(s0[8 * S + 6], s0[8 * S + 7]); }
;             else { w.x = cvt_pk_bf16(s1[8 * S - 16], s1[8 * S - 15]); w.y = cvt_pk_bf16(s1[8 * S - 14], s1[8 * S - 13]); w.z = cvt_pk_bf16(s1[8 * S - 12], s1[8 * S - 11]); w.w = cvt_pk_bf16(s1[8 * S - 10], s1[8 * S - 9]); }
;             pb[S] = __builtin_bit_cast(bf16x8, w); }
	v_cvt_pk_bf16_f32 v23, v50, v51


; __device__ __forceinline__ unsigned cvt_pk_bf16(float lo, float hi) { unsigned r; asm("v_cvt_pk_bf16_f32 %0, %1, %2" : "=v"(r) : "v"(lo), "v"(hi)); return r; }
; template <bool QK, bool SM>
; __device__ __forceinline__ void attn_step(const LAS unsigned char* kb, const LAS unsigned char* vbp, const bf16x8 (&qr)[6],
;                                           f32x16& s0, f32x16& s1, f32x16& o0, f32x16& o1, float& mrow, float& lsum) {
;     ...
;         for (int S = 0; S < 4; ++S) { u32x4 w;
;             if (S < 2) { w.x = cvt_pk_bf16(s0[8 * S + 0], s0[8 * S + 1]); w.y = cvt_pk_bf16(s0[8 * S + 2], s0[8 * S + 3]); w.z = cvt_pk_bf16(s0[8 * S + 4], s0[8 * S + 5]); w.w = cvt_pk_bf16(s0[8 * S + 6], s0[8 * S + 7]); }
;             else { w.x = cvt_pk_bf16(s1[8 * S - 16], s1[8 * S - 15]); w.y = cvt_pk_bf16(s1[8 * S - 14], s1[8 * S - 13]); w.z = cvt_pk_bf16(s1[8 * S - 12], s1[8 * S - 11]); w.w = cvt_pk_bf16(s1[8 * S - 10], s1[8 * S - 9]); }
;             pb[S] = __builtin_bit_cast(bf16x8, w); }
	v_cvt_pk_bf16_f32 v24, v14, v15


; __device__ __forceinline__ unsigned cvt_pk_bf16(float lo, float hi) { unsigned r; asm("v_cvt_pk_bf16_f32 %0, %1, %2" : "=v"(r) : "v"(lo), "v"(hi)); return r; }
; template <bool QK, bool SM>
; __device__ __forceinline__ void attn_step(const LAS unsigned char* kb, const LAS unsigned char* vbp, const bf16x8 (&qr)[6],
;                                           f32x16& s0, f32x16& s1, f32x16& o0, f32x16& o1, float& mrow, float& lsum) {
;     ...
;         for (int S = 0; S < 4; ++S) { u32x4 w;
;             if (S < 2) { w.x = cvt_pk_bf16(s0[8 * S + 0], s0[8 * S + 1]); w.y = cvt_pk_bf16(s0[8 * S + 2], s0[8 * S + 3]); w.z = cvt_pk_bf16(s0[8 * S + 4], s0[8 * S + 5]); w.w = cvt_pk_bf16(s0[8 * S + 6], s0[8 * S + 7]); }
;             else { w.x = cvt_pk_bf16(s1[8 * S - 16], s1[8 * S - 15]); w.y = cvt_pk_bf16(s1[8 * S - 14], s1[8 * S - 13]); w.z = cvt_pk_bf16(s1[8 * S - 12], s1[8 * S - 11]); w.w = cvt_pk_bf16(s1[8 * S - 10], s1[8 * S - 9]); }
;             pb[S] = __builtin_bit_cast(bf16x8, w); }
	v_cvt_pk_bf16_f32 v25, v106, v107

; #define LAS __attribute__((address_space(3)))
; template <bool QK, bool SM>
; __device__ __forceinline__ void attn_step(const LAS unsigned char* kb, const LAS unsigned char* vbp, const bf16x8 (&qr)[6],
;                                           f32x16& s0, f32x16& s1, f32x16& o0, f32x16& o1, float& mrow, float& lsum) {
;     ...
;         for (int s = 0; s < 6; ++s) { const bf16x8 ka = *(const LAS bf16x8*)(kb + s * 32), kc = *(const LAS bf16x8*)(kb + 32 * KPITCH + s * 32);
;             n0 = __builtin_amdgcn_mfma_f32_32x32x16_bf16(ka, qr[s], n0, 0, 0, 0); n1 = __builtin_amdgcn_mfma_f32_32x32x16_bf16(kc, qr[s], n1, 0, 0, 0); }
;     ...
;         for (int r = 0; r < 16; r += 2) { f32x2 a = (f32x2){s0[r], s0[r + 1]} - m2, b = (f32x2){s1[r], s1[r + 1]} - m2;
;             a.x = __builtin_amdgcn_exp2f(a.x); a.y = __builtin_amdgcn_exp2f(a.y); b.x = __builtin_amdgcn_exp2f(b.x); b.y = __builtin_amdgcn_exp2f(b.y);
;             s0[r] = a.x; s0[r + 1] = a.y; s1[r] = b.x; s1[r + 1] = b.y; ps2 += a + b; }
;         const float ps = ps2.x + ps2.y;
;         lsum = lsum * alpha + ps;
; #pragma unroll
;         for (int r = 0; r < 16; ++r) { o0[r] *= alpha; o1[r] *= alpha; }
;         bf16x8 pb[4];
; #pragma unroll
;         for (int S = 0; S < 4; ++S) { u32x4 w;
;             if (S < 2) { w.x = cvt_pk_bf16(s0[8 * S + 0], s0[8 * S + 1]); w.y = cvt_pk_bf16(s0[8 * S + 2], s0[8 * S + 3]); w.z = cvt_pk_bf16(s0[8 * S + 4], s0[8 * S + 5]); w.w = cvt_pk_bf16(s0[8 * S + 6], s0[8 * S + 7]); }
;             else { w.x = cvt_pk_bf16(s1[8 * S - 16], s1[8 * S - 15]); w.y = cvt_pk_bf16(s1[8 * S - 14], s1[8 * S - 13]); w.z = cvt_pk_bf16(s1[8 * S - 12], s1[8 * S - 11]); w.w = cvt_pk_bf16(s1[8 * S - 10], s1[8 * S - 9]); }
;             pb[S] = __builtin_bit_cast(bf16x8, w); }
; #pragma unroll
;         for (int S = 0; S < 4; ++S) {
;             const u32x2 a0 = *(const LAS u32x2*)(vbp + S * 32), a1 = *(const LAS u32x2*)(vbp + S * 32 + 16);
;             const u32x2 c0 = *(const LAS u32x2*)(vbp + 32 * VPITCH + S * 32), c1 = *(const LAS u32x2*)(vbp + 32 * VPITCH + S * 32 + 16);
;             const bf16x8 va = __builtin_bit_cast(bf16x8, (u32x4){a0.x, a0.y, a1.x, a1.y}), vc = __builtin_bit_cast(bf16x8, (u32x4){c0.x, c0.y, c1.x, c1.y});
;             o0 = __builtin_amdgcn_mfma_f32_32x32x16_bf16(va, pb[S], o0, 0, 0, 0); o1 = __builtin_amdgcn_mfma_f32_32x32x16_bf16(vc, pb[S], o1, 0, 0, 0); }
	v_mfma_f32_32x32x16_bf16 v[80:95], v[2:5], v[144:147], v[80:95]
	v_exp_f32_e32 v100, v26
	v_exp_f32_e32 v101, v27
	s_nop 0
	v_exp_f32_e32 v30, v30
	v_exp_f32_e32 v31, v31
	s_waitcnt lgkmcnt(1)
	v_mfma_f32_32x32x16_bf16 v[32:47], v[6:9], v[22:25], v[32:47]
	v_mov_b32_e32 v6, v28
	v_mov_b32_e32 v7, v29
	ds_read2_b64 v[26:29], v111 offset0:44 offset1:46
	v_exp_f32_e32 v102, v6
	v_exp_f32_e32 v103, v7
	ds_read2_b64 v[6:9], v110 offset0:12 offset1:14
	s_waitcnt lgkmcnt(2)
	v_mfma_f32_32x32x16_bf16 v[64:79], v[96:99], v[22:25], v[64:79]

; __device__ __forceinline__ unsigned cvt_pk_bf16(float lo, float hi) { unsigned r; asm("v_cvt_pk_bf16_f32 %0, %1, %2" : "=v"(r) : "v"(lo), "v"(hi)); return r; }
; template <bool QK, bool SM>
; __device__ __forceinline__ void attn_step(const LAS unsigned char* kb, const LAS unsigned char* vbp, const bf16x8 (&qr)[6],
;                                           f32x16& s0, f32x16& s1, f32x16& o0, f32x16& o1, float& mrow, float& lsum) {
;     ...
;         for (int S = 0; S < 4; ++S) { u32x4 w;
;             if (S < 2) { w.x = cvt_pk_bf16(s0[8 * S + 0], s0[8 * S + 1]); w.y = cvt_pk_bf16(s0[8 * S + 2], s0[8 * S + 3]); w.z = cvt_pk_bf16(s0[8 * S + 4], s0[8 * S + 5]); w.w = cvt_pk_bf16(s0[8 * S + 6], s0[8 * S + 7]); }
;             else { w.x = cvt_pk_bf16(s1[8 * S - 16], s1[8 * S - 15]); w.y = cvt_pk_bf16(s1[8 * S - 14], s1[8 * S - 13]); w.z = cvt_pk_bf16(s1[8 * S - 12], s1[8 * S - 11]); w.w = cvt_pk_bf16(s1[8 * S - 10], s1[8 * S - 9]); }
;             pb[S] = __builtin_bit_cast(bf16x8, w); }
	v_cvt_pk_bf16_f32 v22, v108, v109


; __device__ __forceinline__ unsigned cvt_pk_bf16(float lo, float hi) { unsigned r; asm("v_cvt_pk_bf16_f32 %0, %1, %2" : "=v"(r) : "v"(lo), "v"(hi)); return r; }
; template <bool QK, bool SM>
; __device__ __forceinline__ void attn_step(const LAS unsigned char* kb, const LAS unsigned char* vbp, const bf16x8 (&qr)[6],
;                                           f32x16& s0, f32x16& s1, f32x16& o0, f32x16& o1, float& mrow, float& lsum) {
;     ...
;         for (int S = 0; S < 4; ++S) { u32x4 w;
;             if (S < 2) { w.x = cvt_pk_bf16(s0[8 * S + 0], s0[8 * S + 1]); w.y = cvt_pk_bf16(s0[8 * S + 2], s0[8 * S + 3]); w.z = cvt_pk_bf16(s0[8 * S + 4], s0[8 * S + 5]); w.w = cvt_pk_bf16(s0[8 * S + 6], s0[8 * S + 7]); }
;             else { w.x = cvt_pk_bf16(s1[8 * S - 16], s1[8 * S - 15]); w.y = cvt_pk_bf16(s1[8 * S - 14], s1[8 * S - 13]); w.z = cvt_pk_bf16(s1[8 * S - 12], s1[8 * S - 11]); w.w = cvt_pk_bf16(s1[8 * S - 10], s1[8 * S - 9]); }
;             pb[S] = __builtin_bit_cast(bf16x8, w); }
	v_cvt_pk_bf16_f32 v23, v100, v101


; __device__ __forceinline__ unsigned cvt_pk_bf16(float lo, float hi) { unsigned r; asm("v_cvt_pk_bf16_f32 %0, %1, %2" : "=v"(r) : "v"(lo), "v"(hi)); return r; }
; template <bool QK, bool SM>
; __device__ __forceinline__ void attn_step(const LAS unsigned char* kb, const LAS unsigned char* vbp, const bf16x8 (&qr)[6],
;                                           f32x16& s0, f32x16& s1, f32x16& o0, f32x16& o1, float& mrow, float& lsum) {
;     ...
;         for (int S = 0; S < 4; ++S) { u32x4 w;
;             if (S < 2) { w.x = cvt_pk_bf16(s0[8 * S + 0], s0[8 * S + 1]); w.y = cvt_pk_bf16(s0[8 * S + 2], s0[8 * S + 3]); w.z = cvt_pk_bf16(s0[8 * S + 4], s0[8 * S + 5]); w.w = cvt_pk_bf16(s0[8 * S + 6], s0[8 * S + 7]); }
;             else { w.x = cvt_pk_bf16(s1[8 * S - 16], s1[8 * S - 15]); w.y = cvt_pk_bf16(s1[8 * S - 14], s1[8 * S - 13]); w.z = cvt_pk_bf16(s1[8 * S - 12], s1[8 * S - 11]); w.w = cvt_pk_bf16(s1[8 * S - 10], s1[8 * S - 9]); }
;             pb[S] = __builtin_bit_cast(bf16x8, w); }
	v_cvt_pk_bf16_f32 v24, v102, v103


; __device__ __forceinline__ unsigned cvt_pk_bf16(float lo, float hi) { unsigned r; asm("v_cvt_pk_bf16_f32 %0, %1, %2" : "=v"(r) : "v"(lo), "v"(hi)); return r; }
; template <bool QK, bool SM>
; __device__ __forceinline__ void attn_step(const LAS unsigned char* kb, const LAS unsigned char* vbp, const bf16x8 (&qr)[6],
;                                           f32x16& s0, f32x16& s1, f32x16& o0, f32x16& o1, float& mrow, float& lsum) {
;     ...
;         for (int S = 0; S < 4; ++S) { u32x4 w;
;             if (S < 2) { w.x = cvt_pk_bf16(s0[8 * S + 0], s0[8 * S + 1]); w.y = cvt_pk_bf16(s0[8 * S + 2], s0[8 * S + 3]); w.z = cvt_pk_bf16(s0[8 * S + 4], s0[8 * S + 5]); w.w = cvt_pk_bf16(s0[8 * S + 6], s0[8 * S + 7]); }
;             else { w.x = cvt_pk_bf16(s1[8 * S - 16], s1[8 * S - 15]); w.y = cvt_pk_bf16(s1[8 * S - 14], s1[8 * S - 13]); w.z = cvt_pk_bf16(s1[8 * S - 12], s1[8 * S - 11]); w.w = cvt_pk_bf16(s1[8 * S - 10], s1[8 * S - 9]); }
;             pb[S] = __builtin_bit_cast(bf16x8, w); }
	v_cvt_pk_bf16_f32 v25, v30, v31

; #define LAS __attribute__((address_space(3)))
; __device__ __forceinline__ unsigned cvt_pk_bf16(float lo, float hi) { unsigned r; asm("v_cvt_pk_bf16_f32 %0, %1, %2" : "=v"(r) : "v"(lo), "v"(hi)); return r; }
; template <bool QK, bool SM>
; __device__ __forceinline__ void attn_step(const LAS unsigned char* kb, const LAS unsigned char* vbp, const bf16x8 (&qr)[6],
;                                           f32x16& s0, f32x16& s1, f32x16& o0, f32x16& o1, float& mrow, float& lsum) {
;     ...
;         for (int r = 0; r < 16; r += 2) { f32x2 a = (f32x2){s0[r], s0[r + 1]} - m2, b = (f32x2){s1[r], s1[r + 1]} - m2;
;             a.x = __builtin_amdgcn_exp2f(a.x); a.y = __builtin_amdgcn_exp2f(a.y); b.x = __builtin_amdgcn_exp2f(b.x); b.y = __builtin_amdgcn_exp2f(b.y);
;             s0[r] = a.x; s0[r + 1] = a.y; s1[r] = b.x; s1[r + 1] = b.y; ps2 += a + b; }
;         const float ps = ps2.x + ps2.y;
;         lsum = lsum * alpha + ps;
; #pragma unroll
;         for (int r = 0; r < 16; ++r) { o0[r] *= alpha; o1[r] *= alpha; }
;         bf16x8 pb[4];
; #pragma unroll
;         for (int S = 0; S < 4; ++S) { u32x4 w;
;             if (S < 2) { w.x = cvt_pk_bf16(s0[8 * S + 0], s0[8 * S + 1]); w.y = cvt_pk_bf16(s0[8 * S + 2], s0[8 * S + 3]); w.z = cvt_pk_bf16(s0[8 * S + 4], s0[8 * S + 5]); w.w = cvt_pk_bf16(s0[8 * S + 6], s0[8 * S + 7]); }
;             else { w.x = cvt_pk_bf16(s1[8 * S - 16], s1[8 * S - 15]); w.y = cvt_pk_bf16(s1[8 * S - 14], s1[8 * S - 13]); w.z = cvt_pk_bf16(s1[8 * S - 12], s1[8 * S - 11]); w.w = cvt_pk_bf16(s1[8 * S - 10], s1[8 * S - 9]); }
;             pb[S] = __builtin_bit_cast(bf16x8, w); }
; #pragma unroll
;         for (int S = 0; S < 4; ++S) {
;             const u32x2 a0 = *(const LAS u32x2*)(vbp + S * 32), a1 = *(const LAS u32x2*)(vbp + S * 32 + 16);
;             const u32x2 c0 = *(const LAS u32x2*)(vbp + 32 * VPITCH + S * 32), c1 = *(const LAS u32x2*)(vbp + 32 * VPITCH + S * 32 + 16);
;             const bf16x8 va = __builtin_bit_cast(bf16x8, (u32x4){a0.x, a0.y, a1.x, a1.y}), vc = __builtin_bit_cast(bf16x8, (u32x4){c0.x, c0.y, c1.x, c1.y});
;             o0 = __builtin_amdgcn_mfma_f32_32x32x16_bf16(va, pb[S], o0, 0, 0, 0); o1 = __builtin_amdgcn_mfma_f32_32x32x16_bf16(vc, pb[S], o1, 0, 0, 0); }
	s_waitcnt lgkmcnt(0)
	s_nop 0
	v_mfma_f32_32x32x16_bf16 v[32:47], v[6:9], v[22:25], v[32:47]
	v_add_f32_e32 v6, v12, v14
	v_add_f32_e32 v7, v13, v15
	v_add_f32_e32 v8, v16, v106
	v_add_f32_e32 v9, v17, v107
	v_add_f32_e32 v6, v6, v10
	v_add_f32_e32 v7, v7, v11
	v_add_f32_e32 v6, v8, v6
	v_add_f32_e32 v7, v9, v7
	v_add_f32_e32 v8, v18, v108
	v_add_f32_e32 v9, v19, v109
	v_mfma_f32_32x32x16_bf16 v[64:79], v[26:29], v[22:25], v[64:79]
	v_add_f32_e32 v6, v8, v6
	v_add_f32_e32 v7, v9, v7
	v_add_f32_e32 v8, v20, v100
	v_add_f32_e32 v9, v21, v101
	v_add_f32_e32 v6, v8, v6
	v_add_f32_e32 v7, v9, v7
	v_add_f32_e32 v8, v52, v102
	v_add_f32_e32 v9, v53, v103
	s_nop 0
	v_add_f32_e32 v6, v8, v6
	v_add_f32_e32 v7, v9, v7
	v_add_f32_e32 v8, v104, v30
	v_add_f32_e32 v9, v105, v31
	s_nop 0
	v_add_f32_e32 v6, v8, v6
	v_add_f32_e32 v7, v9, v7
	s_nop 0
	v_add_f32_e32 v216, v6, v7
	v_add_f32_e32 v216, v216, v215
	s_cmp_lg_u32 s99, 0
	s_cbranch_scc1 .Latt_slow2A
.Latt_cont2A:
	s_waitcnt vmcnt(5)
	ds_write_b128 v197, v[168:171]
	s_and_saveexec_b64 s[10:11], s[0:1]
	s_cbranch_execnz .LBB0_944
	s_branch .LBB0_945
.Latt_slowA:
	v_max_f32_e32 v10, v0, v206
	v_mov_b32_e32 v206, 0
	v_mov_b32_e32 v208, 0
	v_mov_b32_e32 v234, v10
	s_mov_b32 s99, 1
	v_sub_f32_e32 v16, v16, v10
	v_sub_f32_e32 v17, v17, v10
	v_sub_f32_e32 v18, v18, v10
	v_sub_f32_e32 v19, v19, v10
	v_sub_f32_e32 v20, v20, v10
	v_sub_f32_e32 v21, v21, v10
	v_sub_f32_e32 v22, v22, v10
	v_sub_f32_e32 v23, v23, v10
	v_sub_f32_e32 v24, v24, v10
	v_sub_f32_e32 v25, v25, v10
	v_sub_f32_e32 v26, v26, v10
	v_sub_f32_e32 v27, v27, v10
	v_sub_f32_e32 v28, v28, v10
	v_sub_f32_e32 v29, v29, v10
	v_sub_f32_e32 v30, v30, v10
	v_sub_f32_e32 v31, v31, v10
	v_sub_f32_e32 v48, v48, v10
	v_sub_f32_e32 v49, v49, v10
	v_sub_f32_e32 v50, v50, v10
	v_sub_f32_e32 v51, v51, v10
	v_sub_f32_e32 v52, v52, v10
	v_sub_f32_e32 v53, v53, v10
	v_sub_f32_e32 v54, v54, v10
	v_sub_f32_e32 v55, v55, v10
	v_sub_f32_e32 v56, v56, v10
	v_sub_f32_e32 v57, v57, v10
	v_sub_f32_e32 v58, v58, v10
	v_sub_f32_e32 v59, v59, v10
	v_sub_f32_e32 v60, v60, v10
	v_sub_f32_e32 v61, v61, v10
	v_sub_f32_e32 v62, v62, v10
	v_sub_f32_e32 v63, v63, v10
	v_sub_f32_e32 v11, 0, v10
	v_min_f32_e32 v11, 0x42fc0000, v11
	v_exp_f32_e32 v11, v11
	s_nop 0
	v_mul_f32_e32 v32, v32, v11
	v_mul_f32_e32 v33, v33, v11
	v_mul_f32_e32 v34, v34, v11
	v_mul_f32_e32 v35, v35, v11
	v_mul_f32_e32 v36, v36, v11
	v_mul_f32_e32 v37, v37, v11
	v_mul_f32_e32 v38, v38, v11
	v_mul_f32_e32 v39, v39, v11
	v_mul_f32_e32 v40, v40, v11
	v_mul_f32_e32 v41, v41, v11
	v_mul_f32_e32 v42, v42, v11
	v_mul_f32_e32 v43, v43, v11
	v_mul_f32_e32 v44, v44, v11
	v_mul_f32_e32 v45, v45, v11
	v_mul_f32_e32 v46, v46, v11
	v_mul_f32_e32 v47, v47, v11
	v_mul_f32_e32 v64, v64, v11
	v_mul_f32_e32 v65, v65, v11
	v_mul_f32_e32 v66, v66, v11
	v_mul_f32_e32 v67, v67, v11
	v_mul_f32_e32 v68, v68, v11
	v_mul_f32_e32 v69, v69, v11
	v_mul_f32_e32 v70, v70, v11
	v_mul_f32_e32 v71, v71, v11
	v_mul_f32_e32 v72, v72, v11
	v_mul_f32_e32 v73, v73, v11
	v_mul_f32_e32 v74, v74, v11
	v_mul_f32_e32 v75, v75, v11
	v_mul_f32_e32 v76, v76, v11
	v_mul_f32_e32 v77, v77, v11
	v_mul_f32_e32 v78, v78, v11
	v_mul_f32_e32 v79, v79, v11
	v_mul_f32_e32 v215, v215, v11
	s_nop 1
	s_branch .Latt_contA
.Latt_slow2A:
	s_nop 15
	s_mov_b32 s99, 0
	v_sub_f32_e32 v112, v112, v234
	v_sub_f32_e32 v113, v113, v234
	v_sub_f32_e32 v114, v114, v234
	v_sub_f32_e32 v115, v115, v234
	v_sub_f32_e32 v116, v116, v234
	v_sub_f32_e32 v117, v117, v234
	v_sub_f32_e32 v118, v118, v234
	v_sub_f32_e32 v119, v119, v234
	v_sub_f32_e32 v120, v120, v234
	v_sub_f32_e32 v121, v121, v234
	v_sub_f32_e32 v122, v122, v234
	v_sub_f32_e32 v123, v123, v234
	v_sub_f32_e32 v124, v124, v234
	v_sub_f32_e32 v125, v125, v234
	v_sub_f32_e32 v126, v126, v234
	v_sub_f32_e32 v127, v127, v234
	v_sub_f32_e32 v80, v80, v234
	v_sub_f32_e32 v81, v81, v234
	v_sub_f32_e32 v82, v82, v234
	v_sub_f32_e32 v83, v83, v234
	v_sub_f32_e32 v84, v84, v234
	v_sub_f32_e32 v85, v85, v234
	v_sub_f32_e32 v86, v86, v234
	v_sub_f32_e32 v87, v87, v234
	v_sub_f32_e32 v88, v88, v234
	v_sub_f32_e32 v89, v89, v234
	v_sub_f32_e32 v90, v90, v234
	v_sub_f32_e32 v91, v91, v234
	v_sub_f32_e32 v92, v92, v234
	v_sub_f32_e32 v93, v93, v234
	v_sub_f32_e32 v94, v94, v234
	v_sub_f32_e32 v95, v95, v234
	v_sub_f32_e32 v218, v218, v234
	v_sub_f32_e32 v219, v219, v234
	v_sub_f32_e32 v220, v220, v234
	v_sub_f32_e32 v221, v221, v234
	v_sub_f32_e32 v222, v222, v234
	v_sub_f32_e32 v223, v223, v234
	v_sub_f32_e32 v224, v224, v234
	v_sub_f32_e32 v225, v225, v234
	v_sub_f32_e32 v226, v226, v234
	v_sub_f32_e32 v227, v227, v234
	v_sub_f32_e32 v228, v228, v234
	v_sub_f32_e32 v229, v229, v234
	v_sub_f32_e32 v230, v230, v234
	v_sub_f32_e32 v231, v231, v234
	v_sub_f32_e32 v232, v232, v234
	v_sub_f32_e32 v233, v233, v234
	s_branch .Latt_cont2A
.LBB0_953:
	v_mov_b64_e32 v[16:17], v[80:81]
	v_mov_b64_e32 v[48:49], v[112:113]
	v_mov_b64_e32 v[18:19], v[82:83]
	v_mov_b64_e32 v[20:21], v[84:85]
	v_mov_b64_e32 v[22:23], v[86:87]
	v_mov_b64_e32 v[24:25], v[88:89]
	v_mov_b64_e32 v[26:27], v[90:91]
	v_mov_b64_e32 v[28:29], v[92:93]
	v_mov_b64_e32 v[30:31], v[94:95]
	v_mov_b64_e32 v[50:51], v[114:115]
	v_mov_b64_e32 v[52:53], v[116:117]
	v_mov_b64_e32 v[54:55], v[118:119]
	v_mov_b64_e32 v[56:57], v[120:121]
	v_mov_b64_e32 v[58:59], v[122:123]
	v_mov_b64_e32 v[60:61], v[124:125]
	v_mov_b64_e32 v[62:63], v[126:127]
	v_mov_b32_e32 v215, v216
	v_mov_b32_e32 v206, v208
	s_add_i32 s73, s73, 2
	s_cmp_ge_i32 s75, s74
	s_cbranch_scc0 .LBB0_941
	s_branch .LBB0_960
.LBB0_954:
	v_mov_b64_e32 v[16:17], v[80:81]
	v_mov_b64_e32 v[48:49], v[112:113]
	s_andn2_b64 vcc, exec, s[70:71]
	v_mov_b64_e32 v[18:19], v[82:83]
	v_mov_b64_e32 v[20:21], v[84:85]
	v_mov_b64_e32 v[22:23], v[86:87]
	v_mov_b64_e32 v[24:25], v[88:89]
	v_mov_b64_e32 v[26:27], v[90:91]
	v_mov_b64_e32 v[28:29], v[92:93]
	v_mov_b64_e32 v[30:31], v[94:95]
	v_mov_b64_e32 v[50:51], v[114:115]
	v_mov_b64_e32 v[52:53], v[116:117]
	v_mov_b64_e32 v[54:55], v[118:119]
	v_mov_b64_e32 v[56:57], v[120:121]
	v_mov_b64_e32 v[58:59], v[122:123]
	v_mov_b64_e32 v[60:61], v[124:125]
	v_mov_b64_e32 v[62:63], v[126:127]
	v_mov_b32_e32 v215, v216
	v_mov_b32_e32 v206, v208
	s_cbranch_vccnz .LBB0_956

; __device__ __forceinline__ float max3f(float a, float b, float c) { float r; asm("v_max3_f32 %0, %1, %2, %3" : "=v"(r) : "v"(a), "v"(b), "v"(c)); return r; }
; template <bool QK, bool SM>
; __device__ __forceinline__ void attn_step(const LAS unsigned char* kb, const LAS unsigned char* vbp, const bf16x8 (&qr)[6],
;                                           f32x16& s0, f32x16& s1, f32x16& o0, f32x16& o1, float& mrow, float& lsum) {
;     ...
;         float mx = max3f(s0[0], s1[0], s0[1]); mx = max3f(mx, s1[1], s0[2]); float my = max3f(s1[2], s0[3], s1[3]);
	v_max3_f32 v0, v112, v80, v113


; __device__ __forceinline__ float max3f(float a, float b, float c) { float r; asm("v_max3_f32 %0, %1, %2, %3" : "=v"(r) : "v"(a), "v"(b), "v"(c)); return r; }
; template <bool QK, bool SM>
; __device__ __forceinline__ void attn_step(const LAS unsigned char* kb, const LAS unsigned char* vbp, const bf16x8 (&qr)[6],
;                                           f32x16& s0, f32x16& s1, f32x16& o0, f32x16& o1, float& mrow, float& lsum) {
;     ...
;         float mx = max3f(s0[0], s1[0], s0[1]); mx = max3f(mx, s1[1], s0[2]); float my = max3f(s1[2], s0[3], s1[3]);
	v_max3_f32 v2, v82, v115, v83

; __device__ __forceinline__ float max3f(float a, float b, float c) { float r; asm("v_max3_f32 %0, %1, %2, %3" : "=v"(r) : "v"(a), "v"(b), "v"(c)); return r; }
; template <bool QK, bool SM>
; __device__ __forceinline__ void attn_step(const LAS unsigned char* kb, const LAS unsigned char* vbp, const bf16x8 (&qr)[6],
;                                           f32x16& s0, f32x16& s1, f32x16& o0, f32x16& o1, float& mrow, float& lsum) {
;     ...
;         float mx = max3f(s0[0], s1[0], s0[1]); mx = max3f(mx, s1[1], s0[2]); float my = max3f(s1[2], s0[3], s1[3]);
; #pragma unroll
;         for (int r = 4; r < 16; r += 4) { mx = max3f(mx, s0[r], s1[r]); my = max3f(my, s0[r + 1], s1[r + 1]); mx = max3f(mx, s0[r + 2], s1[r + 2]); my = max3f(my, s0[r + 3], s1[r + 3]); }
;         mx = fmaxf(mx, my);
	s_nop 0

; __device__ __forceinline__ float max3f(float a, float b, float c) { float r; asm("v_max3_f32 %0, %1, %2, %3" : "=v"(r) : "v"(a), "v"(b), "v"(c)); return r; }
; template <bool QK, bool SM>
; __device__ __forceinline__ void attn_step(const LAS unsigned char* kb, const LAS unsigned char* vbp, const bf16x8 (&qr)[6],
;                                           f32x16& s0, f32x16& s1, f32x16& o0, f32x16& o1, float& mrow, float& lsum) {
;     ...
;         float mx = max3f(s0[0], s1[0], s0[1]); mx = max3f(mx, s1[1], s0[2]); float my = max3f(s1[2], s0[3], s1[3]);
; #pragma unroll
;         for (int r = 4; r < 16; r += 4) { mx = max3f(mx, s0[r], s1[r]); my = max3f(my, s0[r + 1], s1[r + 1]); mx = max3f(mx, s0[r + 2], s1[r + 2]); my = max3f(my, s0[r + 3], s1[r + 3]); }
;         mx = fmaxf(mx, my);
	v_max3_f32 v0, v0, v81, v114


; __device__ __forceinline__ float max3f(float a, float b, float c) { float r; asm("v_max3_f32 %0, %1, %2, %3" : "=v"(r) : "v"(a), "v"(b), "v"(c)); return r; }
; template <bool QK, bool SM>
; __device__ __forceinline__ void attn_step(const LAS unsigned char* kb, const LAS unsigned char* vbp, const bf16x8 (&qr)[6],
;                                           f32x16& s0, f32x16& s1, f32x16& o0, f32x16& o1, float& mrow, float& lsum) {
;     ...
;         float mx = max3f(s0[0], s1[0], s0[1]); mx = max3f(mx, s1[1], s0[2]); float my = max3f(s1[2], s0[3], s1[3]);
; #pragma unroll
;         for (int r = 4; r < 16; r += 4) { mx = max3f(mx, s0[r], s1[r]); my = max3f(my, s0[r + 1], s1[r + 1]); mx = max3f(mx, s0[r + 2], s1[r + 2]); my = max3f(my, s0[r + 3], s1[r + 3]); }
;         mx = fmaxf(mx, my);
	v_max3_f32 v2, v2, v117, v85

; __device__ __forceinline__ float max3f(float a, float b, float c) { float r; asm("v_max3_f32 %0, %1, %2, %3" : "=v"(r) : "v"(a), "v"(b), "v"(c)); return r; }
; template <bool QK, bool SM>
; __device__ __forceinline__ void attn_step(const LAS unsigned char* kb, const LAS unsigned char* vbp, const bf16x8 (&qr)[6],
;                                           f32x16& s0, f32x16& s1, f32x16& o0, f32x16& o1, float& mrow, float& lsum) {
;     ...
;         float mx = max3f(s0[0], s1[0], s0[1]); mx = max3f(mx, s1[1], s0[2]); float my = max3f(s1[2], s0[3], s1[3]);
; #pragma unroll
;         for (int r = 4; r < 16; r += 4) { mx = max3f(mx, s0[r], s1[r]); my = max3f(my, s0[r + 1], s1[r + 1]); mx = max3f(mx, s0[r + 2], s1[r + 2]); my = max3f(my, s0[r + 3], s1[r + 3]); }
;         mx = fmaxf(mx, my);
	s_nop 0

; __device__ __forceinline__ float max3f(float a, float b, float c) { float r; asm("v_max3_f32 %0, %1, %2, %3" : "=v"(r) : "v"(a), "v"(b), "v"(c)); return r; }
; template <bool QK, bool SM>
; __device__ __forceinline__ void attn_step(const LAS unsigned char* kb, const LAS unsigned char* vbp, const bf16x8 (&qr)[6],
;                                           f32x16& s0, f32x16& s1, f32x16& o0, f32x16& o1, float& mrow, float& lsum) {
;     ...
;         float mx = max3f(s0[0], s1[0], s0[1]); mx = max3f(mx, s1[1], s0[2]); float my = max3f(s1[2], s0[3], s1[3]);
; #pragma unroll
;         for (int r = 4; r < 16; r += 4) { mx = max3f(mx, s0[r], s1[r]); my = max3f(my, s0[r + 1], s1[r + 1]); mx = max3f(mx, s0[r + 2], s1[r + 2]); my = max3f(my, s0[r + 3], s1[r + 3]); }
;         mx = fmaxf(mx, my);
	v_max3_f32 v0, v0, v116, v84


; __device__ __forceinline__ float max3f(float a, float b, float c) { float r; asm("v_max3_f32 %0, %1, %2, %3" : "=v"(r) : "v"(a), "v"(b), "v"(c)); return r; }
; template <bool QK, bool SM>
; __device__ __forceinline__ void attn_step(const LAS unsigned char* kb, const LAS unsigned char* vbp, const bf16x8 (&qr)[6],
;                                           f32x16& s0, f32x16& s1, f32x16& o0, f32x16& o1, float& mrow, float& lsum) {
;     ...
;         float mx = max3f(s0[0], s1[0], s0[1]); mx = max3f(mx, s1[1], s0[2]); float my = max3f(s1[2], s0[3], s1[3]);
; #pragma unroll
;         for (int r = 4; r < 16; r += 4) { mx = max3f(mx, s0[r], s1[r]); my = max3f(my, s0[r + 1], s1[r + 1]); mx = max3f(mx, s0[r + 2], s1[r + 2]); my = max3f(my, s0[r + 3], s1[r + 3]); }
;         mx = fmaxf(mx, my);
	v_max3_f32 v2, v2, v119, v87

; __device__ __forceinline__ float max3f(float a, float b, float c) { float r; asm("v_max3_f32 %0, %1, %2, %3" : "=v"(r) : "v"(a), "v"(b), "v"(c)); return r; }
; template <bool QK, bool SM>
; __device__ __forceinline__ void attn_step(const LAS unsigned char* kb, const LAS unsigned char* vbp, const bf16x8 (&qr)[6],
;                                           f32x16& s0, f32x16& s1, f32x16& o0, f32x16& o1, float& mrow, float& lsum) {
;     ...
;         float mx = max3f(s0[0], s1[0], s0[1]); mx = max3f(mx, s1[1], s0[2]); float my = max3f(s1[2], s0[3], s1[3]);
; #pragma unroll
;         for (int r = 4; r < 16; r += 4) { mx = max3f(mx, s0[r], s1[r]); my = max3f(my, s0[r + 1], s1[r + 1]); mx = max3f(mx, s0[r + 2], s1[r + 2]); my = max3f(my, s0[r + 3], s1[r + 3]); }
;         mx = fmaxf(mx, my);
	s_nop 0

; __device__ __forceinline__ float max3f(float a, float b, float c) { float r; asm("v_max3_f32 %0, %1, %2, %3" : "=v"(r) : "v"(a), "v"(b), "v"(c)); return r; }
; template <bool QK, bool SM>
; __device__ __forceinline__ void attn_step(const LAS unsigned char* kb, const LAS unsigned char* vbp, const bf16x8 (&qr)[6],
;                                           f32x16& s0, f32x16& s1, f32x16& o0, f32x16& o1, float& mrow, float& lsum) {
;     ...
;         float mx = max3f(s0[0], s1[0], s0[1]); mx = max3f(mx, s1[1], s0[2]); float my = max3f(s1[2], s0[3], s1[3]);
; #pragma unroll
;         for (int r = 4; r < 16; r += 4) { mx = max3f(mx, s0[r], s1[r]); my = max3f(my, s0[r + 1], s1[r + 1]); mx = max3f(mx, s0[r + 2], s1[r + 2]); my = max3f(my, s0[r + 3], s1[r + 3]); }
;         mx = fmaxf(mx, my);
	v_max3_f32 v0, v0, v118, v86


; __device__ __forceinline__ float max3f(float a, float b, float c) { float r; asm("v_max3_f32 %0, %1, %2, %3" : "=v"(r) : "v"(a), "v"(b), "v"(c)); return r; }
; template <bool QK, bool SM>
; __device__ __forceinline__ void attn_step(const LAS unsigned char* kb, const LAS unsigned char* vbp, const bf16x8 (&qr)[6],
;                                           f32x16& s0, f32x16& s1, f32x16& o0, f32x16& o1, float& mrow, float& lsum) {
;     ...
;         float mx = max3f(s0[0], s1[0], s0[1]); mx = max3f(mx, s1[1], s0[2]); float my = max3f(s1[2], s0[3], s1[3]);
; #pragma unroll
;         for (int r = 4; r < 16; r += 4) { mx = max3f(mx, s0[r], s1[r]); my = max3f(my, s0[r + 1], s1[r + 1]); mx = max3f(mx, s0[r + 2], s1[r + 2]); my = max3f(my, s0[r + 3], s1[r + 3]); }
;         mx = fmaxf(mx, my);
	v_max3_f32 v2, v2, v121, v89

; __device__ __forceinline__ float max3f(float a, float b, float c) { float r; asm("v_max3_f32 %0, %1, %2, %3" : "=v"(r) : "v"(a), "v"(b), "v"(c)); return r; }
; template <bool QK, bool SM>
; __device__ __forceinline__ void attn_step(const LAS unsigned char* kb, const LAS unsigned char* vbp, const bf16x8 (&qr)[6],
;                                           f32x16& s0, f32x16& s1, f32x16& o0, f32x16& o1, float& mrow, float& lsum) {
;     ...
;         float mx = max3f(s0[0], s1[0], s0[1]); mx = max3f(mx, s1[1], s0[2]); float my = max3f(s1[2], s0[3], s1[3]);
; #pragma unroll
;         for (int r = 4; r < 16; r += 4) { mx = max3f(mx, s0[r], s1[r]); my = max3f(my, s0[r + 1], s1[r + 1]); mx = max3f(mx, s0[r + 2], s1[r + 2]); my = max3f(my, s0[r + 3], s1[r + 3]); }
;         mx = fmaxf(mx, my);
	s_nop 0

; __device__ __forceinline__ float max3f(float a, float b, float c) { float r; asm("v_max3_f32 %0, %1, %2, %3" : "=v"(r) : "v"(a), "v"(b), "v"(c)); return r; }
; template <bool QK, bool SM>
; __device__ __forceinline__ void attn_step(const LAS unsigned char* kb, const LAS unsigned char* vbp, const bf16x8 (&qr)[6],
;                                           f32x16& s0, f32x16& s1, f32x16& o0, f32x16& o1, float& mrow, float& lsum) {
;     ...
;         float mx = max3f(s0[0], s1[0], s0[1]); mx = max3f(mx, s1[1], s0[2]); float my = max3f(s1[2], s0[3], s1[3]);
; #pragma unroll
;         for (int r = 4; r < 16; r += 4) { mx = max3f(mx, s0[r], s1[r]); my = max3f(my, s0[r + 1], s1[r + 1]); mx = max3f(mx, s0[r + 2], s1[r + 2]); my = max3f(my, s0[r + 3], s1[r + 3]); }
;         mx = fmaxf(mx, my);
	v_max3_f32 v0, v0, v120, v88


; __device__ __forceinline__ float max3f(float a, float b, float c) { float r; asm("v_max3_f32 %0, %1, %2, %3" : "=v"(r) : "v"(a), "v"(b), "v"(c)); return r; }
; template <bool QK, bool SM>
; __device__ __forceinline__ void attn_step(const LAS unsigned char* kb, const LAS unsigned char* vbp, const bf16x8 (&qr)[6],
;                                           f32x16& s0, f32x16& s1, f32x16& o0, f32x16& o1, float& mrow, float& lsum) {
;     ...
;         float mx = max3f(s0[0], s1[0], s0[1]); mx = max3f(mx, s1[1], s0[2]); float my = max3f(s1[2], s0[3], s1[3]);
; #pragma unroll
;         for (int r = 4; r < 16; r += 4) { mx = max3f(mx, s0[r], s1[r]); my = max3f(my, s0[r + 1], s1[r + 1]); mx = max3f(mx, s0[r + 2], s1[r + 2]); my = max3f(my, s0[r + 3], s1[r + 3]); }
;         mx = fmaxf(mx, my);
	v_max3_f32 v2, v2, v123, v91

; __device__ __forceinline__ float max3f(float a, float b, float c) { float r; asm("v_max3_f32 %0, %1, %2, %3" : "=v"(r) : "v"(a), "v"(b), "v"(c)); return r; }
; template <bool QK, bool SM>
; __device__ __forceinline__ void attn_step(const LAS unsigned char* kb, const LAS unsigned char* vbp, const bf16x8 (&qr)[6],
;                                           f32x16& s0, f32x16& s1, f32x16& o0, f32x16& o1, float& mrow, float& lsum) {
;     ...
;         float mx = max3f(s0[0], s1[0], s0[1]); mx = max3f(mx, s1[1], s0[2]); float my = max3f(s1[2], s0[3], s1[3]);
; #pragma unroll
;         for (int r = 4; r < 16; r += 4) { mx = max3f(mx, s0[r], s1[r]); my = max3f(my, s0[r + 1], s1[r + 1]); mx = max3f(mx, s0[r + 2], s1[r + 2]); my = max3f(my, s0[r + 3], s1[r + 3]); }
;         mx = fmaxf(mx, my);
	s_nop 0

; __device__ __forceinline__ float max3f(float a, float b, float c) { float r; asm("v_max3_f32 %0, %1, %2, %3" : "=v"(r) : "v"(a), "v"(b), "v"(c)); return r; }
; template <bool QK, bool SM>
; __device__ __forceinline__ void attn_step(const LAS unsigned char* kb, const LAS unsigned char* vbp, const bf16x8 (&qr)[6],
;                                           f32x16& s0, f32x16& s1, f32x16& o0, f32x16& o1, float& mrow, float& lsum) {
;     ...
;         float mx = max3f(s0[0], s1[0], s0[1]); mx = max3f(mx, s1[1], s0[2]); float my = max3f(s1[2], s0[3], s1[3]);
; #pragma unroll
;         for (int r = 4; r < 16; r += 4) { mx = max3f(mx, s0[r], s1[r]); my = max3f(my, s0[r + 1], s1[r + 1]); mx = max3f(mx, s0[r + 2], s1[r + 2]); my = max3f(my, s0[r + 3], s1[r + 3]); }
;         mx = fmaxf(mx, my);
	v_max3_f32 v0, v0, v122, v90


; __device__ __forceinline__ float max3f(float a, float b, float c) { float r; asm("v_max3_f32 %0, %1, %2, %3" : "=v"(r) : "v"(a), "v"(b), "v"(c)); return r; }
; template <bool QK, bool SM>
; __device__ __forceinline__ void attn_step(const LAS unsigned char* kb, const LAS unsigned char* vbp, const bf16x8 (&qr)[6],
;                                           f32x16& s0, f32x16& s1, f32x16& o0, f32x16& o1, float& mrow, float& lsum) {
;     ...
;         float mx = max3f(s0[0], s1[0], s0[1]); mx = max3f(mx, s1[1], s0[2]); float my = max3f(s1[2], s0[3], s1[3]);
; #pragma unroll
;         for (int r = 4; r < 16; r += 4) { mx = max3f(mx, s0[r], s1[r]); my = max3f(my, s0[r + 1], s1[r + 1]); mx = max3f(mx, s0[r + 2], s1[r + 2]); my = max3f(my, s0[r + 3], s1[r + 3]); }
;         mx = fmaxf(mx, my);
	v_max3_f32 v2, v2, v125, v93

; __device__ __forceinline__ float max3f(float a, float b, float c) { float r; asm("v_max3_f32 %0, %1, %2, %3" : "=v"(r) : "v"(a), "v"(b), "v"(c)); return r; }
; template <bool QK, bool SM>
; __device__ __forceinline__ void attn_step(const LAS unsigned char* kb, const LAS unsigned char* vbp, const bf16x8 (&qr)[6],
;                                           f32x16& s0, f32x16& s1, f32x16& o0, f32x16& o1, float& mrow, float& lsum) {
;     ...
;         float mx = max3f(s0[0], s1[0], s0[1]); mx = max3f(mx, s1[1], s0[2]); float my = max3f(s1[2], s0[3], s1[3]);
; #pragma unroll
;         for (int r = 4; r < 16; r += 4) { mx = max3f(mx, s0[r], s1[r]); my = max3f(my, s0[r + 1], s1[r + 1]); mx = max3f(mx, s0[r + 2], s1[r + 2]); my = max3f(my, s0[r + 3], s1[r + 3]); }
;         mx = fmaxf(mx, my);
	s_nop 0

; __device__ __forceinline__ float max3f(float a, float b, float c) { float r; asm("v_max3_f32 %0, %1, %2, %3" : "=v"(r) : "v"(a), "v"(b), "v"(c)); return r; }
; template <bool QK, bool SM>
; __device__ __forceinline__ void attn_step(const LAS unsigned char* kb, const LAS unsigned char* vbp, const bf16x8 (&qr)[6],
;                                           f32x16& s0, f32x16& s1, f32x16& o0, f32x16& o1, float& mrow, float& lsum) {
;     ...
;         float mx = max3f(s0[0], s1[0], s0[1]); mx = max3f(mx, s1[1], s0[2]); float my = max3f(s1[2], s0[3], s1[3]);
; #pragma unroll
;         for (int r = 4; r < 16; r += 4) { mx = max3f(mx, s0[r], s1[r]); my = max3f(my, s0[r + 1], s1[r + 1]); mx = max3f(mx, s0[r + 2], s1[r + 2]); my = max3f(my, s0[r + 3], s1[r + 3]); }
;         mx = fmaxf(mx, my);
	v_max3_f32 v0, v0, v124, v92


; __device__ __forceinline__ float max3f(float a, float b, float c) { float r; asm("v_max3_f32 %0, %1, %2, %3" : "=v"(r) : "v"(a), "v"(b), "v"(c)); return r; }
; template <bool QK, bool SM>
; __device__ __forceinline__ void attn_step(const LAS unsigned char* kb, const LAS unsigned char* vbp, const bf16x8 (&qr)[6],
;                                           f32x16& s0, f32x16& s1, f32x16& o0, f32x16& o1, float& mrow, float& lsum) {
;     ...
;         float mx = max3f(s0[0], s1[0], s0[1]); mx = max3f(mx, s1[1], s0[2]); float my = max3f(s1[2], s0[3], s1[3]);
; #pragma unroll
;         for (int r = 4; r < 16; r += 4) { mx = max3f(mx, s0[r], s1[r]); my = max3f(my, s0[r + 1], s1[r + 1]); mx = max3f(mx, s0[r + 2], s1[r + 2]); my = max3f(my, s0[r + 3], s1[r + 3]); }
;         mx = fmaxf(mx, my);
	v_max3_f32 v2, v2, v127, v95

; __device__ __forceinline__ float max3f(float a, float b, float c) { float r; asm("v_max3_f32 %0, %1, %2, %3" : "=v"(r) : "v"(a), "v"(b), "v"(c)); return r; }
; template <bool QK, bool SM>
; __device__ __forceinline__ void attn_step(const LAS unsigned char* kb, const LAS unsigned char* vbp, const bf16x8 (&qr)[6],
;                                           f32x16& s0, f32x16& s1, f32x16& o0, f32x16& o1, float& mrow, float& lsum) {
;     ...
;         float mx = max3f(s0[0], s1[0], s0[1]); mx = max3f(mx, s1[1], s0[2]); float my = max3f(s1[2], s0[3], s1[3]);
; #pragma unroll
;         for (int r = 4; r < 16; r += 4) { mx = max3f(mx, s0[r], s1[r]); my = max3f(my, s0[r + 1], s1[r + 1]); mx = max3f(mx, s0[r + 2], s1[r + 2]); my = max3f(my, s0[r + 3], s1[r + 3]); }
;         mx = fmaxf(mx, my);
	s_nop 0

; __device__ __forceinline__ float max3f(float a, float b, float c) { float r; asm("v_max3_f32 %0, %1, %2, %3" : "=v"(r) : "v"(a), "v"(b), "v"(c)); return r; }
; template <bool QK, bool SM>
; __device__ __forceinline__ void attn_step(const LAS unsigned char* kb, const LAS unsigned char* vbp, const bf16x8 (&qr)[6],
;                                           f32x16& s0, f32x16& s1, f32x16& o0, f32x16& o1, float& mrow, float& lsum) {
;     ...
;         float mx = max3f(s0[0], s1[0], s0[1]); mx = max3f(mx, s1[1], s0[2]); float my = max3f(s1[2], s0[3], s1[3]);
; #pragma unroll
;         for (int r = 4; r < 16; r += 4) { mx = max3f(mx, s0[r], s1[r]); my = max3f(my, s0[r + 1], s1[r + 1]); mx = max3f(mx, s0[r + 2], s1[r + 2]); my = max3f(my, s0[r + 3], s1[r + 3]); }
;         mx = fmaxf(mx, my);
	v_max3_f32 v0, v0, v126, v94

; template <bool QK, bool SM>
; __device__ __forceinline__ void attn_step(const LAS unsigned char* kb, const LAS unsigned char* vbp, const bf16x8 (&qr)[6],
;                                           f32x16& s0, f32x16& s1, f32x16& o0, f32x16& o1, float& mrow, float& lsum) {
;     ...
;         { const auto rr = __builtin_amdgcn_permlane32_swap(__float_as_uint(mx), __float_as_uint(mx), false, false); mx = fmaxf(__uint_as_float(rr[0]), __uint_as_float(rr[1])); }
;         const float mnew = fmaxf(mrow, mx), alpha = __builtin_amdgcn_exp2f(mrow - mnew); mrow = mnew;
;         const f32x2 m2 = (f32x2){mnew, mnew}; f32x2 ps2 = (f32x2){0.f, 0.f};
; #pragma unroll
;         for (int r = 0; r < 16; r += 2) { f32x2 a = (f32x2){s0[r], s0[r + 1]} - m2, b = (f32x2){s1[r], s1[r + 1]} - m2;
;             a.x = __builtin_amdgcn_exp2f(a.x); a.y = __builtin_amdgcn_exp2f(a.y); b.x = __builtin_amdgcn_exp2f(b.x); b.y = __builtin_amdgcn_exp2f(b.y);
;             s0[r] = a.x; s0[r + 1] = a.y; s1[r] = b.x; s1[r + 1] = b.y; ps2 += a + b; }
	v_max_f32_e32 v2, v2, v2
	v_max_f32_e32 v0, v0, v0
	v_max_f32_e32 v0, v0, v2
	v_mov_b32_e32 v2, v0
	s_nop 1
	v_permlane32_swap_b32_e32 v0, v2
	v_max3_f32 v206, v208, v0, v2
	v_sub_f32_e32 v2, v112, v206
	v_sub_f32_e32 v3, v113, v206
	v_sub_f32_e32 v4, v80, v206
	v_sub_f32_e32 v5, v81, v206
	v_exp_f32_e32 v14, v2
	v_exp_f32_e32 v15, v3
	v_exp_f32_e32 v2, v4
	v_exp_f32_e32 v3, v5
	v_sub_f32_e32 v4, v114, v206
	v_sub_f32_e32 v5, v115, v206
	v_sub_f32_e32 v6, v82, v206
	v_sub_f32_e32 v7, v83, v206
	v_exp_f32_e32 v16, v4
	v_exp_f32_e32 v17, v5
	v_exp_f32_e32 v4, v6
	v_exp_f32_e32 v5, v7
	v_add_f32_e32 v8, v14, v2
	v_add_f32_e32 v9, v15, v3
	v_sub_f32_e32 v6, v116, v206
	v_sub_f32_e32 v7, v117, v206
	v_sub_f32_e32 v10, v84, v206
	v_sub_f32_e32 v11, v85, v206
	v_exp_f32_e32 v18, v6
	v_exp_f32_e32 v19, v7
	v_exp_f32_e32 v6, v10
	v_exp_f32_e32 v7, v11
	v_add_f32_e32 v8, 0, v8
	v_add_f32_e32 v9, 0, v9
	v_add_f32_e32 v10, v16, v4
	v_add_f32_e32 v11, v17, v5
	v_sub_f32_e32 v30, v88, v206
	v_sub_f32_e32 v31, v89, v206
	v_add_f32_e32 v22, v10, v8
	v_add_f32_e32 v23, v11, v9
	v_sub_f32_e32 v8, v118, v206
	v_sub_f32_e32 v9, v119, v206
	v_sub_f32_e32 v10, v86, v206
	v_sub_f32_e32 v11, v87, v206
	v_exp_f32_e32 v26, v8
	v_exp_f32_e32 v27, v9
	v_sub_f32_e32 v8, v120, v206
	v_sub_f32_e32 v9, v121, v206
	v_exp_f32_e32 v28, v10
	v_exp_f32_e32 v29, v11
	v_exp_f32_e32 v49, v9
	v_sub_f32_e32 v10, v122, v206
	v_sub_f32_e32 v11, v123, v206
	v_add_u32_e32 v9, v214, v204
	v_exp_f32_e32 v48, v8
	v_exp_f32_e32 v8, v30
	v_exp_f32_e32 v50, v10
	v_exp_f32_e32 v51, v11
	v_sub_f32_e32 v10, v124, v206
	v_sub_f32_e32 v11, v125, v206
	v_add_u32_e32 v30, 0x8800, v9
	v_exp_f32_e32 v52, v10
	v_exp_f32_e32 v53, v11
	ds_read2_b64 v[10:13], v30 offset0:64 offset1:66
	v_add_u32_e32 v56, 0x9800, v9
	v_add_f32_e32 v24, v18, v6
	v_add_f32_e32 v25, v19, v7

; __device__ __forceinline__ unsigned cvt_pk_bf16(float lo, float hi) { unsigned r; asm("v_cvt_pk_bf16_f32 %0, %1, %2" : "=v"(r) : "v"(lo), "v"(hi)); return r; }
; template <bool QK, bool SM>
; __device__ __forceinline__ void attn_step(const LAS unsigned char* kb, const LAS unsigned char* vbp, const bf16x8 (&qr)[6],
;                                           f32x16& s0, f32x16& s1, f32x16& o0, f32x16& o1, float& mrow, float& lsum) {
;     ...
;         for (int S = 0; S < 4; ++S) { u32x4 w;
;             if (S < 2) { w.x = cvt_pk_bf16(s0[8 * S + 0], s0[8 * S + 1]); w.y = cvt_pk_bf16(s0[8 * S + 2], s0[8 * S + 3]); w.z = cvt_pk_bf16(s0[8 * S + 4], s0[8 * S + 5]); w.w = cvt_pk_bf16(s0[8 * S + 6], s0[8 * S + 7]); }
;             else { w.x = cvt_pk_bf16(s1[8 * S - 16], s1[8 * S - 15]); w.y = cvt_pk_bf16(s1[8 * S - 14], s1[8 * S - 13]); w.z = cvt_pk_bf16(s1[8 * S - 12], s1[8 * S - 11]); w.w = cvt_pk_bf16(s1[8 * S - 10], s1[8 * S - 9]); }
;             pb[S] = __builtin_bit_cast(bf16x8, w); }
	v_cvt_pk_bf16_f32 v14, v14, v15


; __device__ __forceinline__ unsigned cvt_pk_bf16(float lo, float hi) { unsigned r; asm("v_cvt_pk_bf16_f32 %0, %1, %2" : "=v"(r) : "v"(lo), "v"(hi)); return r; }
; template <bool QK, bool SM>
; __device__ __forceinline__ void attn_step(const LAS unsigned char* kb, const LAS unsigned char* vbp, const bf16x8 (&qr)[6],
;                                           f32x16& s0, f32x16& s1, f32x16& o0, f32x16& o1, float& mrow, float& lsum) {
;     ...
;         for (int S = 0; S < 4; ++S) { u32x4 w;
;             if (S < 2) { w.x = cvt_pk_bf16(s0[8 * S + 0], s0[8 * S + 1]); w.y = cvt_pk_bf16(s0[8 * S + 2], s0[8 * S + 3]); w.z = cvt_pk_bf16(s0[8 * S + 4], s0[8 * S + 5]); w.w = cvt_pk_bf16(s0[8 * S + 6], s0[8 * S + 7]); }
;             else { w.x = cvt_pk_bf16(s1[8 * S - 16], s1[8 * S - 15]); w.y = cvt_pk_bf16(s1[8 * S - 14], s1[8 * S - 13]); w.z = cvt_pk_bf16(s1[8 * S - 12], s1[8 * S - 11]); w.w = cvt_pk_bf16(s1[8 * S - 10], s1[8 * S - 9]); }
;             pb[S] = __builtin_bit_cast(bf16x8, w); }
	v_cvt_pk_bf16_f32 v15, v16, v17


; __device__ __forceinline__ unsigned cvt_pk_bf16(float lo, float hi) { unsigned r; asm("v_cvt_pk_bf16_f32 %0, %1, %2" : "=v"(r) : "v"(lo), "v"(hi)); return r; }
; template <bool QK, bool SM>
; __device__ __forceinline__ void attn_step(const LAS unsigned char* kb, const LAS unsigned char* vbp, const bf16x8 (&qr)[6],
;                                           f32x16& s0, f32x16& s1, f32x16& o0, f32x16& o1, float& mrow, float& lsum) {
;     ...
;         for (int S = 0; S < 4; ++S) { u32x4 w;
;             if (S < 2) { w.x = cvt_pk_bf16(s0[8 * S + 0], s0[8 * S + 1]); w.y = cvt_pk_bf16(s0[8 * S + 2], s0[8 * S + 3]); w.z = cvt_pk_bf16(s0[8 * S + 4], s0[8 * S + 5]); w.w = cvt_pk_bf16(s0[8 * S + 6], s0[8 * S + 7]); }
;             else { w.x = cvt_pk_bf16(s1[8 * S - 16], s1[8 * S - 15]); w.y = cvt_pk_bf16(s1[8 * S - 14], s1[8 * S - 13]); w.z = cvt_pk_bf16(s1[8 * S - 12], s1[8 * S - 11]); w.w = cvt_pk_bf16(s1[8 * S - 10], s1[8 * S - 9]); }
;             pb[S] = __builtin_bit_cast(bf16x8, w); }
	v_cvt_pk_bf16_f32 v16, v18, v19

; #define LAS __attribute__((address_space(3)))
; __device__ __forceinline__ unsigned cvt_pk_bf16(float lo, float hi) { unsigned r; asm("v_cvt_pk_bf16_f32 %0, %1, %2" : "=v"(r) : "v"(lo), "v"(hi)); return r; }
; template <bool QK, bool SM>
; __device__ __forceinline__ void attn_step(const LAS unsigned char* kb, const LAS unsigned char* vbp, const bf16x8 (&qr)[6],
;                                           f32x16& s0, f32x16& s1, f32x16& o0, f32x16& o1, float& mrow, float& lsum) {
;     ...
;         const float mnew = fmaxf(mrow, mx), alpha = __builtin_amdgcn_exp2f(mrow - mnew); mrow = mnew;
;         const f32x2 m2 = (f32x2){mnew, mnew}; f32x2 ps2 = (f32x2){0.f, 0.f};
; #pragma unroll
;         for (int r = 0; r < 16; r += 2) { f32x2 a = (f32x2){s0[r], s0[r + 1]} - m2, b = (f32x2){s1[r], s1[r + 1]} - m2;
;             a.x = __builtin_amdgcn_exp2f(a.x); a.y = __builtin_amdgcn_exp2f(a.y); b.x = __builtin_amdgcn_exp2f(b.x); b.y = __builtin_amdgcn_exp2f(b.y);
;             s0[r] = a.x; s0[r + 1] = a.y; s1[r] = b.x; s1[r + 1] = b.y; ps2 += a + b; }
;         const float ps = ps2.x + ps2.y;
;         lsum = lsum * alpha + ps;
; #pragma unroll
;         for (int r = 0; r < 16; ++r) { o0[r] *= alpha; o1[r] *= alpha; }
;         bf16x8 pb[4];
; #pragma unroll
;         for (int S = 0; S < 4; ++S) { u32x4 w;
;             if (S < 2) { w.x = cvt_pk_bf16(s0[8 * S + 0], s0[8 * S + 1]); w.y = cvt_pk_bf16(s0[8 * S + 2], s0[8 * S + 3]); w.z = cvt_pk_bf16(s0[8 * S + 4], s0[8 * S + 5]); w.w = cvt_pk_bf16(s0[8 * S + 6], s0[8 * S + 7]); }
;             else { w.x = cvt_pk_bf16(s1[8 * S - 16], s1[8 * S - 15]); w.y = cvt_pk_bf16(s1[8 * S - 14], s1[8 * S - 13]); w.z = cvt_pk_bf16(s1[8 * S - 12], s1[8 * S - 11]); w.w = cvt_pk_bf16(s1[8 * S - 10], s1[8 * S - 9]); }
;             pb[S] = __builtin_bit_cast(bf16x8, w); }
; #pragma unroll
;         for (int S = 0; S < 4; ++S) {
;             const u32x2 a0 = *(const LAS u32x2*)(vbp + S * 32), a1 = *(const LAS u32x2*)(vbp + S * 32 + 16);
;             const u32x2 c0 = *(const LAS u32x2*)(vbp + 32 * VPITCH + S * 32), c1 = *(const LAS u32x2*)(vbp + 32 * VPITCH + S * 32 + 16);
	ds_read2_b64 v[18:21], v56 offset0:96 offset1:98
	v_sub_f32_e32 v0, v208, v206
	v_exp_f32_e32 v0, v0

; __device__ __forceinline__ unsigned cvt_pk_bf16(float lo, float hi) { unsigned r; asm("v_cvt_pk_bf16_f32 %0, %1, %2" : "=v"(r) : "v"(lo), "v"(hi)); return r; }
; template <bool QK, bool SM>
; __device__ __forceinline__ void attn_step(const LAS unsigned char* kb, const LAS unsigned char* vbp, const bf16x8 (&qr)[6],
;                                           f32x16& s0, f32x16& s1, f32x16& o0, f32x16& o1, float& mrow, float& lsum) {
;     ...
;         for (int r = 0; r < 16; r += 2) { f32x2 a = (f32x2){s0[r], s0[r + 1]} - m2, b = (f32x2){s1[r], s1[r + 1]} - m2;
;             a.x = __builtin_amdgcn_exp2f(a.x); a.y = __builtin_amdgcn_exp2f(a.y); b.x = __builtin_amdgcn_exp2f(b.x); b.y = __builtin_amdgcn_exp2f(b.y);
;             s0[r] = a.x; s0[r + 1] = a.y; s1[r] = b.x; s1[r + 1] = b.y; ps2 += a + b; }
;         const float ps = ps2.x + ps2.y;
;         lsum = lsum * alpha + ps;
; #pragma unroll
;         for (int r = 0; r < 16; ++r) { o0[r] *= alpha; o1[r] *= alpha; }
;         bf16x8 pb[4];
; #pragma unroll
;         for (int S = 0; S < 4; ++S) { u32x4 w;
;             if (S < 2) { w.x = cvt_pk_bf16(s0[8 * S + 0], s0[8 * S + 1]); w.y = cvt_pk_bf16(s0[8 * S + 2], s0[8 * S + 3]); w.z = cvt_pk_bf16(s0[8 * S + 4], s0[8 * S + 5]); w.w = cvt_pk_bf16(s0[8 * S + 6], s0[8 * S + 7]); }
;             else { w.x = cvt_pk_bf16(s1[8 * S - 16], s1[8 * S - 15]); w.y = cvt_pk_bf16(s1[8 * S - 14], s1[8 * S - 13]); w.z = cvt_pk_bf16(s1[8 * S - 12], s1[8 * S - 11]); w.w = cvt_pk_bf16(s1[8 * S - 10], s1[8 * S - 9]); }
	v_cvt_pk_bf16_f32 v17, v26, v27

; #define LAS __attribute__((address_space(3)))
; template <bool QK, bool SM>
; __device__ __forceinline__ void attn_step(const LAS unsigned char* kb, const LAS unsigned char* vbp, const bf16x8 (&qr)[6],
;                                           f32x16& s0, f32x16& s1, f32x16& o0, f32x16& o1, float& mrow, float& lsum) {
;     ...
;         const float mnew = fmaxf(mrow, mx), alpha = __builtin_amdgcn_exp2f(mrow - mnew); mrow = mnew;
;         const f32x2 m2 = (f32x2){mnew, mnew}; f32x2 ps2 = (f32x2){0.f, 0.f};
; #pragma unroll
;         for (int r = 0; r < 16; r += 2) { f32x2 a = (f32x2){s0[r], s0[r + 1]} - m2, b = (f32x2){s1[r], s1[r + 1]} - m2;
;             a.x = __builtin_amdgcn_exp2f(a.x); a.y = __builtin_amdgcn_exp2f(a.y); b.x = __builtin_amdgcn_exp2f(b.x); b.y = __builtin_amdgcn_exp2f(b.y);
;             s0[r] = a.x; s0[r + 1] = a.y; s1[r] = b.x; s1[r + 1] = b.y; ps2 += a + b; }
;         const float ps = ps2.x + ps2.y;
;         lsum = lsum * alpha + ps;
; #pragma unroll
;         for (int r = 0; r < 16; ++r) { o0[r] *= alpha; o1[r] *= alpha; }
;         bf16x8 pb[4];
; #pragma unroll
;         for (int S = 0; S < 4; ++S) { u32x4 w;
;             if (S < 2) { w.x = cvt_pk_bf16(s0[8 * S + 0], s0[8 * S + 1]); w.y = cvt_pk_bf16(s0[8 * S + 2], s0[8 * S + 3]); w.z = cvt_pk_bf16(s0[8 * S + 4], s0[8 * S + 5]); w.w = cvt_pk_bf16(s0[8 * S + 6], s0[8 * S + 7]); }
;             else { w.x = cvt_pk_bf16(s1[8 * S - 16], s1[8 * S - 15]); w.y = cvt_pk_bf16(s1[8 * S - 14], s1[8 * S - 13]); w.z = cvt_pk_bf16(s1[8 * S - 12], s1[8 * S - 11]); w.w = cvt_pk_bf16(s1[8 * S - 10], s1[8 * S - 9]); }
;             pb[S] = __builtin_bit_cast(bf16x8, w); }
; #pragma unroll
;         for (int S = 0; S < 4; ++S) {
;             const u32x2 a0 = *(const LAS u32x2*)(vbp + S * 32), a1 = *(const LAS u32x2*)(vbp + S * 32 + 16);
;             const u32x2 c0 = *(const LAS u32x2*)(vbp + 32 * VPITCH + S * 32), c1 = *(const LAS u32x2*)(vbp + 32 * VPITCH + S * 32 + 16);
;             const bf16x8 va = __builtin_bit_cast(bf16x8, (u32x4){a0.x, a0.y, a1.x, a1.y}), vc = __builtin_bit_cast(bf16x8, (u32x4){c0.x, c0.y, c1.x, c1.y});
;             o0 = __builtin_amdgcn_mfma_f32_32x32x16_bf16(va, pb[S], o0, 0, 0, 0); o1 = __builtin_amdgcn_mfma_f32_32x32x16_bf16(vc, pb[S], o1, 0, 0, 0); }
;     }
;     s0 = n0; s1 = n1;
	v_sub_f32_e32 v54, v126, v206
	v_sub_f32_e32 v55, v127, v206
	v_exp_f32_e32 v9, v31
	v_mul_f32_e32 v46, v46, v0
	v_mul_f32_e32 v47, v47, v0
	v_mul_f32_e32 v44, v44, v0
	v_mul_f32_e32 v45, v45, v0
	v_mul_f32_e32 v42, v42, v0
	v_mul_f32_e32 v43, v43, v0
	v_mul_f32_e32 v40, v40, v0
	v_mul_f32_e32 v41, v41, v0
	v_mul_f32_e32 v38, v38, v0
	v_mul_f32_e32 v39, v39, v0
	v_mul_f32_e32 v36, v36, v0
	v_mul_f32_e32 v37, v37, v0
	v_mul_f32_e32 v34, v34, v0
	v_mul_f32_e32 v35, v35, v0
	v_mul_f32_e32 v32, v32, v0
	v_mul_f32_e32 v33, v33, v0
	v_mul_f32_e32 v78, v78, v0
	v_mul_f32_e32 v79, v79, v0
	v_mul_f32_e32 v76, v76, v0
	v_mul_f32_e32 v77, v77, v0
	s_waitcnt lgkmcnt(1)
	v_mfma_f32_32x32x16_bf16 v[32:47], v[10:13], v[14:17], v[32:47]
	v_mul_f32_e32 v74, v74, v0
	v_mul_f32_e32 v75, v75, v0
	v_mul_f32_e32 v72, v72, v0
	v_mul_f32_e32 v73, v73, v0
	v_mul_f32_e32 v70, v70, v0
	v_mul_f32_e32 v71, v71, v0
	v_mul_f32_e32 v68, v68, v0
	v_mul_f32_e32 v69, v69, v0
	v_mul_f32_e32 v66, v66, v0
	v_mul_f32_e32 v67, v67, v0
	v_mul_f32_e32 v64, v64, v0
	v_mul_f32_e32 v65, v65, v0
	ds_read2_b64 v[10:13], v30 offset0:68 offset1:70
	v_exp_f32_e32 v54, v54
	s_waitcnt lgkmcnt(1)
	v_mfma_f32_32x32x16_bf16 v[64:79], v[18:21], v[14:17], v[64:79]
	ds_read2_b64 v[18:21], v56 offset0:100 offset1:102
	v_exp_f32_e32 v55, v55
	v_cvt_pk_bf16_f32 v14, v48, v49
	v_cvt_pk_bf16_f32 v15, v50, v51
	v_cvt_pk_bf16_f32 v16, v52, v53
	v_cvt_pk_bf16_f32 v17, v54, v55
	v_cvt_pk_bf16_f32 v2, v2, v3
	v_cvt_pk_bf16_f32 v3, v4, v5
	v_cvt_pk_bf16_f32 v4, v6, v7
	v_sub_f32_e32 v6, v92, v206
	v_sub_f32_e32 v7, v93, v206
	s_waitcnt lgkmcnt(1)
	v_mfma_f32_32x32x16_bf16 v[32:47], v[10:13], v[14:17], v[32:47]
	v_add_f32_e32 v10, v24, v22
	v_add_f32_e32 v11, v25, v23
	v_add_f32_e32 v12, v26, v28
	v_add_f32_e32 v13, v27, v29
	v_add_f32_e32 v24, v48, v8
	v_add_f32_e32 v25, v49, v9
	v_add_f32_e32 v22, v12, v10
	v_add_f32_e32 v23, v13, v11
	ds_read2_b64 v[10:13], v30 offset0:72 offset1:74
	v_cvt_pk_bf16_f32 v5, v28, v29
	v_sub_f32_e32 v26, v90, v206
	v_sub_f32_e32 v27, v91, v206
	s_waitcnt lgkmcnt(1)
	v_mfma_f32_32x32x16_bf16 v[64:79], v[18:21], v[14:17], v[64:79]
	ds_read2_b64 v[14:17], v56 offset0:104 offset1:106
	v_add_f32_e32 v20, v24, v22
	v_add_f32_e32 v21, v25, v23
	v_exp_f32_e32 v24, v6
	v_exp_f32_e32 v25, v7
	v_sub_f32_e32 v6, v94, v206
	v_sub_f32_e32 v7, v95, v206
	v_exp_f32_e32 v18, v26
	v_exp_f32_e32 v19, v27
	s_waitcnt lgkmcnt(1)
	v_mfma_f32_32x32x16_bf16 v[32:47], v[10:13], v[2:5], v[32:47]
	ds_read2_b64 v[10:13], v30 offset0:76 offset1:78
	v_add_f32_e32 v22, v50, v18
	v_add_f32_e32 v23, v51, v19
	s_waitcnt lgkmcnt(1)
	v_mfma_f32_32x32x16_bf16 v[64:79], v[14:17], v[2:5], v[64:79]
	v_exp_f32_e32 v14, v6
	v_exp_f32_e32 v15, v7
	v_cvt_pk_bf16_f32 v2, v8, v9
	ds_read2_b64 v[6:9], v56 offset0:108 offset1:110
	v_cvt_pk_bf16_f32 v3, v18, v19
	v_cvt_pk_bf16_f32 v4, v24, v25
	v_cvt_pk_bf16_f32 v5, v14, v15
	s_waitcnt lgkmcnt(1)
	v_mfma_f32_32x32x16_bf16 v[32:47], v[10:13], v[2:5], v[32:47]
	v_add_f32_e32 v10, v22, v20
	v_add_f32_e32 v11, v23, v21
	v_add_f32_e32 v12, v52, v24
	v_add_f32_e32 v13, v53, v25
	v_add_f32_e32 v10, v12, v10
	v_add_f32_e32 v11, v13, v11
	v_add_f32_e32 v12, v54, v14
	v_add_f32_e32 v13, v55, v15
	v_mov_b32_e32 v14, v1
	v_add_f32_e32 v10, v12, v10
	v_add_f32_e32 v11, v13, v11
	s_waitcnt lgkmcnt(0)
	v_mfma_f32_32x32x16_bf16 v[64:79], v[6:9], v[2:5], v[64:79]
	v_add_f32_e32 v215, v10, v11
	v_mov_b32_e32 v15, v1
	v_fmac_f32_e32 v215, v216, v0
	v_mov_b32_e32 v0, v1
	v_mov_b32_e32 v2, v1
	v_mov_b32_e32 v3, v1
	v_mov_b32_e32 v4, v1
	v_mov_b32_e32 v5, v1
	v_mov_b32_e32 v6, v1
	v_mov_b32_e32 v7, v1
	v_mov_b32_e32 v8, v1
	v_mov_b32_e32 v9, v1
	v_mov_b32_e32 v10, v1
	v_mov_b32_e32 v11, v1
	v_mov_b32_e32 v12, v1
	v_mov_b32_e32 v13, v1
	v_mov_b64_e32 v[30:31], v[14:15]
	v_mov_b64_e32 v[62:63], v[14:15]
	v_mov_b64_e32 v[28:29], v[12:13]
	v_mov_b64_e32 v[26:27], v[10:11]
	v_mov_b64_e32 v[24:25], v[8:9]
	v_mov_b64_e32 v[22:23], v[6:7]
	v_mov_b64_e32 v[20:21], v[4:5]
	v_mov_b64_e32 v[18:19], v[2:3]
	v_mov_b64_e32 v[16:17], v[0:1]
	v_mov_b64_e32 v[60:61], v[12:13]
	v_mov_b64_e32 v[58:59], v[10:11]
	v_mov_b64_e32 v[56:57], v[8:9]
	v_mov_b64_e32 v[54:55], v[6:7]
	v_mov_b64_e32 v[52:53], v[4:5]
	v_mov_b64_e32 v[50:51], v[2:3]
	v_mov_b64_e32 v[48:49], v[0:1]

; #define LAS __attribute__((address_space(3)))
; template <bool QK, bool SM>
; __device__ __forceinline__ void attn_step(const LAS unsigned char* kb, const LAS unsigned char* vbp, const bf16x8 (&qr)[6],
;                                           f32x16& s0, f32x16& s1, f32x16& o0, f32x16& o1, float& mrow, float& lsum) {
;     ...
;         for (int s = 0; s < 6; ++s) { const bf16x8 ka = *(const LAS bf16x8*)(kb + s * 32), kc = *(const LAS bf16x8*)(kb + 32 * KPITCH + s * 32);
;             n0 = __builtin_amdgcn_mfma_f32_32x32x16_bf16(ka, qr[s], n0, 0, 0, 0); n1 = __builtin_amdgcn_mfma_f32_32x32x16_bf16(kc, qr[s], n1, 0, 0, 0); }
.LBB0_957:
	ds_read_b128 v[2:5], v213
	ds_read_b128 v[10:13], v213 offset:32
	ds_read_b128 v[14:17], v213 offset:6656
	ds_read_b128 v[96:99], v213 offset:6688
	ds_read_b128 v[18:21], v213 offset:64
	ds_read_b128 v[22:25], v213 offset:96
	s_waitcnt lgkmcnt(5)
	v_mfma_f32_32x32x16_bf16 v[48:63], v[2:5], v[164:167], v[218:233]

; #define LAS __attribute__((address_space(3)))
; __device__ __forceinline__ float max3f(float a, float b, float c) { float r; asm("v_max3_f32 %0, %1, %2, %3" : "=v"(r) : "v"(a), "v"(b), "v"(c)); return r; }
; template <bool QK, bool SM>
; __device__ __forceinline__ void attn_step(const LAS unsigned char* kb, const LAS unsigned char* vbp, const bf16x8 (&qr)[6],
;                                           f32x16& s0, f32x16& s1, f32x16& o0, f32x16& o1, float& mrow, float& lsum) {
;     ...
;         for (int s = 0; s < 6; ++s) { const bf16x8 ka = *(const LAS bf16x8*)(kb + s * 32), kc = *(const LAS bf16x8*)(kb + 32 * KPITCH + s * 32);
;             n0 = __builtin_amdgcn_mfma_f32_32x32x16_bf16(ka, qr[s], n0, 0, 0, 0); n1 = __builtin_amdgcn_mfma_f32_32x32x16_bf16(kc, qr[s], n1, 0, 0, 0); }
;     }
;     if constexpr (SM) {
;         float mx = max3f(s0[0], s1[0], s0[1]); mx = max3f(mx, s1[1], s0[2]); float my = max3f(s1[2], s0[3], s1[3]);
	v_max3_f32 v0, v112, v80, v113

; #define LAS __attribute__((address_space(3)))
; template <bool QK, bool SM>
; __device__ __forceinline__ void attn_step(const LAS unsigned char* kb, const LAS unsigned char* vbp, const bf16x8 (&qr)[6],
;                                           f32x16& s0, f32x16& s1, f32x16& o0, f32x16& o1, float& mrow, float& lsum) {
;     ...
;         for (int s = 0; s < 6; ++s) { const bf16x8 ka = *(const LAS bf16x8*)(kb + s * 32), kc = *(const LAS bf16x8*)(kb + 32 * KPITCH + s * 32);
	ds_read_b128 v[100:103], v213 offset:6720
	ds_read_b128 v[104:107], v213 offset:6752
	ds_read_b128 v[26:29], v213 offset:128
	ds_read_b128 v[108:111], v213 offset:160
	ds_read_b128 v[6:9], v213 offset:6784
	ds_read_b128 v[2:5], v213 offset:6816

; __device__ __forceinline__ float max3f(float a, float b, float c) { float r; asm("v_max3_f32 %0, %1, %2, %3" : "=v"(r) : "v"(a), "v"(b), "v"(c)); return r; }
; template <bool QK, bool SM>
; __device__ __forceinline__ void attn_step(const LAS unsigned char* kb, const LAS unsigned char* vbp, const bf16x8 (&qr)[6],
;                                           f32x16& s0, f32x16& s1, f32x16& o0, f32x16& o1, float& mrow, float& lsum) {
;     ...
;         float mx = max3f(s0[0], s1[0], s0[1]); mx = max3f(mx, s1[1], s0[2]); float my = max3f(s1[2], s0[3], s1[3]);
; #pragma unroll
;         for (int r = 4; r < 16; r += 4) { mx = max3f(mx, s0[r], s1[r]); my = max3f(my, s0[r + 1], s1[r + 1]); mx = max3f(mx, s0[r + 2], s1[r + 2]); my = max3f(my, s0[r + 3], s1[r + 3]); }
	v_max3_f32 v0, v0, v81, v114

; #define LAS __attribute__((address_space(3)))
; template <bool QK, bool SM>
; __device__ __forceinline__ void attn_step(const LAS unsigned char* kb, const LAS unsigned char* vbp, const bf16x8 (&qr)[6],
;                                           f32x16& s0, f32x16& s1, f32x16& o0, f32x16& o1, float& mrow, float& lsum) {
;     ...
;             const u32x2 a0 = *(const LAS u32x2*)(vbp + S * 32), a1 = *(const LAS u32x2*)(vbp + S * 32 + 16);
;             const u32x2 c0 = *(const LAS u32x2*)(vbp + 32 * VPITCH + S * 32), c1 = *(const LAS u32x2*)(vbp + 32 * VPITCH + S * 32 + 16);
	v_add_u32_e32 v132, v214, v204

; __device__ __forceinline__ float max3f(float a, float b, float c) { float r; asm("v_max3_f32 %0, %1, %2, %3" : "=v"(r) : "v"(a), "v"(b), "v"(c)); return r; }
; template <bool QK, bool SM>
; __device__ __forceinline__ void attn_step(const LAS unsigned char* kb, const LAS unsigned char* vbp, const bf16x8 (&qr)[6],
;                                           f32x16& s0, f32x16& s1, f32x16& o0, f32x16& o1, float& mrow, float& lsum) {
;     ...
;         float mx = max3f(s0[0], s1[0], s0[1]); mx = max3f(mx, s1[1], s0[2]); float my = max3f(s1[2], s0[3], s1[3]);
; #pragma unroll
;         for (int r = 4; r < 16; r += 4) { mx = max3f(mx, s0[r], s1[r]); my = max3f(my, s0[r + 1], s1[r + 1]); mx = max3f(mx, s0[r + 2], s1[r + 2]); my = max3f(my, s0[r + 3], s1[r + 3]); }
	v_max3_f32 v0, v0, v116, v84

; __device__ __forceinline__ float max3f(float a, float b, float c) { float r; asm("v_max3_f32 %0, %1, %2, %3" : "=v"(r) : "v"(a), "v"(b), "v"(c)); return r; }
; template <bool QK, bool SM>
; __device__ __forceinline__ void attn_step(const LAS unsigned char* kb, const LAS unsigned char* vbp, const bf16x8 (&qr)[6],
;                                           f32x16& s0, f32x16& s1, f32x16& o0, f32x16& o1, float& mrow, float& lsum) {
;     ...
;         float mx = max3f(s0[0], s1[0], s0[1]); mx = max3f(mx, s1[1], s0[2]); float my = max3f(s1[2], s0[3], s1[3]);
; #pragma unroll
;         for (int r = 4; r < 16; r += 4) { mx = max3f(mx, s0[r], s1[r]); my = max3f(my, s0[r + 1], s1[r + 1]); mx = max3f(mx, s0[r + 2], s1[r + 2]); my = max3f(my, s0[r + 3], s1[r + 3]); }
	s_nop 0

; __device__ __forceinline__ float max3f(float a, float b, float c) { float r; asm("v_max3_f32 %0, %1, %2, %3" : "=v"(r) : "v"(a), "v"(b), "v"(c)); return r; }
; template <bool QK, bool SM>
; __device__ __forceinline__ void attn_step(const LAS unsigned char* kb, const LAS unsigned char* vbp, const bf16x8 (&qr)[6],
;                                           f32x16& s0, f32x16& s1, f32x16& o0, f32x16& o1, float& mrow, float& lsum) {
;     ...
;         float mx = max3f(s0[0], s1[0], s0[1]); mx = max3f(mx, s1[1], s0[2]); float my = max3f(s1[2], s0[3], s1[3]);
; #pragma unroll
;         for (int r = 4; r < 16; r += 4) { mx = max3f(mx, s0[r], s1[r]); my = max3f(my, s0[r + 1], s1[r + 1]); mx = max3f(mx, s0[r + 2], s1[r + 2]); my = max3f(my, s0[r + 3], s1[r + 3]); }
	v_max3_f32 v0, v0, v118, v86

; #define LAS __attribute__((address_space(3)))
; template <bool QK, bool SM>
; __device__ __forceinline__ void attn_step(const LAS unsigned char* kb, const LAS unsigned char* vbp, const bf16x8 (&qr)[6],
;                                           f32x16& s0, f32x16& s1, f32x16& o0, f32x16& o1, float& mrow, float& lsum) {
;     ...
;         for (int s = 0; s < 6; ++s) { const bf16x8 ka = *(const LAS bf16x8*)(kb + s * 32), kc = *(const LAS bf16x8*)(kb + 32 * KPITCH + s * 32);
;             n0 = __builtin_amdgcn_mfma_f32_32x32x16_bf16(ka, qr[s], n0, 0, 0, 0); n1 = __builtin_amdgcn_mfma_f32_32x32x16_bf16(kc, qr[s], n1, 0, 0, 0); }
	s_waitcnt lgkmcnt(10)
	v_mfma_f32_32x32x16_bf16 v[48:63], v[10:13], v[160:163], v[48:63]

; __device__ __forceinline__ float max3f(float a, float b, float c) { float r; asm("v_max3_f32 %0, %1, %2, %3" : "=v"(r) : "v"(a), "v"(b), "v"(c)); return r; }
; template <bool QK, bool SM>
; __device__ __forceinline__ void attn_step(const LAS unsigned char* kb, const LAS unsigned char* vbp, const bf16x8 (&qr)[6],
;                                           f32x16& s0, f32x16& s1, f32x16& o0, f32x16& o1, float& mrow, float& lsum) {
;     ...
;         float mx = max3f(s0[0], s1[0], s0[1]); mx = max3f(mx, s1[1], s0[2]); float my = max3f(s1[2], s0[3], s1[3]);
; #pragma unroll
;         for (int r = 4; r < 16; r += 4) { mx = max3f(mx, s0[r], s1[r]); my = max3f(my, s0[r + 1], s1[r + 1]); mx = max3f(mx, s0[r + 2], s1[r + 2]); my = max3f(my, s0[r + 3], s1[r + 3]); }
	v_max3_f32 v10, v82, v115, v83


; __device__ __forceinline__ float max3f(float a, float b, float c) { float r; asm("v_max3_f32 %0, %1, %2, %3" : "=v"(r) : "v"(a), "v"(b), "v"(c)); return r; }
; template <bool QK, bool SM>
; __device__ __forceinline__ void attn_step(const LAS unsigned char* kb, const LAS unsigned char* vbp, const bf16x8 (&qr)[6],
;                                           f32x16& s0, f32x16& s1, f32x16& o0, f32x16& o1, float& mrow, float& lsum) {
;     ...
;         float mx = max3f(s0[0], s1[0], s0[1]); mx = max3f(mx, s1[1], s0[2]); float my = max3f(s1[2], s0[3], s1[3]);
; #pragma unroll
;         for (int r = 4; r < 16; r += 4) { mx = max3f(mx, s0[r], s1[r]); my = max3f(my, s0[r + 1], s1[r + 1]); mx = max3f(mx, s0[r + 2], s1[r + 2]); my = max3f(my, s0[r + 3], s1[r + 3]); }
	v_max3_f32 v0, v0, v120, v88

; __device__ __forceinline__ float max3f(float a, float b, float c) { float r; asm("v_max3_f32 %0, %1, %2, %3" : "=v"(r) : "v"(a), "v"(b), "v"(c)); return r; }
; template <bool QK, bool SM>
; __device__ __forceinline__ void attn_step(const LAS unsigned char* kb, const LAS unsigned char* vbp, const bf16x8 (&qr)[6],
;                                           f32x16& s0, f32x16& s1, f32x16& o0, f32x16& o1, float& mrow, float& lsum) {
;     ...
;         float mx = max3f(s0[0], s1[0], s0[1]); mx = max3f(mx, s1[1], s0[2]); float my = max3f(s1[2], s0[3], s1[3]);
; #pragma unroll
;         for (int r = 4; r < 16; r += 4) { mx = max3f(mx, s0[r], s1[r]); my = max3f(my, s0[r + 1], s1[r + 1]); mx = max3f(mx, s0[r + 2], s1[r + 2]); my = max3f(my, s0[r + 3], s1[r + 3]); }
	s_nop 0

; __device__ __forceinline__ float max3f(float a, float b, float c) { float r; asm("v_max3_f32 %0, %1, %2, %3" : "=v"(r) : "v"(a), "v"(b), "v"(c)); return r; }
; template <bool QK, bool SM>
; __device__ __forceinline__ void attn_step(const LAS unsigned char* kb, const LAS unsigned char* vbp, const bf16x8 (&qr)[6],
;                                           f32x16& s0, f32x16& s1, f32x16& o0, f32x16& o1, float& mrow, float& lsum) {
;     ...
;         float mx = max3f(s0[0], s1[0], s0[1]); mx = max3f(mx, s1[1], s0[2]); float my = max3f(s1[2], s0[3], s1[3]);
; #pragma unroll
;         for (int r = 4; r < 16; r += 4) { mx = max3f(mx, s0[r], s1[r]); my = max3f(my, s0[r + 1], s1[r + 1]); mx = max3f(mx, s0[r + 2], s1[r + 2]); my = max3f(my, s0[r + 3], s1[r + 3]); }
	v_max3_f32 v10, v10, v117, v85


; __device__ __forceinline__ float max3f(float a, float b, float c) { float r; asm("v_max3_f32 %0, %1, %2, %3" : "=v"(r) : "v"(a), "v"(b), "v"(c)); return r; }
; template <bool QK, bool SM>
; __device__ __forceinline__ void attn_step(const LAS unsigned char* kb, const LAS unsigned char* vbp, const bf16x8 (&qr)[6],
;                                           f32x16& s0, f32x16& s1, f32x16& o0, f32x16& o1, float& mrow, float& lsum) {
;     ...
;         float mx = max3f(s0[0], s1[0], s0[1]); mx = max3f(mx, s1[1], s0[2]); float my = max3f(s1[2], s0[3], s1[3]);
; #pragma unroll
;         for (int r = 4; r < 16; r += 4) { mx = max3f(mx, s0[r], s1[r]); my = max3f(my, s0[r + 1], s1[r + 1]); mx = max3f(mx, s0[r + 2], s1[r + 2]); my = max3f(my, s0[r + 3], s1[r + 3]); }
	v_max3_f32 v0, v0, v122, v90

; __device__ __forceinline__ float max3f(float a, float b, float c) { float r; asm("v_max3_f32 %0, %1, %2, %3" : "=v"(r) : "v"(a), "v"(b), "v"(c)); return r; }
; template <bool QK, bool SM>
; __device__ __forceinline__ void attn_step(const LAS unsigned char* kb, const LAS unsigned char* vbp, const bf16x8 (&qr)[6],
;                                           f32x16& s0, f32x16& s1, f32x16& o0, f32x16& o1, float& mrow, float& lsum) {
;     ...
;         float mx = max3f(s0[0], s1[0], s0[1]); mx = max3f(mx, s1[1], s0[2]); float my = max3f(s1[2], s0[3], s1[3]);
; #pragma unroll
;         for (int r = 4; r < 16; r += 4) { mx = max3f(mx, s0[r], s1[r]); my = max3f(my, s0[r + 1], s1[r + 1]); mx = max3f(mx, s0[r + 2], s1[r + 2]); my = max3f(my, s0[r + 3], s1[r + 3]); }
	s_nop 0

; __device__ __forceinline__ float max3f(float a, float b, float c) { float r; asm("v_max3_f32 %0, %1, %2, %3" : "=v"(r) : "v"(a), "v"(b), "v"(c)); return r; }
; template <bool QK, bool SM>
; __device__ __forceinline__ void attn_step(const LAS unsigned char* kb, const LAS unsigned char* vbp, const bf16x8 (&qr)[6],
;                                           f32x16& s0, f32x16& s1, f32x16& o0, f32x16& o1, float& mrow, float& lsum) {
;     ...
;         float mx = max3f(s0[0], s1[0], s0[1]); mx = max3f(mx, s1[1], s0[2]); float my = max3f(s1[2], s0[3], s1[3]);
; #pragma unroll
;         for (int r = 4; r < 16; r += 4) { mx = max3f(mx, s0[r], s1[r]); my = max3f(my, s0[r + 1], s1[r + 1]); mx = max3f(mx, s0[r + 2], s1[r + 2]); my = max3f(my, s0[r + 3], s1[r + 3]); }
	v_max3_f32 v10, v10, v119, v87

; #define LAS __attribute__((address_space(3)))
; template <bool QK, bool SM>
; __device__ __forceinline__ void attn_step(const LAS unsigned char* kb, const LAS unsigned char* vbp, const bf16x8 (&qr)[6],
;                                           f32x16& s0, f32x16& s1, f32x16& o0, f32x16& o1, float& mrow, float& lsum) {
;     ...
;         for (int s = 0; s < 6; ++s) { const bf16x8 ka = *(const LAS bf16x8*)(kb + s * 32), kc = *(const LAS bf16x8*)(kb + 32 * KPITCH + s * 32);
;             n0 = __builtin_amdgcn_mfma_f32_32x32x16_bf16(ka, qr[s], n0, 0, 0, 0); n1 = __builtin_amdgcn_mfma_f32_32x32x16_bf16(kc, qr[s], n1, 0, 0, 0); }
	s_waitcnt lgkmcnt(7)
	v_mfma_f32_32x32x16_bf16 v[48:63], v[18:21], v[156:159], v[48:63]

; __device__ __forceinline__ float max3f(float a, float b, float c) { float r; asm("v_max3_f32 %0, %1, %2, %3" : "=v"(r) : "v"(a), "v"(b), "v"(c)); return r; }
; template <bool QK, bool SM>
; __device__ __forceinline__ void attn_step(const LAS unsigned char* kb, const LAS unsigned char* vbp, const bf16x8 (&qr)[6],
;                                           f32x16& s0, f32x16& s1, f32x16& o0, f32x16& o1, float& mrow, float& lsum) {
;     ...
;         float mx = max3f(s0[0], s1[0], s0[1]); mx = max3f(mx, s1[1], s0[2]); float my = max3f(s1[2], s0[3], s1[3]);
; #pragma unroll
;         for (int r = 4; r < 16; r += 4) { mx = max3f(mx, s0[r], s1[r]); my = max3f(my, s0[r + 1], s1[r + 1]); mx = max3f(mx, s0[r + 2], s1[r + 2]); my = max3f(my, s0[r + 3], s1[r + 3]); }
	v_max3_f32 v10, v10, v121, v89


; __device__ __forceinline__ float max3f(float a, float b, float c) { float r; asm("v_max3_f32 %0, %1, %2, %3" : "=v"(r) : "v"(a), "v"(b), "v"(c)); return r; }
; template <bool QK, bool SM>
; __device__ __forceinline__ void attn_step(const LAS unsigned char* kb, const LAS unsigned char* vbp, const bf16x8 (&qr)[6],
;                                           f32x16& s0, f32x16& s1, f32x16& o0, f32x16& o1, float& mrow, float& lsum) {
;     ...
;         float mx = max3f(s0[0], s1[0], s0[1]); mx = max3f(mx, s1[1], s0[2]); float my = max3f(s1[2], s0[3], s1[3]);
; #pragma unroll
;         for (int r = 4; r < 16; r += 4) { mx = max3f(mx, s0[r], s1[r]); my = max3f(my, s0[r + 1], s1[r + 1]); mx = max3f(mx, s0[r + 2], s1[r + 2]); my = max3f(my, s0[r + 3], s1[r + 3]); }
	v_max3_f32 v0, v0, v124, v92

; __device__ __forceinline__ float max3f(float a, float b, float c) { float r; asm("v_max3_f32 %0, %1, %2, %3" : "=v"(r) : "v"(a), "v"(b), "v"(c)); return r; }
; template <bool QK, bool SM>
; __device__ __forceinline__ void attn_step(const LAS unsigned char* kb, const LAS unsigned char* vbp, const bf16x8 (&qr)[6],
;                                           f32x16& s0, f32x16& s1, f32x16& o0, f32x16& o1, float& mrow, float& lsum) {
;     ...
;         float mx = max3f(s0[0], s1[0], s0[1]); mx = max3f(mx, s1[1], s0[2]); float my = max3f(s1[2], s0[3], s1[3]);
; #pragma unroll
;         for (int r = 4; r < 16; r += 4) { mx = max3f(mx, s0[r], s1[r]); my = max3f(my, s0[r + 1], s1[r + 1]); mx = max3f(mx, s0[r + 2], s1[r + 2]); my = max3f(my, s0[r + 3], s1[r + 3]); }
	s_nop 0

; __device__ __forceinline__ float max3f(float a, float b, float c) { float r; asm("v_max3_f32 %0, %1, %2, %3" : "=v"(r) : "v"(a), "v"(b), "v"(c)); return r; }
; template <bool QK, bool SM>
; __device__ __forceinline__ void attn_step(const LAS unsigned char* kb, const LAS unsigned char* vbp, const bf16x8 (&qr)[6],
;                                           f32x16& s0, f32x16& s1, f32x16& o0, f32x16& o1, float& mrow, float& lsum) {
;     ...
;         float mx = max3f(s0[0], s1[0], s0[1]); mx = max3f(mx, s1[1], s0[2]); float my = max3f(s1[2], s0[3], s1[3]);
; #pragma unroll
;         for (int r = 4; r < 16; r += 4) { mx = max3f(mx, s0[r], s1[r]); my = max3f(my, s0[r + 1], s1[r + 1]); mx = max3f(mx, s0[r + 2], s1[r + 2]); my = max3f(my, s0[r + 3], s1[r + 3]); }
	v_max3_f32 v10, v10, v123, v91


; __device__ __forceinline__ float max3f(float a, float b, float c) { float r; asm("v_max3_f32 %0, %1, %2, %3" : "=v"(r) : "v"(a), "v"(b), "v"(c)); return r; }
; template <bool QK, bool SM>
; __device__ __forceinline__ void attn_step(const LAS unsigned char* kb, const LAS unsigned char* vbp, const bf16x8 (&qr)[6],
;                                           f32x16& s0, f32x16& s1, f32x16& o0, f32x16& o1, float& mrow, float& lsum) {
;     ...
;         float mx = max3f(s0[0], s1[0], s0[1]); mx = max3f(mx, s1[1], s0[2]); float my = max3f(s1[2], s0[3], s1[3]);
; #pragma unroll
;         for (int r = 4; r < 16; r += 4) { mx = max3f(mx, s0[r], s1[r]); my = max3f(my, s0[r + 1], s1[r + 1]); mx = max3f(mx, s0[r + 2], s1[r + 2]); my = max3f(my, s0[r + 3], s1[r + 3]); }
	v_max3_f32 v0, v0, v126, v94

; __device__ __forceinline__ float max3f(float a, float b, float c) { float r; asm("v_max3_f32 %0, %1, %2, %3" : "=v"(r) : "v"(a), "v"(b), "v"(c)); return r; }
; template <bool QK, bool SM>
; __device__ __forceinline__ void attn_step(const LAS unsigned char* kb, const LAS unsigned char* vbp, const bf16x8 (&qr)[6],
;                                           f32x16& s0, f32x16& s1, f32x16& o0, f32x16& o1, float& mrow, float& lsum) {
;     ...
;         float mx = max3f(s0[0], s1[0], s0[1]); mx = max3f(mx, s1[1], s0[2]); float my = max3f(s1[2], s0[3], s1[3]);
; #pragma unroll
;         for (int r = 4; r < 16; r += 4) { mx = max3f(mx, s0[r], s1[r]); my = max3f(my, s0[r + 1], s1[r + 1]); mx = max3f(mx, s0[r + 2], s1[r + 2]); my = max3f(my, s0[r + 3], s1[r + 3]); }
	s_nop 0

; __device__ __forceinline__ float max3f(float a, float b, float c) { float r; asm("v_max3_f32 %0, %1, %2, %3" : "=v"(r) : "v"(a), "v"(b), "v"(c)); return r; }
; template <bool QK, bool SM>
; __device__ __forceinline__ void attn_step(const LAS unsigned char* kb, const LAS unsigned char* vbp, const bf16x8 (&qr)[6],
;                                           f32x16& s0, f32x16& s1, f32x16& o0, f32x16& o1, float& mrow, float& lsum) {
;     ...
;         float mx = max3f(s0[0], s1[0], s0[1]); mx = max3f(mx, s1[1], s0[2]); float my = max3f(s1[2], s0[3], s1[3]);
; #pragma unroll
;         for (int r = 4; r < 16; r += 4) { mx = max3f(mx, s0[r], s1[r]); my = max3f(my, s0[r + 1], s1[r + 1]); mx = max3f(mx, s0[r + 2], s1[r + 2]); my = max3f(my, s0[r + 3], s1[r + 3]); }
	v_max3_f32 v10, v10, v125, v93

; #define LAS __attribute__((address_space(3)))
; template <bool QK, bool SM>
; __device__ __forceinline__ void attn_step(const LAS unsigned char* kb, const LAS unsigned char* vbp, const bf16x8 (&qr)[6],
;                                           f32x16& s0, f32x16& s1, f32x16& o0, f32x16& o1, float& mrow, float& lsum) {
;     ...
;         for (int s = 0; s < 6; ++s) { const bf16x8 ka = *(const LAS bf16x8*)(kb + s * 32), kc = *(const LAS bf16x8*)(kb + 32 * KPITCH + s * 32);
;             n0 = __builtin_amdgcn_mfma_f32_32x32x16_bf16(ka, qr[s], n0, 0, 0, 0); n1 = __builtin_amdgcn_mfma_f32_32x32x16_bf16(kc, qr[s], n1, 0, 0, 0); }
	s_waitcnt lgkmcnt(6)
	v_mfma_f32_32x32x16_bf16 v[48:63], v[22:25], v[152:155], v[48:63]

; __device__ __forceinline__ float max3f(float a, float b, float c) { float r; asm("v_max3_f32 %0, %1, %2, %3" : "=v"(r) : "v"(a), "v"(b), "v"(c)); return r; }
; template <bool QK, bool SM>
; __device__ __forceinline__ void attn_step(const LAS unsigned char* kb, const LAS unsigned char* vbp, const bf16x8 (&qr)[6],
;                                           f32x16& s0, f32x16& s1, f32x16& o0, f32x16& o1, float& mrow, float& lsum) {
;     ...
;         float mx = max3f(s0[0], s1[0], s0[1]); mx = max3f(mx, s1[1], s0[2]); float my = max3f(s1[2], s0[3], s1[3]);
; #pragma unroll
;         for (int r = 4; r < 16; r += 4) { mx = max3f(mx, s0[r], s1[r]); my = max3f(my, s0[r + 1], s1[r + 1]); mx = max3f(mx, s0[r + 2], s1[r + 2]); my = max3f(my, s0[r + 3], s1[r + 3]); }
	v_max3_f32 v10, v10, v127, v95

; template <bool QK, bool SM>
; __device__ __forceinline__ void attn_step(const LAS unsigned char* kb, const LAS unsigned char* vbp, const bf16x8 (&qr)[6],
;                                           f32x16& s0, f32x16& s1, f32x16& o0, f32x16& o1, float& mrow, float& lsum) {
;     ...
;         mx = fmaxf(mx, my);
;         { const auto rr = __builtin_amdgcn_permlane32_swap(__float_as_uint(mx), __float_as_uint(mx), false, false); mx = fmaxf(__uint_as_float(rr[0]), __uint_as_float(rr[1])); }
;         const float mnew = fmaxf(mrow, mx), alpha = __builtin_amdgcn_exp2f(mrow - mnew); mrow = mnew;
;         const f32x2 m2 = (f32x2){mnew, mnew}; f32x2 ps2 = (f32x2){0.f, 0.f};
; #pragma unroll
;         for (int r = 0; r < 16; r += 2) { f32x2 a = (f32x2){s0[r], s0[r + 1]} - m2, b = (f32x2){s1[r], s1[r + 1]} - m2;
;             a.x = __builtin_amdgcn_exp2f(a.x); a.y = __builtin_amdgcn_exp2f(a.y); b.x = __builtin_amdgcn_exp2f(b.x); b.y = __builtin_amdgcn_exp2f(b.y);
;             s0[r] = a.x; s0[r + 1] = a.y; s1[r] = b.x; s1[r + 1] = b.y; ps2 += a + b; }
;         const float ps = ps2.x + ps2.y;
;         lsum = lsum * alpha + ps;
; #pragma unroll
;         for (int r = 0; r < 16; ++r) { o0[r] *= alpha; o1[r] *= alpha; }
	v_max_f32_e32 v0, v0, v0
	v_max_f32_e32 v10, v10, v10
	v_max_f32_e32 v0, v0, v10
	v_mov_b32_e32 v10, v0
	s_nop 1
	v_permlane32_swap_b32_e32 v0, v10
	v_max_f32_e32 v0, v0, v10
	v_sub_f32_e32 v10, v0, v208
	v_cmp_lt_f32_e32 vcc, 0x41000000, v10
	v_mov_b32_e32 v206, v208
	s_nop 0
	s_cbranch_vccnz .Latt_slowB
.Latt_contB:
	s_waitcnt lgkmcnt(3)
	v_mfma_f32_32x32x16_bf16 v[48:63], v[26:29], v[148:151], v[48:63]
	v_exp_f32_e32 v130, v114
	v_exp_f32_e32 v131, v115
	v_exp_f32_e32 v114, v82
	v_exp_f32_e32 v115, v83
	v_mfma_f32_32x32x16_bf16 v[16:31], v[14:17], v[164:167], v[218:233]
	v_exp_f32_e32 v128, v112
	v_exp_f32_e32 v129, v113
	v_exp_f32_e32 v112, v80
	v_exp_f32_e32 v113, v81
	v_add_f32_e32 v12, v130, v114
	v_add_f32_e32 v13, v131, v115
	v_mov_b32_e32 v14, v84
	v_mov_b32_e32 v15, v85
	v_mfma_f32_32x32x16_bf16 v[16:31], v[96:99], v[160:163], v[16:31]
	v_add_f32_e32 v10, v128, v112
	v_add_f32_e32 v11, v129, v113
	v_exp_f32_e32 v80, v118
	v_exp_f32_e32 v81, v119
	v_add_f32_e32 v10, 0, v10
	v_add_f32_e32 v11, 0, v11
	v_exp_f32_e32 v82, v120
	v_mfma_f32_32x32x16_bf16 v[16:31], v[100:103], v[156:159], v[16:31]
	v_exp_f32_e32 v83, v121
	v_add_f32_e32 v10, v12, v10
	v_add_f32_e32 v11, v13, v11
	v_exp_f32_e32 v84, v122
	v_exp_f32_e32 v85, v123
	v_mfma_f32_32x32x16_bf16 v[16:31], v[104:107], v[152:155], v[16:31]
	v_mov_b32_e32 v12, v116
	v_mov_b32_e32 v13, v117
	v_exp_f32_e32 v116, v124
	v_exp_f32_e32 v117, v125
	s_waitcnt lgkmcnt(2)
	v_mfma_f32_32x32x16_bf16 v[48:63], v[108:111], v[144:147], v[48:63]
	v_add_u32_e32 v110, 0x8800, v132
	v_add_u32_e32 v111, 0x9800, v132
	ds_read2_b64 v[100:103], v111 offset0:96 offset1:98
	v_exp_f32_e32 v12, v12
	s_waitcnt lgkmcnt(2)
	v_mfma_f32_32x32x16_bf16 v[16:31], v[6:9], v[148:151], v[16:31]
	ds_read2_b64 v[6:9], v110 offset0:64 offset1:66
	v_exp_f32_e32 v13, v13

; __device__ __forceinline__ unsigned cvt_pk_bf16(float lo, float hi) { unsigned r; asm("v_cvt_pk_bf16_f32 %0, %1, %2" : "=v"(r) : "v"(lo), "v"(hi)); return r; }
; template <bool QK, bool SM>
; __device__ __forceinline__ void attn_step(const LAS unsigned char* kb, const LAS unsigned char* vbp, const bf16x8 (&qr)[6],
;                                           f32x16& s0, f32x16& s1, f32x16& o0, f32x16& o1, float& mrow, float& lsum) {
;     ...
;         for (int S = 0; S < 4; ++S) { u32x4 w;
;             if (S < 2) { w.x = cvt_pk_bf16(s0[8 * S + 0], s0[8 * S + 1]); w.y = cvt_pk_bf16(s0[8 * S + 2], s0[8 * S + 3]); w.z = cvt_pk_bf16(s0[8 * S + 4], s0[8 * S + 5]); w.w = cvt_pk_bf16(s0[8 * S + 6], s0[8 * S + 7]); }
;             else { w.x = cvt_pk_bf16(s1[8 * S - 16], s1[8 * S - 15]); w.y = cvt_pk_bf16(s1[8 * S - 14], s1[8 * S - 13]); w.z = cvt_pk_bf16(s1[8 * S - 12], s1[8 * S - 11]); w.w = cvt_pk_bf16(s1[8 * S - 10], s1[8 * S - 9]); }
;             pb[S] = __builtin_bit_cast(bf16x8, w); }
	v_cvt_pk_bf16_f32 v96, v128, v129


; __device__ __forceinline__ unsigned cvt_pk_bf16(float lo, float hi) { unsigned r; asm("v_cvt_pk_bf16_f32 %0, %1, %2" : "=v"(r) : "v"(lo), "v"(hi)); return r; }
; template <bool QK, bool SM>
; __device__ __forceinline__ void attn_step(const LAS unsigned char* kb, const LAS unsigned char* vbp, const bf16x8 (&qr)[6],
;                                           f32x16& s0, f32x16& s1, f32x16& o0, f32x16& o1, float& mrow, float& lsum) {
;     ...
;         for (int S = 0; S < 4; ++S) { u32x4 w;
;             if (S < 2) { w.x = cvt_pk_bf16(s0[8 * S + 0], s0[8 * S + 1]); w.y = cvt_pk_bf16(s0[8 * S + 2], s0[8 * S + 3]); w.z = cvt_pk_bf16(s0[8 * S + 4], s0[8 * S + 5]); w.w = cvt_pk_bf16(s0[8 * S + 6], s0[8 * S + 7]); }
;             else { w.x = cvt_pk_bf16(s1[8 * S - 16], s1[8 * S - 15]); w.y = cvt_pk_bf16(s1[8 * S - 14], s1[8 * S - 13]); w.z = cvt_pk_bf16(s1[8 * S - 12], s1[8 * S - 11]); w.w = cvt_pk_bf16(s1[8 * S - 10], s1[8 * S - 9]); }
;             pb[S] = __builtin_bit_cast(bf16x8, w); }
	v_cvt_pk_bf16_f32 v97, v130, v131


; __device__ __forceinline__ unsigned cvt_pk_bf16(float lo, float hi) { unsigned r; asm("v_cvt_pk_bf16_f32 %0, %1, %2" : "=v"(r) : "v"(lo), "v"(hi)); return r; }
; template <bool QK, bool SM>
; __device__ __forceinline__ void attn_step(const LAS unsigned char* kb, const LAS unsigned char* vbp, const bf16x8 (&qr)[6],
;                                           f32x16& s0, f32x16& s1, f32x16& o0, f32x16& o1, float& mrow, float& lsum) {
;     ...
;         for (int S = 0; S < 4; ++S) { u32x4 w;
;             if (S < 2) { w.x = cvt_pk_bf16(s0[8 * S + 0], s0[8 * S + 1]); w.y = cvt_pk_bf16(s0[8 * S + 2], s0[8 * S + 3]); w.z = cvt_pk_bf16(s0[8 * S + 4], s0[8 * S + 5]); w.w = cvt_pk_bf16(s0[8 * S + 6], s0[8 * S + 7]); }
;             else { w.x = cvt_pk_bf16(s1[8 * S - 16], s1[8 * S - 15]); w.y = cvt_pk_bf16(s1[8 * S - 14], s1[8 * S - 13]); w.z = cvt_pk_bf16(s1[8 * S - 12], s1[8 * S - 11]); w.w = cvt_pk_bf16(s1[8 * S - 10], s1[8 * S - 9]); }
;             pb[S] = __builtin_bit_cast(bf16x8, w); }
	v_cvt_pk_bf16_f32 v98, v12, v13


; __device__ __forceinline__ unsigned cvt_pk_bf16(float lo, float hi) { unsigned r; asm("v_cvt_pk_bf16_f32 %0, %1, %2" : "=v"(r) : "v"(lo), "v"(hi)); return r; }
; template <bool QK, bool SM>
; __device__ __forceinline__ void attn_step(const LAS unsigned char* kb, const LAS unsigned char* vbp, const bf16x8 (&qr)[6],
;                                           f32x16& s0, f32x16& s1, f32x16& o0, f32x16& o1, float& mrow, float& lsum) {
;     ...
;         for (int S = 0; S < 4; ++S) { u32x4 w;
;             if (S < 2) { w.x = cvt_pk_bf16(s0[8 * S + 0], s0[8 * S + 1]); w.y = cvt_pk_bf16(s0[8 * S + 2], s0[8 * S + 3]); w.z = cvt_pk_bf16(s0[8 * S + 4], s0[8 * S + 5]); w.w = cvt_pk_bf16(s0[8 * S + 6], s0[8 * S + 7]); }
;             else { w.x = cvt_pk_bf16(s1[8 * S - 16], s1[8 * S - 15]); w.y = cvt_pk_bf16(s1[8 * S - 14], s1[8 * S - 13]); w.z = cvt_pk_bf16(s1[8 * S - 12], s1[8 * S - 11]); w.w = cvt_pk_bf16(s1[8 * S - 10], s1[8 * S - 9]); }
;             pb[S] = __builtin_bit_cast(bf16x8, w); }
	v_cvt_pk_bf16_f32 v99, v80, v81

; #define LAS __attribute__((address_space(3)))
; template <bool QK, bool SM>
; __device__ __forceinline__ void attn_step(const LAS unsigned char* kb, const LAS unsigned char* vbp, const bf16x8 (&qr)[6],
;                                           f32x16& s0, f32x16& s1, f32x16& o0, f32x16& o1, float& mrow, float& lsum) {
;     ...
;         const float mnew = fmaxf(mrow, mx), alpha = __builtin_amdgcn_exp2f(mrow - mnew); mrow = mnew;
;         const f32x2 m2 = (f32x2){mnew, mnew}; f32x2 ps2 = (f32x2){0.f, 0.f};
; #pragma unroll
;         for (int r = 0; r < 16; r += 2) { f32x2 a = (f32x2){s0[r], s0[r + 1]} - m2, b = (f32x2){s1[r], s1[r + 1]} - m2;
;             a.x = __builtin_amdgcn_exp2f(a.x); a.y = __builtin_amdgcn_exp2f(a.y); b.x = __builtin_amdgcn_exp2f(b.x); b.y = __builtin_amdgcn_exp2f(b.y);
;             s0[r] = a.x; s0[r + 1] = a.y; s1[r] = b.x; s1[r + 1] = b.y; ps2 += a + b; }
;         const float ps = ps2.x + ps2.y;
;         lsum = lsum * alpha + ps;
; #pragma unroll
;         for (int r = 0; r < 16; ++r) { o0[r] *= alpha; o1[r] *= alpha; }
;         bf16x8 pb[4];
; #pragma unroll
;         for (int S = 0; S < 4; ++S) { u32x4 w;
;             if (S < 2) { w.x = cvt_pk_bf16(s0[8 * S + 0], s0[8 * S + 1]); w.y = cvt_pk_bf16(s0[8 * S + 2], s0[8 * S + 3]); w.z = cvt_pk_bf16(s0[8 * S + 4], s0[8 * S + 5]); w.w = cvt_pk_bf16(s0[8 * S + 6], s0[8 * S + 7]); }
;             else { w.x = cvt_pk_bf16(s1[8 * S - 16], s1[8 * S - 15]); w.y = cvt_pk_bf16(s1[8 * S - 14], s1[8 * S - 13]); w.z = cvt_pk_bf16(s1[8 * S - 12], s1[8 * S - 11]); w.w = cvt_pk_bf16(s1[8 * S - 10], s1[8 * S - 9]); }
;             pb[S] = __builtin_bit_cast(bf16x8, w); }
; #pragma unroll
;         for (int S = 0; S < 4; ++S) {
;             const u32x2 a0 = *(const LAS u32x2*)(vbp + S * 32), a1 = *(const LAS u32x2*)(vbp + S * 32 + 16);
;             const u32x2 c0 = *(const LAS u32x2*)(vbp + 32 * VPITCH + S * 32), c1 = *(const LAS u32x2*)(vbp + 32 * VPITCH + S * 32 + 16);
;             const bf16x8 va = __builtin_bit_cast(bf16x8, (u32x4){a0.x, a0.y, a1.x, a1.y}), vc = __builtin_bit_cast(bf16x8, (u32x4){c0.x, c0.y, c1.x, c1.y});
;             o0 = __builtin_amdgcn_mfma_f32_32x32x16_bf16(va, pb[S], o0, 0, 0, 0); o1 = __builtin_amdgcn_mfma_f32_32x32x16_bf16(vc, pb[S], o1, 0, 0, 0); }
;     }
;     s0 = n0; s1 = n1;
	s_waitcnt lgkmcnt(0)
	s_nop 0
	v_mfma_f32_32x32x16_bf16 v[32:47], v[6:9], v[96:99], v[32:47]
	ds_read2_b64 v[6:9], v110 offset0:68 offset1:70
	v_exp_f32_e32 v14, v14
	v_mfma_f32_32x32x16_bf16 v[64:79], v[100:103], v[96:99], v[64:79]
	ds_read2_b64 v[100:103], v111 offset0:100 offset1:102
	v_exp_f32_e32 v104, v126
	v_exp_f32_e32 v105, v127
	v_cvt_pk_bf16_f32 v96, v82, v83
	v_cvt_pk_bf16_f32 v97, v84, v85
	v_cvt_pk_bf16_f32 v98, v116, v117
	v_cvt_pk_bf16_f32 v99, v104, v105
	v_exp_f32_e32 v15, v15
	s_waitcnt lgkmcnt(1)
	v_mfma_f32_32x32x16_bf16 v[32:47], v[6:9], v[96:99], v[32:47]
	v_exp_f32_e32 v106, v86
	v_exp_f32_e32 v107, v87
	ds_read2_b64 v[6:9], v110 offset0:72 offset1:74
	v_exp_f32_e32 v108, v88
	v_exp_f32_e32 v109, v89
	s_waitcnt lgkmcnt(1)
	v_mfma_f32_32x32x16_bf16 v[64:79], v[100:103], v[96:99], v[64:79]
	ds_read2_b64 v[96:99], v111 offset0:104 offset1:106
	v_cvt_pk_bf16_f32 v86, v112, v113
	v_cvt_pk_bf16_f32 v87, v114, v115
	v_cvt_pk_bf16_f32 v88, v14, v15
	v_cvt_pk_bf16_f32 v89, v106, v107
	s_waitcnt lgkmcnt(1)
	s_nop 0
	v_mfma_f32_32x32x16_bf16 v[32:47], v[6:9], v[86:89], v[32:47]
	v_exp_f32_e32 v100, v90
	v_exp_f32_e32 v101, v91
	v_exp_f32_e32 v102, v92
	v_exp_f32_e32 v103, v93
	ds_read2_b64 v[6:9], v110 offset0:76 offset1:78
	v_exp_f32_e32 v94, v94
	v_exp_f32_e32 v95, v95
	ds_read2_b64 v[90:93], v111 offset0:108 offset1:110
	s_waitcnt lgkmcnt(2)
	v_mfma_f32_32x32x16_bf16 v[64:79], v[96:99], v[86:89], v[64:79]
	v_cvt_pk_bf16_f32 v86, v108, v109
	v_cvt_pk_bf16_f32 v87, v100, v101
	v_cvt_pk_bf16_f32 v88, v102, v103
	v_cvt_pk_bf16_f32 v89, v94, v95
	s_waitcnt lgkmcnt(1)
	s_nop 0
	v_mfma_f32_32x32x16_bf16 v[32:47], v[6:9], v[86:89], v[32:47]
	v_add_f32_e32 v6, v12, v14
	v_add_f32_e32 v7, v13, v15
	v_add_f32_e32 v8, v80, v106
	v_add_f32_e32 v9, v81, v107
	v_add_f32_e32 v6, v6, v10
	v_add_f32_e32 v7, v7, v11
	v_add_f32_e32 v6, v8, v6
	v_add_f32_e32 v7, v9, v7
	v_add_f32_e32 v8, v82, v108
	v_add_f32_e32 v9, v83, v109
	s_waitcnt lgkmcnt(0)
	v_mfma_f32_32x32x16_bf16 v[64:79], v[90:93], v[86:89], v[64:79]
	v_add_f32_e32 v6, v8, v6
	v_add_f32_e32 v7, v9, v7
	v_add_f32_e32 v8, v84, v100
	v_add_f32_e32 v9, v85, v101
	v_add_f32_e32 v6, v8, v6
	v_add_f32_e32 v7, v9, v7
	v_add_f32_e32 v8, v116, v102
	v_add_f32_e32 v9, v117, v103
	s_nop 0
	v_add_f32_e32 v6, v8, v6
	v_add_f32_e32 v7, v9, v7
	v_mfma_f32_32x32x16_bf16 v[16:31], v[2:5], v[144:147], v[16:31]
	v_add_f32_e32 v8, v104, v94
	v_add_f32_e32 v9, v105, v95
	v_add_f32_e32 v6, v8, v6
	v_add_f32_e32 v7, v9, v7
	v_add_f32_e32 v215, v6, v7
	v_add_f32_e32 v215, v215, v216
	s_cmp_lg_u32 s99, 0
	s_cbranch_scc1 .Latt_slow2B
.Latt_cont2B:
	s_waitcnt vmcnt(5)
	ds_write_b128 v197, v[184:187] offset:13312
	s_and_saveexec_b64 s[10:11], s[0:1]
	s_cbranch_execz .LBB0_940
.LBB0_958:
	s_waitcnt vmcnt(4)
	ds_write_b128 v212, v[180:183] offset:13312
	s_branch .LBB0_940
.Latt_slowB:
	v_max_f32_e32 v10, v0, v208
	v_mov_b32_e32 v208, 0
	v_mov_b32_e32 v206, 0
	v_mov_b32_e32 v234, v10
	s_mov_b32 s99, 1
	v_sub_f32_e32 v112, v112, v10
	v_sub_f32_e32 v113, v113, v10
	v_sub_f32_e32 v114, v114, v10
	v_sub_f32_e32 v115, v115, v10
	v_sub_f32_e32 v116, v116, v10
	v_sub_f32_e32 v117, v117, v10
	v_sub_f32_e32 v118, v118, v10
	v_sub_f32_e32 v119, v119, v10
	v_sub_f32_e32 v120, v120, v10
	v_sub_f32_e32 v121, v121, v10
	v_sub_f32_e32 v122, v122, v10
	v_sub_f32_e32 v123, v123, v10
	v_sub_f32_e32 v124, v124, v10
	v_sub_f32_e32 v125, v125, v10
	v_sub_f32_e32 v126, v126, v10
	v_sub_f32_e32 v127, v127, v10
	v_sub_f32_e32 v80, v80, v10
	v_sub_f32_e32 v81, v81, v10
	v_sub_f32_e32 v82, v82, v10
	v_sub_f32_e32 v83, v83, v10
	v_sub_f32_e32 v84, v84, v10
	v_sub_f32_e32 v85, v85, v10
	v_sub_f32_e32 v86, v86, v10
	v_sub_f32_e32 v87, v87, v10
	v_sub_f32_e32 v88, v88, v10
	v_sub_f32_e32 v89, v89, v10
	v_sub_f32_e32 v90, v90, v10
	v_sub_f32_e32 v91, v91, v10
	v_sub_f32_e32 v92, v92, v10
	v_sub_f32_e32 v93, v93, v10
	v_sub_f32_e32 v94, v94, v10
	v_sub_f32_e32 v95, v95, v10
	v_sub_f32_e32 v11, 0, v10
	v_min_f32_e32 v11, 0x42fc0000, v11
	v_exp_f32_e32 v11, v11
	s_nop 0
	v_mul_f32_e32 v32, v32, v11
	v_mul_f32_e32 v33, v33, v11
	v_mul_f32_e32 v34, v34, v11
	v_mul_f32_e32 v35, v35, v11
	v_mul_f32_e32 v36, v36, v11
	v_mul_f32_e32 v37, v37, v11
	v_mul_f32_e32 v38, v38, v11
	v_mul_f32_e32 v39, v39, v11
	v_mul_f32_e32 v40, v40, v11
	v_mul_f32_e32 v41, v41, v11
	v_mul_f32_e32 v42, v42, v11
	v_mul_f32_e32 v43, v43, v11
	v_mul_f32_e32 v44, v44, v11
	v_mul_f32_e32 v45, v45, v11
	v_mul_f32_e32 v46, v46, v11
	v_mul_f32_e32 v47, v47, v11
	v_mul_f32_e32 v64, v64, v11
	v_mul_f32_e32 v65, v65, v11
	v_mul_f32_e32 v66, v66, v11
	v_mul_f32_e32 v67, v67, v11
	v_mul_f32_e32 v68, v68, v11
	v_mul_f32_e32 v69, v69, v11
	v_mul_f32_e32 v70, v70, v11
	v_mul_f32_e32 v71, v71, v11
	v_mul_f32_e32 v72, v72, v11
	v_mul_f32_e32 v73, v73, v11
	v_mul_f32_e32 v74, v74, v11
	v_mul_f32_e32 v75, v75, v11
	v_mul_f32_e32 v76, v76, v11
	v_mul_f32_e32 v77, v77, v11
	v_mul_f32_e32 v78, v78, v11
	v_mul_f32_e32 v79, v79, v11
	v_mul_f32_e32 v216, v216, v11
	s_nop 1
	s_branch .Latt_contB
.Latt_slow2B:
	s_nop 15
	s_mov_b32 s99, 0
	v_sub_f32_e32 v48, v48, v234
	v_sub_f32_e32 v49, v49, v234
	v_sub_f32_e32 v50, v50, v234
	v_sub_f32_e32 v51, v51, v234
	v_sub_f32_e32 v52, v52, v234
	v_sub_f32_e32 v53, v53, v234
	v_sub_f32_e32 v54, v54, v234
	v_sub_f32_e32 v55, v55, v234
	v_sub_f32_e32 v56, v56, v234
	v_sub_f32_e32 v57, v57, v234
	v_sub_f32_e32 v58, v58, v234
	v_sub_f32_e32 v59, v59, v234
	v_sub_f32_e32 v60, v60, v234
	v_sub_f32_e32 v61, v61, v234
	v_sub_f32_e32 v62, v62, v234
	v_sub_f32_e32 v63, v63, v234
	v_sub_f32_e32 v16, v16, v234
	v_sub_f32_e32 v17, v17, v234
	v_sub_f32_e32 v18, v18, v234
	v_sub_f32_e32 v19, v19, v234
	v_sub_f32_e32 v20, v20, v234
	v_sub_f32_e32 v21, v21, v234
	v_sub_f32_e32 v22, v22, v234
	v_sub_f32_e32 v23, v23, v234
	v_sub_f32_e32 v24, v24, v234
	v_sub_f32_e32 v25, v25, v234
	v_sub_f32_e32 v26, v26, v234
	v_sub_f32_e32 v27, v27, v234
	v_sub_f32_e32 v28, v28, v234
	v_sub_f32_e32 v29, v29, v234
	v_sub_f32_e32 v30, v30, v234
	v_sub_f32_e32 v31, v31, v234
	v_sub_f32_e32 v218, v218, v234
	v_sub_f32_e32 v219, v219, v234
	v_sub_f32_e32 v220, v220, v234
	v_sub_f32_e32 v221, v221, v234
	v_sub_f32_e32 v222, v222, v234
	v_sub_f32_e32 v223, v223, v234
	v_sub_f32_e32 v224, v224, v234
	v_sub_f32_e32 v225, v225, v234
	v_sub_f32_e32 v226, v226, v234
	v_sub_f32_e32 v227, v227, v234
	v_sub_f32_e32 v228, v228, v234
	v_sub_f32_e32 v229, v229, v234
	v_sub_f32_e32 v230, v230, v234
	v_sub_f32_e32 v231, v231, v234
	v_sub_f32_e32 v232, v232, v234
	v_sub_f32_e32 v233, v233, v234
	s_branch .Latt_cont2B

; __global__ void __launch_bounds__(512, 2) mega_fwd(Args a) {
	.amdhsa_kernel _Z8mega_fwd4Args
		.amdhsa_group_segment_fixed_size 0
		.amdhsa_private_segment_fixed_size 0
		.amdhsa_kernarg_size 464
		.amdhsa_user_sgpr_count 2
		.amdhsa_user_sgpr_dispatch_ptr 0
		.amdhsa_user_sgpr_queue_ptr 0
		.amdhsa_user_sgpr_kernarg_segment_ptr 1
		.amdhsa_user_sgpr_dispatch_id 0
		.amdhsa_user_sgpr_kernarg_preload_length 0
		.amdhsa_user_sgpr_kernarg_preload_offset 0
		.amdhsa_user_sgpr_private_segment_size 0
		.amdhsa_uses_dynamic_stack 0
		.amdhsa_enable_private_segment 0
		.amdhsa_system_sgpr_workgroup_id_x 1
		.amdhsa_system_sgpr_workgroup_id_y 0
		.amdhsa_system_sgpr_workgroup_id_z 0
		.amdhsa_system_sgpr_workgroup_info 0
		.amdhsa_system_vgpr_workitem_id 2
		.amdhsa_next_free_vgpr 239
		.amdhsa_next_free_sgpr 102
		.amdhsa_accum_offset 240
		.amdhsa_reserve_vcc 1
		.amdhsa_float_round_mode_32 0
		.amdhsa_float_round_mode_16_64 0
		.amdhsa_float_denorm_mode_32 3
		.amdhsa_float_denorm_mode_16_64 3
		.amdhsa_dx10_clamp 1
		.amdhsa_ieee_mode 1
		.amdhsa_fp16_overflow 0
		.amdhsa_tg_split 0
		.amdhsa_exception_fp_ieee_invalid_op 0
		.amdhsa_exception_fp_denorm_src 0
		.amdhsa_exception_fp_ieee_div_zero 0
		.amdhsa_exception_fp_ieee_overflow 0
		.amdhsa_exception_fp_ieee_underflow 0
		.amdhsa_exception_fp_ieee_inexact 0
		.amdhsa_exception_int_div_zero 0
	.end_amdhsa_kernel

; __global__ void __launch_bounds__(512, 2) mega_fwd(Args a) {
amdhsa.kernels:
  - .agpr_count:     0
    .args:
      - .offset:         0
        .size:           208
        .value_kind:     by_value
      - .offset:         208
        .size:           4
        .value_kind:     hidden_block_count_x
      - .offset:         212
        .size:           4
        .value_kind:     hidden_block_count_y
      - .offset:         216
        .size:           4
        .value_kind:     hidden_block_count_z
      - .offset:         220
        .size:           2
        .value_kind:     hidden_group_size_x
      - .offset:         222
        .size:           2
        .value_kind:     hidden_group_size_y
      - .offset:         224
        .size:           2
        .value_kind:     hidden_group_size_z
      - .offset:         226
        .size:           2
        .value_kind:     hidden_remainder_x
      - .offset:         228
        .size:           2
        .value_kind:     hidden_remainder_y
      - .offset:         230
        .size:           2
        .value_kind:     hidden_remainder_z
      - .offset:         248
        .size:           8
        .value_kind:     hidden_global_offset_x
      - .offset:         256
        .size:           8
        .value_kind:     hidden_global_offset_y
      - .offset:         264
        .size:           8
        .value_kind:     hidden_global_offset_z
      - .offset:         272
        .size:           2
        .value_kind:     hidden_grid_dims
      - .offset:         296
        .size:           8
        .value_kind:     hidden_multigrid_sync_arg
      - .offset:         328
        .size:           4
        .value_kind:     hidden_dynamic_lds_size
    .group_segment_fixed_size: 0
    .kernarg_segment_align: 8
    .kernarg_segment_size: 464
    .language:       OpenCL C
    .language_version:
      - 2
      - 0
    .max_flat_workgroup_size: 512
    .name:           _Z8mega_fwd4Args
    .private_segment_fixed_size: 0
    .sgpr_count:     108
    .sgpr_spill_count: 66
    .symbol:         _Z8mega_fwd4Args.kd
    .uniform_work_group_size: 1
    .uses_dynamic_stack: false
    .vgpr_count:     239
    .vgpr_spill_count: 0
    .wavefront_size: 64
